# rotated attention loops (deferred PV), widened store_o, batched loads in mla_up rmsnorm prologue / ret_kv V copy / in-proj q-k epilogue
# speedup vs baseline: 1.0232x; 1.0232x over previous
; DI float shx(float v, int k) { return __int_as_float(__builtin_amdgcn_ds_bpermute((lane_id_l() ^ k) << 2, __float_as_int(v))); }
; DI void inproj_tile8(const Params& P, const WsPtrs& W, int layer, int mt, int nt, unsigned char* smem) {
;     ...
;         if (qsec) {
;           const bool isq = cb < O_BK;
;           const float* gp = (isq ? P.in[I_DQG] : P.in[I_DKG]) + layer * 64;
;           float ss = 0.f;
; #pragma unroll
;           for (int m = 0; m < 4; ++m) ss += v[m].x * v[m].x + v[m].y * v[m].y + v[m].z * v[m].z + v[m].w * v[m].w;
;           ss += shx(ss, 16);
;           ss += shx(ss, 32);
;           const float sc = rsqrtf(ss * (1.f / 64.f) + EPSV) * (isq ? 0.125f * LOG2E : 1.f);
; #pragma unroll
;           for (int m = 0; m < 4; ++m) {
;             const f32x4 g4 = *(const f32x4*)(gp + m * 16 + fq * 4);
;             v[m].x *= sc * g4.x; v[m].y *= sc * g4.y; v[m].z *= sc * g4.z; v[m].w *= sc * g4.w;
;           }
;           const f32x4 fr4 = *(const f32x4*)(W.rope + (fq & 1) * 4);
;           float mine[4] = {v[0].x, v[0].y, v[0].z, v[0].w}, frq[4] = {fr4.x, fr4.y, fr4.z, fr4.w}, outv[4];
; #pragma unroll
;           for (int j = 0; j < 4; ++j) {
;             float c, sn; rot_cs(pos, frq[j], c, sn);
;             float oth = shx(mine[j], 32);
;             outv[j] = (fq < 2) ? (mine[j] * c - oth * sn) : (mine[j] * c + oth * sn);
;           }
;           v[0].x = outv[0]; v[0].y = outv[1]; v[0].z = outv[2]; v[0].w = outv[3];
.LBB0_217:
	v_mov_b32_e32 v0, 0x68
	v_mov_b32_e32 v98, 0x60
	v_readlane_b32 s8, v253, 3
	v_cndmask_b32_e64 v0, v0, v98, s[18:19]
	v_readlane_b32 s9, v253, 4
	v_mov_b32_e32 v102, v121
	v_mov_b32_e32 v103, v107
	v_lshl_add_u64 v[98:99], s[8:9], 0, v[0:1]
	global_load_dwordx2 v[172:173], v[98:99], off
	s_nop 0
	v_mov_b32_e32 v100, v120
	v_mov_b32_e32 v101, v106
	v_pk_mul_f32 v[102:103], v[102:103], v[102:103]
	s_mov_b32 s2, 0x800000
	v_pk_fma_f32 v[100:101], v[100:101], v[100:101], v[102:103]
	v_mov_b32_e32 v102, v118
	v_mov_b32_e32 v103, v108
	v_pk_fma_f32 v[100:101], v[102:103], v[102:103], v[100:101]
	v_mov_b32_e32 v102, v119
	v_mov_b32_e32 v103, v109
	v_pk_fma_f32 v[100:101], v[102:103], v[102:103], v[100:101]
	v_pk_mul_f32 v[102:103], v[126:127], v[126:127]
	v_add_f32_e32 v0, v100, v101
	v_pk_fma_f32 v[102:103], v[124:125], v[124:125], v[102:103]
	v_mov_b32_e32 v100, v229
	v_pk_fma_f32 v[102:103], v[128:129], v[128:129], v[102:103]
	v_readlane_b32 s8, v255, 17
	v_pk_fma_f32 v[102:103], v[130:131], v[130:131], v[102:103]
	v_lshlrev_b32_e32 v100, 2, v100
	v_add_f32_e32 v0, v103, v0
	v_add_f32_e32 v0, v102, v0
	v_xor_b32_e32 v100, 64, v100
	ds_bpermute_b32 v100, v100, v0
	v_readlane_b32 s9, v255, 18
	v_mov_b32_e32 v123, v1
	v_mov_b32_e32 v110, v125
	v_mov_b32_e32 v111, v127
	s_waitcnt lgkmcnt(0)
	v_add_f32_e32 v0, v0, v100
	v_mov_b32_e32 v100, v229
	v_mov_b32_e32 v125, v126
	v_lshlrev_b32_e32 v100, 2, v100
	v_xor_b32_e32 v100, 0x80, v100
	ds_bpermute_b32 v100, v100, v0
	v_mov_b32_e32 v126, v229
	s_waitcnt lgkmcnt(0)
	v_add_f32_e32 v0, v0, v100
	v_fmamk_f32 v0, v0, 0x3c800000, v228
	v_cmp_gt_f32_e32 vcc, s2, v0
	v_mul_f32_e32 v100, 0x4b800000, v0
	s_waitcnt vmcnt(0)
	v_lshl_add_u64 v[98:99], s[8:9], 2, v[172:173]
	v_cndmask_b32_e32 v0, v0, v100, vcc
	v_rsq_f32_e32 v0, v0
	v_lshl_add_u64 v[132:133], v[98:99], 0, v[122:123]
	global_load_dwordx4 v[176:179], v[132:133], off
	global_load_dwordx4 v[180:183], v[132:133], off offset:64
	global_load_dwordx4 v[184:187], v[132:133], off offset:128
	global_load_dwordx4 v[188:191], v[132:133], off offset:192
	v_readlane_b32 s8, v253, 54
	v_readlane_b32 s9, v253, 55
	v_mul_f32_e32 v100, 0x45800000, v0
	v_cndmask_b32_e32 v0, v0, v100, vcc
	v_cndmask_b32_e64 v100, 1.0, v252, s[18:19]
	v_mul_f32_e32 v0, v100, v0
	s_nop 0
	s_nop 0
	global_load_dwordx4 v[192:195], v150, s[8:9]
	s_waitcnt vmcnt(4)
	v_pk_mul_f32 v[102:103], v[176:177], v[0:1] op_sel_hi:[1,0]
	s_waitcnt vmcnt(3)
	v_pk_mul_f32 v[98:99], v[180:181], v[0:1] op_sel_hi:[1,0]
	v_pk_mul_f32 v[100:101], v[182:183], v[0:1] op_sel_hi:[1,0]
	v_pk_mul_f32 v[98:99], v[106:107], v[98:99]
	v_pk_mul_f32 v[100:101], v[108:109], v[100:101]
	s_nop 0
	v_pk_mul_f32 v[102:103], v[120:121], v[102:103]
	v_pk_mul_f32 v[104:105], v[178:179], v[0:1] op_sel_hi:[1,0]
	s_waitcnt vmcnt(2)
	v_pk_mul_f32 v[106:107], v[184:185], v[0:1] op_sel_hi:[1,0]
	s_nop 0
	v_pk_mul_f32 v[112:113], v[110:111], v[106:107]
	v_pk_mul_f32 v[106:107], v[186:187], v[0:1] op_sel_hi:[1,0]
	v_mov_b32_e32 v108, v129
	v_mov_b32_e32 v109, v131
	v_pk_mul_f32 v[110:111], v[108:109], v[106:107]
	s_nop 0
	v_mov_b32_e32 v129, v130
	v_pk_mul_f32 v[104:105], v[118:119], v[104:105]
	s_waitcnt vmcnt(1)
	v_pk_mul_f32 v[106:107], v[188:189], v[0:1] op_sel_hi:[1,0]
	s_nop 0
	v_pk_mul_f32 v[134:135], v[124:125], v[106:107]
	v_pk_mul_f32 v[106:107], v[190:191], v[0:1] op_sel_hi:[1,0]
	s_nop 0
	v_pk_mul_f32 v[132:133], v[128:129], v[106:107]
	s_nop 0
	s_waitcnt vmcnt(0)
	v_mul_f32_e32 v123, v192, v161
	v_floor_f32_e32 v123, v123
	v_fma_f32 v123, v192, v161, -v123
	v_cos_f32_e32 v106, v123
	v_sin_f32_e32 v124, v123
	v_mov_b32_e32 v123, v229
	v_mul_f32_e32 v125, v193, v161
	v_lshlrev_b32_e32 v123, 2, v123
	v_lshlrev_b32_e32 v126, 2, v126
	v_xor_b32_e32 v123, 0x80, v123
	v_floor_f32_e32 v125, v125
	v_xor_b32_e32 v126, 0x80, v126
	v_fma_f32 v125, v193, v161, -v125
	ds_bpermute_b32 v120, v123, v102
	ds_bpermute_b32 v121, v126, v103
	v_cos_f32_e32 v107, v125
	v_sin_f32_e32 v125, v125
	v_mul_f32_e32 v123, v194, v161
	v_floor_f32_e32 v123, v123
	v_fma_f32 v123, v194, v161, -v123
	s_waitcnt lgkmcnt(0)
	v_pk_mul_f32 v[120:121], v[124:125], v[120:121]
	v_cos_f32_e32 v108, v123
	v_sin_f32_e32 v124, v123
	v_mov_b32_e32 v123, v229
	v_mov_b32_e32 v126, v229
	v_mul_f32_e32 v125, v195, v161
	v_lshlrev_b32_e32 v123, 2, v123
	v_lshlrev_b32_e32 v126, 2, v126
	v_xor_b32_e32 v123, 0x80, v123
	v_floor_f32_e32 v125, v125
	v_xor_b32_e32 v126, 0x80, v126
	v_fma_f32 v125, v195, v161, -v125
	ds_bpermute_b32 v118, v123, v104
	ds_bpermute_b32 v119, v126, v105
	v_cos_f32_e32 v109, v125
	v_sin_f32_e32 v125, v125
	v_cndmask_b32_e64 v121, v121, -v121, s[4:5]
	v_cndmask_b32_e64 v120, v120, -v120, s[4:5]
	v_pk_fma_f32 v[136:137], v[106:107], v[102:103], v[120:121]
	s_waitcnt lgkmcnt(0)
	v_pk_mul_f32 v[118:119], v[124:125], v[118:119]
	s_nop 0
	v_cndmask_b32_e64 v119, v119, -v119, s[4:5]
	v_cndmask_b32_e64 v118, v118, -v118, s[4:5]
	v_pk_fma_f32 v[104:105], v[108:109], v[104:105], v[118:119]

; DI float shx(float v, int k) { return __int_as_float(__builtin_amdgcn_ds_bpermute((lane_id_l() ^ k) << 2, __float_as_int(v))); }
; DI void inproj_tile8(const Params& P, const WsPtrs& W, int layer, int mt, int nt, unsigned char* smem) {
;     ...
;         if (qsec) {
;           const bool isq = cb < O_BK;
;           const float* gp = (isq ? P.in[I_DQG] : P.in[I_DKG]) + layer * 64;
;           float ss = 0.f;
; #pragma unroll
;           for (int m = 0; m < 4; ++m) ss += v[m].x * v[m].x + v[m].y * v[m].y + v[m].z * v[m].z + v[m].w * v[m].w;
;           ss += shx(ss, 16);
;           ss += shx(ss, 32);
;           const float sc = rsqrtf(ss * (1.f / 64.f) + EPSV) * (isq ? 0.125f * LOG2E : 1.f);
; #pragma unroll
;           for (int m = 0; m < 4; ++m) {
;             const f32x4 g4 = *(const f32x4*)(gp + m * 16 + fq * 4);
;             v[m].x *= sc * g4.x; v[m].y *= sc * g4.y; v[m].z *= sc * g4.z; v[m].w *= sc * g4.w;
;           }
;           const f32x4 fr4 = *(const f32x4*)(W.rope + (fq & 1) * 4);
;           float mine[4] = {v[0].x, v[0].y, v[0].z, v[0].w}, frq[4] = {fr4.x, fr4.y, fr4.z, fr4.w}, outv[4];
; #pragma unroll
;           for (int j = 0; j < 4; ++j) {
;             float c, sn; rot_cs(pos, frq[j], c, sn);
;             float oth = shx(mine[j], 32);
;             outv[j] = (fq < 2) ? (mine[j] * c - oth * sn) : (mine[j] * c + oth * sn);
;           }
;           v[0].x = outv[0]; v[0].y = outv[1]; v[0].z = outv[2]; v[0].w = outv[3];
.LBB0_230:
	s_movk_i32 s2, 0xc00
	v_cmp_gt_i32_e32 vcc, s2, v158
	v_mov_b32_e32 v0, 0x68
	v_mov_b32_e32 v82, 0x60
	v_readlane_b32 s20, v253, 3
	v_cndmask_b32_e32 v0, v0, v82, vcc
	v_readlane_b32 s21, v253, 4
	v_mov_b32_e32 v86, v105
	v_mov_b32_e32 v87, v91
	v_lshl_add_u64 v[82:83], s[20:21], 0, v[0:1]
	global_load_dwordx2 v[172:173], v[82:83], off
	s_nop 0
	v_mov_b32_e32 v84, v104
	v_mov_b32_e32 v85, v90
	v_pk_mul_f32 v[86:87], v[86:87], v[86:87]
	s_mov_b32 s2, 0x800000
	v_pk_fma_f32 v[84:85], v[84:85], v[84:85], v[86:87]
	v_mov_b32_e32 v86, v100
	v_mov_b32_e32 v87, v92
	v_pk_fma_f32 v[84:85], v[86:87], v[86:87], v[84:85]
	v_mov_b32_e32 v86, v101
	v_mov_b32_e32 v87, v93
	v_pk_fma_f32 v[84:85], v[86:87], v[86:87], v[84:85]
	v_pk_mul_f32 v[86:87], v[108:109], v[108:109]
	v_add_f32_e32 v0, v84, v85
	v_pk_fma_f32 v[86:87], v[106:107], v[106:107], v[86:87]
	v_mov_b32_e32 v84, v229
	v_pk_fma_f32 v[86:87], v[110:111], v[110:111], v[86:87]
	v_readlane_b32 s20, v255, 17
	v_pk_fma_f32 v[86:87], v[112:113], v[112:113], v[86:87]
	v_lshlrev_b32_e32 v84, 2, v84
	v_add_f32_e32 v0, v87, v0
	v_add_f32_e32 v0, v86, v0
	v_xor_b32_e32 v84, 64, v84
	ds_bpermute_b32 v84, v84, v0
	v_readlane_b32 s21, v255, 18
	v_mov_b32_e32 v123, v1
	v_mov_b32_e32 v94, v107
	v_mov_b32_e32 v95, v109
	s_waitcnt lgkmcnt(0)
	v_add_f32_e32 v0, v0, v84
	v_mov_b32_e32 v84, v229
	v_mov_b32_e32 v107, v108
	v_lshlrev_b32_e32 v84, 2, v84
	v_xor_b32_e32 v84, 0x80, v84
	ds_bpermute_b32 v84, v84, v0
	v_mov_b32_e32 v109, v229
	s_waitcnt lgkmcnt(0)
	v_add_f32_e32 v0, v0, v84
	v_fmamk_f32 v0, v0, 0x3c800000, v228
	v_cmp_gt_f32_e64 s[28:29], s2, v0
	v_mul_f32_e32 v84, 0x4b800000, v0
	s_waitcnt vmcnt(0)
	v_lshl_add_u64 v[82:83], s[20:21], 2, v[172:173]
	v_cndmask_b32_e64 v0, v0, v84, s[28:29]
	v_rsq_f32_e32 v0, v0
	v_lshl_add_u64 v[116:117], v[82:83], 0, v[122:123]
	global_load_dwordx4 v[176:179], v[116:117], off
	global_load_dwordx4 v[180:183], v[116:117], off offset:64
	global_load_dwordx4 v[184:187], v[116:117], off offset:128
	global_load_dwordx4 v[188:191], v[116:117], off offset:192
	v_readlane_b32 s20, v253, 54
	v_readlane_b32 s21, v253, 55
	v_mul_f32_e32 v84, 0x45800000, v0
	v_cndmask_b32_e64 v0, v0, v84, s[28:29]
	v_cndmask_b32_e32 v84, 1.0, v252, vcc
	v_mul_f32_e32 v0, v84, v0
	s_nop 0
	s_nop 0
	global_load_dwordx4 v[192:195], v150, s[20:21]
	s_waitcnt vmcnt(4)
	v_pk_mul_f32 v[86:87], v[176:177], v[0:1] op_sel_hi:[1,0]
	s_waitcnt vmcnt(3)
	v_pk_mul_f32 v[82:83], v[180:181], v[0:1] op_sel_hi:[1,0]
	v_pk_mul_f32 v[84:85], v[182:183], v[0:1] op_sel_hi:[1,0]
	v_pk_mul_f32 v[82:83], v[90:91], v[82:83]
	v_pk_mul_f32 v[84:85], v[92:93], v[84:85]
	s_nop 0
	v_pk_mul_f32 v[86:87], v[104:105], v[86:87]
	v_pk_mul_f32 v[88:89], v[178:179], v[0:1] op_sel_hi:[1,0]
	s_waitcnt vmcnt(2)
	v_pk_mul_f32 v[90:91], v[184:185], v[0:1] op_sel_hi:[1,0]
	s_nop 0
	v_pk_mul_f32 v[96:97], v[94:95], v[90:91]
	v_pk_mul_f32 v[90:91], v[186:187], v[0:1] op_sel_hi:[1,0]
	v_mov_b32_e32 v92, v111
	v_mov_b32_e32 v93, v113
	v_pk_mul_f32 v[94:95], v[92:93], v[90:91]
	s_nop 0
	v_mov_b32_e32 v111, v112
	v_pk_mul_f32 v[88:89], v[100:101], v[88:89]
	s_waitcnt vmcnt(1)
	v_pk_mul_f32 v[90:91], v[188:189], v[0:1] op_sel_hi:[1,0]
	s_nop 0
	v_pk_mul_f32 v[118:119], v[106:107], v[90:91]
	v_pk_mul_f32 v[90:91], v[190:191], v[0:1] op_sel_hi:[1,0]
	v_mov_b32_e32 v107, v229
	v_pk_mul_f32 v[116:117], v[110:111], v[90:91]
	s_nop 0
	s_waitcnt vmcnt(0)
	v_mul_f32_e32 v106, v192, v132
	v_lshlrev_b32_e32 v107, 2, v107
	v_xor_b32_e32 v108, 0x80, v107
	v_mul_f32_e32 v107, v193, v132
	v_lshlrev_b32_e32 v109, 2, v109
	v_floor_f32_e32 v106, v106
	v_floor_f32_e32 v107, v107
	v_xor_b32_e32 v109, 0x80, v109
	v_fma_f32 v106, v192, v132, -v106
	v_fma_f32 v107, v193, v132, -v107
	ds_bpermute_b32 v104, v108, v86
	ds_bpermute_b32 v105, v109, v87
	v_cos_f32_e32 v90, v106
	v_sin_f32_e32 v106, v106
	v_cos_f32_e32 v91, v107
	v_sin_f32_e32 v107, v107
	v_mov_b32_e32 v109, v229
	s_waitcnt lgkmcnt(0)
	v_pk_mul_f32 v[104:105], v[106:107], v[104:105]
	v_mov_b32_e32 v107, v229
	v_mul_f32_e32 v106, v194, v132
	v_lshlrev_b32_e32 v107, 2, v107
	v_xor_b32_e32 v108, 0x80, v107
	v_mul_f32_e32 v107, v195, v132
	v_lshlrev_b32_e32 v109, 2, v109
	v_floor_f32_e32 v106, v106
	v_floor_f32_e32 v107, v107
	v_xor_b32_e32 v109, 0x80, v109
	v_fma_f32 v106, v194, v132, -v106
	v_fma_f32 v107, v195, v132, -v107
	ds_bpermute_b32 v100, v108, v88
	ds_bpermute_b32 v101, v109, v89
	v_cos_f32_e32 v92, v106
	v_sin_f32_e32 v106, v106
	v_cos_f32_e32 v93, v107
	v_sin_f32_e32 v107, v107
	v_cndmask_b32_e64 v105, v105, -v105, s[4:5]
	v_cndmask_b32_e64 v104, v104, -v104, s[4:5]
	v_pk_fma_f32 v[120:121], v[90:91], v[86:87], v[104:105]
	s_waitcnt lgkmcnt(0)
	v_pk_mul_f32 v[100:101], v[106:107], v[100:101]
	s_nop 0
	v_cndmask_b32_e64 v101, v101, -v101, s[4:5]
	v_cndmask_b32_e64 v100, v100, -v100, s[4:5]
	v_pk_fma_f32 v[88:89], v[92:93], v[88:89], v[100:101]

; DI float shx(float v, int k) { return __int_as_float(__builtin_amdgcn_ds_bpermute((lane_id_l() ^ k) << 2, __float_as_int(v))); }
; DI void inproj_tile8(const Params& P, const WsPtrs& W, int layer, int mt, int nt, unsigned char* smem) {
;     ...
;         if (qsec) {
;           const bool isq = cb < O_BK;
;           const float* gp = (isq ? P.in[I_DQG] : P.in[I_DKG]) + layer * 64;
;           float ss = 0.f;
; #pragma unroll
;           for (int m = 0; m < 4; ++m) ss += v[m].x * v[m].x + v[m].y * v[m].y + v[m].z * v[m].z + v[m].w * v[m].w;
;           ss += shx(ss, 16);
;           ss += shx(ss, 32);
;           const float sc = rsqrtf(ss * (1.f / 64.f) + EPSV) * (isq ? 0.125f * LOG2E : 1.f);
; #pragma unroll
;           for (int m = 0; m < 4; ++m) {
;             const f32x4 g4 = *(const f32x4*)(gp + m * 16 + fq * 4);
;             v[m].x *= sc * g4.x; v[m].y *= sc * g4.y; v[m].z *= sc * g4.z; v[m].w *= sc * g4.w;
;           }
;           const f32x4 fr4 = *(const f32x4*)(W.rope + (fq & 1) * 4);
;           float mine[4] = {v[0].x, v[0].y, v[0].z, v[0].w}, frq[4] = {fr4.x, fr4.y, fr4.z, fr4.w}, outv[4];
; #pragma unroll
;           for (int j = 0; j < 4; ++j) {
;             float c, sn; rot_cs(pos, frq[j], c, sn);
;             float oth = shx(mine[j], 32);
;             outv[j] = (fq < 2) ? (mine[j] * c - oth * sn) : (mine[j] * c + oth * sn);
;           }
;           v[0].x = outv[0]; v[0].y = outv[1]; v[0].z = outv[2]; v[0].w = outv[3];
.LBB0_247:
	s_movk_i32 s2, 0xc00
	v_cmp_gt_i32_e32 vcc, s2, v158
	v_mov_b32_e32 v0, 0x68
	v_mov_b32_e32 v50, 0x60
	v_readlane_b32 s20, v253, 3
	v_cndmask_b32_e32 v0, v0, v50, vcc
	v_readlane_b32 s21, v253, 4
	v_mov_b32_e32 v54, v71
	v_mov_b32_e32 v55, v59
	v_lshl_add_u64 v[50:51], s[20:21], 0, v[0:1]
	global_load_dwordx2 v[172:173], v[50:51], off
	s_nop 0
	v_mov_b32_e32 v52, v70
	v_mov_b32_e32 v53, v58
	v_pk_mul_f32 v[54:55], v[54:55], v[54:55]
	s_mov_b32 s2, 0x800000
	v_pk_fma_f32 v[52:53], v[52:53], v[52:53], v[54:55]
	v_mov_b32_e32 v54, v68
	v_mov_b32_e32 v55, v60
	v_pk_fma_f32 v[52:53], v[54:55], v[54:55], v[52:53]
	v_mov_b32_e32 v54, v69
	v_mov_b32_e32 v55, v61
	v_pk_fma_f32 v[52:53], v[54:55], v[54:55], v[52:53]
	v_pk_mul_f32 v[54:55], v[74:75], v[74:75]
	v_add_f32_e32 v0, v52, v53
	v_pk_fma_f32 v[54:55], v[72:73], v[72:73], v[54:55]
	v_mov_b32_e32 v52, v229
	v_pk_fma_f32 v[54:55], v[76:77], v[76:77], v[54:55]
	v_readlane_b32 s20, v255, 17
	v_pk_fma_f32 v[54:55], v[78:79], v[78:79], v[54:55]
	v_lshlrev_b32_e32 v52, 2, v52
	v_add_f32_e32 v0, v55, v0
	v_add_f32_e32 v0, v54, v0
	v_xor_b32_e32 v52, 64, v52
	ds_bpermute_b32 v52, v52, v0
	v_readlane_b32 s21, v255, 18
	v_mov_b32_e32 v123, v1
	v_mov_b32_e32 v62, v73
	v_mov_b32_e32 v63, v75
	s_waitcnt lgkmcnt(0)
	v_add_f32_e32 v0, v0, v52
	v_mov_b32_e32 v52, v229
	v_mov_b32_e32 v73, v74
	v_lshlrev_b32_e32 v52, 2, v52
	v_xor_b32_e32 v52, 0x80, v52
	ds_bpermute_b32 v52, v52, v0
	v_mov_b32_e32 v75, v229
	s_waitcnt lgkmcnt(0)
	v_add_f32_e32 v0, v0, v52
	v_fmamk_f32 v0, v0, 0x3c800000, v228
	v_cmp_gt_f32_e64 s[28:29], s2, v0
	v_mul_f32_e32 v52, 0x4b800000, v0
	s_waitcnt vmcnt(0)
	v_lshl_add_u64 v[50:51], s[20:21], 2, v[172:173]
	v_cndmask_b32_e64 v0, v0, v52, s[28:29]
	v_rsq_f32_e32 v0, v0
	v_lshl_add_u64 v[80:81], v[50:51], 0, v[122:123]
	global_load_dwordx4 v[176:179], v[80:81], off
	global_load_dwordx4 v[180:183], v[80:81], off offset:64
	global_load_dwordx4 v[184:187], v[80:81], off offset:128
	global_load_dwordx4 v[188:191], v[80:81], off offset:192
	v_readlane_b32 s20, v253, 54
	v_readlane_b32 s21, v253, 55
	v_mul_f32_e32 v52, 0x45800000, v0
	v_cndmask_b32_e64 v0, v0, v52, s[28:29]
	v_cndmask_b32_e32 v52, 1.0, v252, vcc
	v_mul_f32_e32 v0, v52, v0
	s_nop 0
	s_nop 0
	global_load_dwordx4 v[192:195], v150, s[20:21]
	s_waitcnt vmcnt(4)
	v_pk_mul_f32 v[54:55], v[176:177], v[0:1] op_sel_hi:[1,0]
	s_waitcnt vmcnt(3)
	v_pk_mul_f32 v[50:51], v[180:181], v[0:1] op_sel_hi:[1,0]
	v_pk_mul_f32 v[52:53], v[182:183], v[0:1] op_sel_hi:[1,0]
	v_pk_mul_f32 v[50:51], v[58:59], v[50:51]
	v_pk_mul_f32 v[52:53], v[60:61], v[52:53]
	s_nop 0
	v_pk_mul_f32 v[54:55], v[70:71], v[54:55]
	v_pk_mul_f32 v[56:57], v[178:179], v[0:1] op_sel_hi:[1,0]
	s_waitcnt vmcnt(2)
	v_pk_mul_f32 v[58:59], v[184:185], v[0:1] op_sel_hi:[1,0]
	s_nop 0
	v_pk_mul_f32 v[64:65], v[62:63], v[58:59]
	v_pk_mul_f32 v[58:59], v[186:187], v[0:1] op_sel_hi:[1,0]
	v_mov_b32_e32 v60, v77
	v_mov_b32_e32 v61, v79
	v_pk_mul_f32 v[62:63], v[60:61], v[58:59]
	s_nop 0
	v_mov_b32_e32 v77, v78
	v_pk_mul_f32 v[56:57], v[68:69], v[56:57]
	s_waitcnt vmcnt(1)
	v_pk_mul_f32 v[58:59], v[188:189], v[0:1] op_sel_hi:[1,0]
	s_nop 0
	v_pk_mul_f32 v[82:83], v[72:73], v[58:59]
	v_pk_mul_f32 v[58:59], v[190:191], v[0:1] op_sel_hi:[1,0]
	v_mov_b32_e32 v73, v229
	v_pk_mul_f32 v[80:81], v[76:77], v[58:59]
	s_nop 0
	s_waitcnt vmcnt(0)
	v_mul_f32_e32 v72, v192, v94
	v_lshlrev_b32_e32 v73, 2, v73
	v_xor_b32_e32 v74, 0x80, v73
	v_mul_f32_e32 v73, v193, v94
	v_lshlrev_b32_e32 v75, 2, v75
	v_floor_f32_e32 v72, v72
	v_floor_f32_e32 v73, v73
	v_xor_b32_e32 v75, 0x80, v75
	v_fma_f32 v72, v192, v94, -v72
	v_fma_f32 v73, v193, v94, -v73
	ds_bpermute_b32 v70, v74, v54
	ds_bpermute_b32 v71, v75, v55
	v_cos_f32_e32 v58, v72
	v_sin_f32_e32 v72, v72
	v_cos_f32_e32 v59, v73
	v_sin_f32_e32 v73, v73
	v_mov_b32_e32 v75, v229
	s_waitcnt lgkmcnt(0)
	v_pk_mul_f32 v[70:71], v[72:73], v[70:71]
	v_mov_b32_e32 v73, v229
	v_mul_f32_e32 v72, v194, v94
	v_lshlrev_b32_e32 v73, 2, v73
	v_xor_b32_e32 v74, 0x80, v73
	v_mul_f32_e32 v73, v195, v94
	v_lshlrev_b32_e32 v75, 2, v75
	v_floor_f32_e32 v72, v72
	v_floor_f32_e32 v73, v73
	v_xor_b32_e32 v75, 0x80, v75
	v_fma_f32 v72, v194, v94, -v72
	v_fma_f32 v73, v195, v94, -v73
	ds_bpermute_b32 v68, v74, v56
	ds_bpermute_b32 v69, v75, v57
	v_cos_f32_e32 v60, v72
	v_sin_f32_e32 v72, v72
	v_cos_f32_e32 v61, v73
	v_sin_f32_e32 v73, v73
	v_cndmask_b32_e64 v71, v71, -v71, s[4:5]
	v_cndmask_b32_e64 v70, v70, -v70, s[4:5]
	v_pk_fma_f32 v[84:85], v[58:59], v[54:55], v[70:71]
	s_waitcnt lgkmcnt(0)
	v_pk_mul_f32 v[68:69], v[72:73], v[68:69]
	s_nop 0
	v_cndmask_b32_e64 v69, v69, -v69, s[4:5]
	v_cndmask_b32_e64 v68, v68, -v68, s[4:5]
	v_pk_fma_f32 v[56:57], v[60:61], v[56:57], v[68:69]

; DI float shx(float v, int k) { return __int_as_float(__builtin_amdgcn_ds_bpermute((lane_id_l() ^ k) << 2, __float_as_int(v))); }
; DI void inproj_tile8(const Params& P, const WsPtrs& W, int layer, int mt, int nt, unsigned char* smem) {
;     ...
;         if (qsec) {
;           const bool isq = cb < O_BK;
;           const float* gp = (isq ? P.in[I_DQG] : P.in[I_DKG]) + layer * 64;
;           float ss = 0.f;
; #pragma unroll
;           for (int m = 0; m < 4; ++m) ss += v[m].x * v[m].x + v[m].y * v[m].y + v[m].z * v[m].z + v[m].w * v[m].w;
;           ss += shx(ss, 16);
;           ss += shx(ss, 32);
;           const float sc = rsqrtf(ss * (1.f / 64.f) + EPSV) * (isq ? 0.125f * LOG2E : 1.f);
; #pragma unroll
;           for (int m = 0; m < 4; ++m) {
;             const f32x4 g4 = *(const f32x4*)(gp + m * 16 + fq * 4);
;             v[m].x *= sc * g4.x; v[m].y *= sc * g4.y; v[m].z *= sc * g4.z; v[m].w *= sc * g4.w;
;           }
;           const f32x4 fr4 = *(const f32x4*)(W.rope + (fq & 1) * 4);
;           float mine[4] = {v[0].x, v[0].y, v[0].z, v[0].w}, frq[4] = {fr4.x, fr4.y, fr4.z, fr4.w}, outv[4];
; #pragma unroll
;           for (int j = 0; j < 4; ++j) {
;             float c, sn; rot_cs(pos, frq[j], c, sn);
;             float oth = shx(mine[j], 32);
;             outv[j] = (fq < 2) ? (mine[j] * c - oth * sn) : (mine[j] * c + oth * sn);
;           }
;           v[0].x = outv[0]; v[0].y = outv[1]; v[0].z = outv[2]; v[0].w = outv[3];
.LBB0_264:
	s_movk_i32 s2, 0xc00
	v_cmp_gt_i32_e32 vcc, s2, v158
	v_mov_b32_e32 v0, 0x68
	v_mov_b32_e32 v18, 0x60
	v_readlane_b32 s20, v253, 3
	v_cndmask_b32_e32 v0, v0, v18, vcc
	v_readlane_b32 s21, v253, 4
	v_mov_b32_e32 v22, v39
	v_mov_b32_e32 v23, v27
	v_lshl_add_u64 v[18:19], s[20:21], 0, v[0:1]
	global_load_dwordx2 v[172:173], v[18:19], off
	s_nop 0
	v_mov_b32_e32 v20, v38
	v_mov_b32_e32 v21, v26
	v_pk_mul_f32 v[22:23], v[22:23], v[22:23]
	s_mov_b32 s2, 0x800000
	v_pk_fma_f32 v[20:21], v[20:21], v[20:21], v[22:23]
	v_mov_b32_e32 v22, v36
	v_mov_b32_e32 v23, v28
	v_pk_fma_f32 v[20:21], v[22:23], v[22:23], v[20:21]
	v_mov_b32_e32 v22, v37
	v_mov_b32_e32 v23, v29
	v_pk_fma_f32 v[20:21], v[22:23], v[22:23], v[20:21]
	v_pk_mul_f32 v[22:23], v[42:43], v[42:43]
	v_add_f32_e32 v0, v20, v21
	v_pk_fma_f32 v[22:23], v[40:41], v[40:41], v[22:23]
	v_mov_b32_e32 v20, v229
	v_pk_fma_f32 v[22:23], v[44:45], v[44:45], v[22:23]
	v_readlane_b32 s20, v255, 17
	v_pk_fma_f32 v[22:23], v[46:47], v[46:47], v[22:23]
	v_lshlrev_b32_e32 v20, 2, v20
	v_add_f32_e32 v0, v23, v0
	v_add_f32_e32 v0, v22, v0
	v_xor_b32_e32 v20, 64, v20
	ds_bpermute_b32 v20, v20, v0
	v_readlane_b32 s21, v255, 18
	v_mov_b32_e32 v123, v1
	v_mov_b32_e32 v30, v41
	v_mov_b32_e32 v31, v43
	s_waitcnt lgkmcnt(0)
	v_add_f32_e32 v0, v0, v20
	v_mov_b32_e32 v20, v229
	v_mov_b32_e32 v41, v42
	v_lshlrev_b32_e32 v20, 2, v20
	v_xor_b32_e32 v20, 0x80, v20
	ds_bpermute_b32 v20, v20, v0
	v_mov_b32_e32 v43, v229
	s_waitcnt lgkmcnt(0)
	v_add_f32_e32 v0, v0, v20
	v_fmamk_f32 v0, v0, 0x3c800000, v228
	v_cmp_gt_f32_e64 s[28:29], s2, v0
	v_mul_f32_e32 v20, 0x4b800000, v0
	s_waitcnt vmcnt(0)
	v_lshl_add_u64 v[18:19], s[20:21], 2, v[172:173]
	v_cndmask_b32_e64 v0, v0, v20, s[28:29]
	v_rsq_f32_e32 v0, v0
	v_lshl_add_u64 v[48:49], v[18:19], 0, v[122:123]
	global_load_dwordx4 v[176:179], v[48:49], off
	global_load_dwordx4 v[180:183], v[48:49], off offset:64
	global_load_dwordx4 v[184:187], v[48:49], off offset:128
	global_load_dwordx4 v[188:191], v[48:49], off offset:192
	v_readlane_b32 s20, v253, 54
	v_readlane_b32 s21, v253, 55
	v_mul_f32_e32 v20, 0x45800000, v0
	v_cndmask_b32_e64 v0, v0, v20, s[28:29]
	v_cndmask_b32_e32 v20, 1.0, v252, vcc
	v_mul_f32_e32 v0, v20, v0
	s_nop 0
	s_nop 0
	global_load_dwordx4 v[192:195], v150, s[20:21]
	s_waitcnt vmcnt(4)
	v_pk_mul_f32 v[22:23], v[176:177], v[0:1] op_sel_hi:[1,0]
	s_waitcnt vmcnt(3)
	v_pk_mul_f32 v[18:19], v[180:181], v[0:1] op_sel_hi:[1,0]
	v_pk_mul_f32 v[20:21], v[182:183], v[0:1] op_sel_hi:[1,0]
	v_pk_mul_f32 v[18:19], v[26:27], v[18:19]
	v_pk_mul_f32 v[20:21], v[28:29], v[20:21]
	s_nop 0
	v_pk_mul_f32 v[22:23], v[38:39], v[22:23]
	v_pk_mul_f32 v[24:25], v[178:179], v[0:1] op_sel_hi:[1,0]
	s_waitcnt vmcnt(2)
	v_pk_mul_f32 v[26:27], v[184:185], v[0:1] op_sel_hi:[1,0]
	s_nop 0
	v_pk_mul_f32 v[32:33], v[30:31], v[26:27]
	v_pk_mul_f32 v[26:27], v[186:187], v[0:1] op_sel_hi:[1,0]
	v_mov_b32_e32 v28, v45
	v_mov_b32_e32 v29, v47
	v_pk_mul_f32 v[30:31], v[28:29], v[26:27]
	s_nop 0
	v_mov_b32_e32 v45, v46
	v_pk_mul_f32 v[24:25], v[36:37], v[24:25]
	s_waitcnt vmcnt(1)
	v_pk_mul_f32 v[26:27], v[188:189], v[0:1] op_sel_hi:[1,0]
	s_nop 0
	v_pk_mul_f32 v[50:51], v[40:41], v[26:27]
	v_pk_mul_f32 v[26:27], v[190:191], v[0:1] op_sel_hi:[1,0]
	v_mov_b32_e32 v41, v229
	v_pk_mul_f32 v[48:49], v[44:45], v[26:27]
	s_nop 0
	s_waitcnt vmcnt(0)
	v_mul_f32_e32 v40, v192, v62
	v_lshlrev_b32_e32 v41, 2, v41
	v_xor_b32_e32 v42, 0x80, v41
	v_mul_f32_e32 v41, v193, v62
	v_lshlrev_b32_e32 v43, 2, v43
	v_floor_f32_e32 v40, v40
	v_floor_f32_e32 v41, v41
	v_xor_b32_e32 v43, 0x80, v43
	v_fma_f32 v40, v192, v62, -v40
	v_fma_f32 v41, v193, v62, -v41
	ds_bpermute_b32 v38, v42, v22
	ds_bpermute_b32 v39, v43, v23
	v_cos_f32_e32 v26, v40
	v_sin_f32_e32 v40, v40
	v_cos_f32_e32 v27, v41
	v_sin_f32_e32 v41, v41
	v_mov_b32_e32 v43, v229
	s_waitcnt lgkmcnt(0)
	v_pk_mul_f32 v[38:39], v[40:41], v[38:39]
	v_mov_b32_e32 v41, v229
	v_mul_f32_e32 v40, v194, v62
	v_lshlrev_b32_e32 v41, 2, v41
	v_xor_b32_e32 v42, 0x80, v41
	v_mul_f32_e32 v41, v195, v62
	v_lshlrev_b32_e32 v43, 2, v43
	v_floor_f32_e32 v40, v40
	v_floor_f32_e32 v41, v41
	v_xor_b32_e32 v43, 0x80, v43
	v_fma_f32 v40, v194, v62, -v40
	v_fma_f32 v41, v195, v62, -v41
	ds_bpermute_b32 v36, v42, v24
	ds_bpermute_b32 v37, v43, v25
	v_cos_f32_e32 v28, v40
	v_sin_f32_e32 v40, v40
	v_cos_f32_e32 v29, v41
	v_sin_f32_e32 v41, v41
	v_cndmask_b32_e64 v39, v39, -v39, s[4:5]
	v_cndmask_b32_e64 v38, v38, -v38, s[4:5]
	v_pk_fma_f32 v[52:53], v[26:27], v[22:23], v[38:39]
	s_waitcnt lgkmcnt(0)
	v_pk_mul_f32 v[36:37], v[40:41], v[36:37]
	s_nop 0
	v_cndmask_b32_e64 v37, v37, -v37, s[4:5]
	v_cndmask_b32_e64 v36, v36, -v36, s[4:5]
	v_pk_fma_f32 v[24:25], v[28:29], v[24:25], v[36:37]

; DI u32 pack2(float a, float b) { f2_t v = {a, b}; bf2_t r = __builtin_convertvector(v, bf2_t); return __builtin_bit_cast(u32, r); }
; DI float bflo(u32 v) { return __uint_as_float(v << 16); }
; DI float bfhi(u32 v) { return __uint_as_float(v & 0xffff0000u); }
; DI int get_tid() { int t = threadIdx.x; asm volatile("" : "+v"(t)); return t; }
; DI int vperm(int s) { return (s & ~12) | ((s & 4) << 1) | ((s & 8) >> 1); }
; #define WSP ws_ptrs(P.ws, launder_s(P.G))
; DI void ret_kv_item(const WsPtrs& W, int item, unsigned char* smem) {
;     ...
;   const int bh = item >> 4, qb = item & 15, bl = bh >> 3, hh = bh & 7;
;   const float dl = log2f(1.f - exp2f(-5.f - (float)hh));
;   u16* KTf = (u16*)smem;
;   u16* KTb = KTf + 64 * 264;
;   u16* VT = KTb + 64 * 264;
;   const size_t tok0 = (size_t)bl * 4096 + qb * 256;
;   __syncthreads();
;   {
;     const int j = tid >> 1, half = tid & 1;
;     const u16* kp = W.Y + (tok0 + j) * LDY + O_DK + hh * 64 + half * 32;
;     const float wf = __builtin_amdgcn_exp2f(dl * (float)(255 - j)), wb = __builtin_amdgcn_exp2f(dl * (float)j);
;     const int jp = vperm(j);
; #pragma unroll
;     for (int c = 0; c < 4; ++c) {
;       const u32x4 u = *(const u32x4*)(kp + 8 * c);
;       const float kv[8] = {bflo(u.x), bfhi(u.x), bflo(u.y), bfhi(u.y), bflo(u.z), bfhi(u.z), bflo(u.w), bfhi(u.w)};
; #pragma unroll
;       for (int i = 0; i < 8; ++i) {
;         const int dk = half * 32 + 8 * c + i;
;         KTf[dk * 264 + jp] = (u16)pack2(kv[i] * wf, 0.f);
;         KTb[dk * 264 + jp] = (u16)pack2(kv[i] * wb, 0.f);
;       }
;     }
; __global__ void __launch_bounds__(NTHR, 2) hybrid_encoder_mega(Params P) {
;     ...
;           __syncthreads();
;           if (get_tid() == 0) s_item = atomicAdd(ctr3, 1);
;           __syncthreads();
;           const int t = s_item;
;           if (t >= total3) break;
;           if (t < mtiles * 14) { if (PH(3)) mla_up_tile8(WSP, layer, t, mtiles, smem); } else ret_kv_item(WSP, t - mtiles * 14, smem);
.LBB0_379:
	s_or_b64 exec, exec, s[4:5]
	s_waitcnt lgkmcnt(0)
	s_barrier
	ds_read_b32 v0, v1 offset:48
	v_readlane_b32 s2, v254, 20
	s_mov_b64 s[4:5], -1
	s_waitcnt lgkmcnt(0)
	v_readfirstlane_b32 s10, v0
	v_cmp_le_i32_e32 vcc, s2, v0
	s_cbranch_vccnz .LBB0_374
	v_readlane_b32 s2, v254, 19
	s_cmp_ge_i32 s10, s2
	s_cbranch_scc0 .LBB0_382
	v_readlane_b32 s2, v253, 10
	s_mov_b32 s4, s2
	s_ashr_i32 s5, s4, 31
	s_lshl_b64 s[8:9], s[4:5], 14
	s_add_u32 s2, s62, s8
	s_addc_u32 s8, s63, s9
	s_add_u32 s16, s2, 0x7046100
	s_addc_u32 s17, s8, 0
	s_mul_i32 s8, s4, 0x6600000
	s_mul_hi_i32 s2, s4, 0x6600000
	s_add_u32 s8, s16, s8
	s_addc_u32 s9, s17, s2
	s_lshl_b64 s[12:13], s[4:5], 23
	s_lshl_b64 s[4:5], s[4:5], 24
	s_add_u32 s2, s8, s4
	s_addc_u32 s4, s9, s5
	s_add_u32 s12, s2, s12
	v_readlane_b32 s2, v254, 19
	s_addc_u32 s13, s4, s13
	s_sub_i32 s11, s10, s2
	s_bfe_u32 s5, s11, 0x30004
	v_cvt_f32_ubyte0_e32 v0, s5
	v_sub_f32_e32 v0, 0xc0a00000, v0
	s_mov_b32 s14, 0xc2fc0000
	v_cmp_gt_f32_e32 vcc, s14, v0
	s_lshr_b32 s4, s11, 4
	s_lshr_b32 s2, s11, 7
	v_cndmask_b32_e32 v2, 0, v234, vcc
	v_add_f32_e32 v0, v0, v2
	v_exp_f32_e32 v0, v0
	s_and_b64 s[14:15], vcc, exec
	s_cselect_b32 s14, 0xffffffc0, 0
	v_mov_b32_e32 v14, v250
	v_ldexp_f32 v0, v0, s14
	v_sub_f32_e32 v0, 1.0, v0
	s_mov_b32 s14, 0x800000
	v_cmp_gt_f32_e32 vcc, s14, v0
	s_and_b64 s[14:15], vcc, exec
	s_cselect_b32 s14, 32, 0
	v_ldexp_f32 v0, v0, s14
	v_log_f32_e32 v0, v0
	v_cndmask_b32_e32 v2, 0, v235, vcc
	s_lshl_b64 s[18:19], s[2:3], 12
	s_lshl_b32 s2, s10, 8
	v_sub_f32_e32 v8, v0, v2
	s_and_b32 s14, s2, 0xf00
	v_ashrrev_i32_e32 v2, 1, v14
	s_or_b32 s18, s18, s14
	v_ashrrev_i32_e32 v3, 31, v2
	v_lshl_add_u64 v[4:5], s[18:19], 0, v[2:3]
	v_mov_b64_e32 v[6:7], s[16:17]
	v_cvt_f32_i32_e32 v3, v2
	v_mad_u64_u32 v[6:7], s[16:17], v4, s33, v[6:7]
	v_lshlrev_b32_e32 v0, 5, v14
	v_mad_i32_i24 v7, v5, s33, v7
	s_lshl_b32 s2, s5, 7
	v_and_b32_e32 v20, 32, v0
	v_lshl_add_u64 v[4:5], v[6:7], 0, s[2:3]
	v_lshlrev_b32_e32 v0, 1, v20
	v_lshl_add_u64 v[4:5], v[4:5], 0, v[0:1]
	v_sub_u32_e32 v0, 0xff, v2
	v_mul_f32_e32 v3, v8, v3
	v_cvt_f32_i32_e32 v0, v0
	v_exp_f32_e32 v15, v3
	v_and_b32_e32 v3, 0x7ffffff3, v2
	v_lshrrev_b32_e32 v2, 1, v2
	v_and_b32_e32 v6, 8, v14
	v_and_b32_e32 v2, 4, v2
	s_movk_i32 s2, 0x3000
	s_mov_b64 s[16:17], 0x3400
	v_or3_b32 v21, v3, v6, v2
	v_add_co_u32_e32 v2, vcc, s2, v4
	v_lshl_add_u64 v[10:11], v[4:5], 0, s[16:17]
	s_nop 0
	v_addc_co_u32_e32 v3, vcc, 0, v5, vcc
	s_barrier
	v_mul_f32_e32 v0, v8, v0
	global_load_dwordx4 v[16:19], v[2:3], off offset:1024
	s_nop 0
	global_load_dwordx4 v[2:5], v[10:11], off offset:48
	global_load_dwordx4 v[6:9], v[10:11], off offset:32
	s_nop 0
	global_load_dwordx4 v[10:13], v[10:11], off offset:16
	v_exp_f32_e32 v0, v0
	s_movk_i32 s2, 0x108
	v_mad_u32_u24 v20, v20, s2, v21
	v_lshl_add_u32 v20, v20, 1, 64
	s_mov_b32 s5, s3
	s_lshl_b64 s[4:5], s[4:5], 20
	s_add_u32 s2, s12, s4
	s_addc_u32 s5, s13, s5
	s_lshl_b32 s4, s14, 1
	s_add_u32 s4, s2, s4
	s_addc_u32 s5, s5, 0
	v_readlane_b32 s2, v254, 34
	s_movk_i32 s12, 0x210
	v_and_b32_e32 v35, 31, v14
	s_waitcnt vmcnt(0)
	v_lshlrev_b32_e32 v22, 16, v16
	v_mul_f32_e32 v21, v15, v22
	v_and_b32_e32 v16, 0xffff0000, v16
	v_cvt_pk_bf16_f32 v21, v21, s0
	ds_write_b16 v20, v21 offset:33792
	v_mul_f32_e32 v21, v0, v16
	v_mul_f32_e32 v16, v15, v16
	v_lshlrev_b32_e32 v23, 16, v17
	v_cvt_pk_bf16_f32 v16, v16, s0
	ds_write_b16 v20, v16 offset:34320
	v_mul_f32_e32 v16, v0, v23
	v_cvt_pk_bf16_f32 v16, v16, s0
	ds_write_b16 v20, v16 offset:1056
	v_mul_f32_e32 v16, v15, v23
	v_and_b32_e32 v17, 0xffff0000, v17
	v_cvt_pk_bf16_f32 v16, v16, s0
	ds_write_b16 v20, v16 offset:34848
	v_mul_f32_e32 v16, v0, v17
	v_cvt_pk_bf16_f32 v16, v16, s0
	ds_write_b16 v20, v16 offset:1584
	v_mul_f32_e32 v16, v15, v17
	v_lshlrev_b32_e32 v24, 16, v18
	v_cvt_pk_bf16_f32 v16, v16, s0
	ds_write_b16 v20, v16 offset:35376
	v_mul_f32_e32 v16, v0, v24
	v_cvt_pk_bf16_f32 v16, v16, s0
	ds_write_b16 v20, v16 offset:2112
	v_mul_f32_e32 v16, v15, v24
	v_and_b32_e32 v18, 0xffff0000, v18
	v_cvt_pk_bf16_f32 v16, v16, s0
	ds_write_b16 v20, v16 offset:35904
	v_mul_f32_e32 v16, v0, v18
	v_cvt_pk_bf16_f32 v16, v16, s0
	ds_write_b16 v20, v16 offset:2640
	v_mul_f32_e32 v16, v15, v18
	v_lshlrev_b32_e32 v25, 16, v19
	v_cvt_pk_bf16_f32 v16, v16, s0
	ds_write_b16 v20, v16 offset:36432
	v_mul_f32_e32 v16, v0, v25
	v_cvt_pk_bf16_f32 v16, v16, s0
	ds_write_b16 v20, v16 offset:3168
	v_mul_f32_e32 v16, v15, v25
	v_and_b32_e32 v19, 0xffff0000, v19
	v_cvt_pk_bf16_f32 v16, v16, s0
	ds_write_b16 v20, v16 offset:36960
	v_mul_f32_e32 v16, v0, v19
	v_cvt_pk_bf16_f32 v16, v16, s0
	ds_write_b16 v20, v16 offset:3696
	v_mul_f32_e32 v16, v15, v19
	v_cvt_pk_bf16_f32 v16, v16, s0
	v_cvt_pk_bf16_f32 v21, v21, s0
	ds_write_b16 v20, v16 offset:37488
	s_waitcnt vmcnt(0)
; DI u32 pack2(float a, float b) { f2_t v = {a, b}; bf2_t r = __builtin_convertvector(v, bf2_t); return __builtin_bit_cast(u32, r); }
; DI void ret_kv_item(const WsPtrs& W, int item, unsigned char* smem) {
;     ...
;         const int dk = half * 32 + 8 * c + i;
;         KTf[dk * 264 + jp] = (u16)pack2(kv[i] * wf, 0.f);
;         KTb[dk * 264 + jp] = (u16)pack2(kv[i] * wb, 0.f);
;       }
;     }
;     const u16* vp = W.DVT + (size_t)bh * 128 * 4096 + qb * 256;
; #pragma unroll
;     for (int i = 0; i < 8; ++i) {
;       const int c = tid + 512 * i, row = c >> 5, kc = c & 31;
;       *(u32x4*)(VT + row * 264 + 8 * kc) = *(const u32x4*)(vp + (size_t)row * 4096 + 8 * kc);
	v_lshlrev_b32_e32 v16, 16, v10
	ds_write_b16 v20, v21 offset:528
	v_mul_f32_e32 v21, v0, v16
	v_mul_f32_e32 v16, v15, v16
	v_and_b32_e32 v10, 0xffff0000, v10
	v_cvt_pk_bf16_f32 v16, v16, s0
	ds_write_b16 v20, v16 offset:38016
	v_mul_f32_e32 v16, v0, v10
	v_mul_f32_e32 v10, v15, v10
	v_lshlrev_b32_e32 v17, 16, v11
	v_cvt_pk_bf16_f32 v10, v10, s0
	ds_write_b16 v20, v10 offset:38544
	v_mul_f32_e32 v10, v0, v17
	v_cvt_pk_bf16_f32 v10, v10, s0
	ds_write_b16 v20, v10 offset:5280
	v_mul_f32_e32 v10, v15, v17
	v_and_b32_e32 v11, 0xffff0000, v11
	v_cvt_pk_bf16_f32 v10, v10, s0
	ds_write_b16 v20, v10 offset:39072
	v_mul_f32_e32 v10, v0, v11
	v_cvt_pk_bf16_f32 v10, v10, s0
	ds_write_b16 v20, v10 offset:5808
	v_mul_f32_e32 v10, v15, v11
	v_lshlrev_b32_e32 v18, 16, v12
	v_cvt_pk_bf16_f32 v10, v10, s0
	ds_write_b16 v20, v10 offset:39600
	v_mul_f32_e32 v10, v0, v18
	v_cvt_pk_bf16_f32 v10, v10, s0
	ds_write_b16 v20, v10 offset:6336
	v_mul_f32_e32 v10, v15, v18
	v_and_b32_e32 v12, 0xffff0000, v12
	v_cvt_pk_bf16_f32 v10, v10, s0
	ds_write_b16 v20, v10 offset:40128
	v_mul_f32_e32 v10, v0, v12
	v_cvt_pk_bf16_f32 v10, v10, s0
	ds_write_b16 v20, v10 offset:6864
	v_mul_f32_e32 v10, v15, v12
	v_lshlrev_b32_e32 v19, 16, v13
	v_cvt_pk_bf16_f32 v10, v10, s0
	ds_write_b16 v20, v10 offset:40656
	v_mul_f32_e32 v10, v0, v19
	v_cvt_pk_bf16_f32 v10, v10, s0
	ds_write_b16 v20, v10 offset:7392
	v_mul_f32_e32 v10, v15, v19
	v_and_b32_e32 v13, 0xffff0000, v13
	v_cvt_pk_bf16_f32 v10, v10, s0
	ds_write_b16 v20, v10 offset:41184
	v_mul_f32_e32 v10, v0, v13
	v_cvt_pk_bf16_f32 v10, v10, s0
	ds_write_b16 v20, v10 offset:7920
	v_mul_f32_e32 v10, v15, v13
	v_cvt_pk_bf16_f32 v10, v10, s0
	v_cvt_pk_bf16_f32 v16, v16, s0
	ds_write_b16 v20, v10 offset:41712
	v_lshlrev_b32_e32 v10, 16, v6
	ds_write_b16 v20, v16 offset:4752
	v_mul_f32_e32 v16, v0, v10
	v_mul_f32_e32 v10, v15, v10
	v_and_b32_e32 v6, 0xffff0000, v6
	v_cvt_pk_bf16_f32 v10, v10, s0
	ds_write_b16 v20, v10 offset:42240
	v_mul_f32_e32 v10, v0, v6
	v_mul_f32_e32 v6, v15, v6
	v_lshlrev_b32_e32 v11, 16, v7
	v_cvt_pk_bf16_f32 v6, v6, s0
	ds_write_b16 v20, v6 offset:42768
	v_mul_f32_e32 v6, v0, v11
	v_cvt_pk_bf16_f32 v6, v6, s0
	ds_write_b16 v20, v6 offset:9504
	v_mul_f32_e32 v6, v15, v11
	v_and_b32_e32 v7, 0xffff0000, v7
	v_cvt_pk_bf16_f32 v6, v6, s0
	ds_write_b16 v20, v6 offset:43296
	v_mul_f32_e32 v6, v0, v7
	v_cvt_pk_bf16_f32 v6, v6, s0
	ds_write_b16 v20, v6 offset:10032
	v_mul_f32_e32 v6, v15, v7
	v_lshlrev_b32_e32 v12, 16, v8
	v_cvt_pk_bf16_f32 v6, v6, s0
	ds_write_b16 v20, v6 offset:43824
	v_mul_f32_e32 v6, v0, v12
	v_cvt_pk_bf16_f32 v6, v6, s0
	ds_write_b16 v20, v6 offset:10560
	v_mul_f32_e32 v6, v15, v12
	v_and_b32_e32 v8, 0xffff0000, v8
	v_cvt_pk_bf16_f32 v6, v6, s0
	ds_write_b16 v20, v6 offset:44352
	v_mul_f32_e32 v6, v0, v8
	v_cvt_pk_bf16_f32 v6, v6, s0
	ds_write_b16 v20, v6 offset:11088
	v_mul_f32_e32 v6, v15, v8
	v_lshlrev_b32_e32 v13, 16, v9
	v_cvt_pk_bf16_f32 v6, v6, s0
	ds_write_b16 v20, v6 offset:44880
	v_mul_f32_e32 v6, v0, v13
	v_cvt_pk_bf16_f32 v6, v6, s0
	ds_write_b16 v20, v6 offset:11616
	v_mul_f32_e32 v6, v15, v13
	v_and_b32_e32 v9, 0xffff0000, v9
	v_cvt_pk_bf16_f32 v6, v6, s0
	ds_write_b16 v20, v6 offset:45408
	v_mul_f32_e32 v6, v0, v9
	v_cvt_pk_bf16_f32 v6, v6, s0
	ds_write_b16 v20, v6 offset:12144
	v_mul_f32_e32 v6, v15, v9
	v_cvt_pk_bf16_f32 v6, v6, s0
	v_cvt_pk_bf16_f32 v10, v10, s0
	ds_write_b16 v20, v6 offset:45936
	v_lshlrev_b32_e32 v6, 16, v2
	ds_write_b16 v20, v10 offset:8976
	v_mul_f32_e32 v10, v0, v6
	v_mul_f32_e32 v6, v15, v6
	v_and_b32_e32 v2, 0xffff0000, v2
	v_cvt_pk_bf16_f32 v6, v6, s0
	ds_write_b16 v20, v6 offset:46464
	v_mul_f32_e32 v6, v0, v2
	v_mul_f32_e32 v2, v15, v2
	v_lshlrev_b32_e32 v7, 16, v3
	v_cvt_pk_bf16_f32 v2, v2, s0
	ds_write_b16 v20, v2 offset:46992
	v_mul_f32_e32 v2, v0, v7
	v_cvt_pk_bf16_f32 v2, v2, s0
	ds_write_b16 v20, v2 offset:13728
	v_mul_f32_e32 v2, v15, v7
	v_and_b32_e32 v3, 0xffff0000, v3
	v_cvt_pk_bf16_f32 v2, v2, s0
	ds_write_b16 v20, v2 offset:47520
	v_mul_f32_e32 v2, v0, v3
	v_cvt_pk_bf16_f32 v2, v2, s0
	ds_write_b16 v20, v2 offset:14256
	v_mul_f32_e32 v2, v15, v3
	v_lshlrev_b32_e32 v8, 16, v4
	v_cvt_pk_bf16_f32 v2, v2, s0
	ds_write_b16 v20, v2 offset:48048
	v_mul_f32_e32 v2, v0, v8
	v_cvt_pk_bf16_f32 v2, v2, s0
	ds_write_b16 v20, v2 offset:14784
	v_mul_f32_e32 v2, v15, v8
	v_and_b32_e32 v4, 0xffff0000, v4
	v_cvt_pk_bf16_f32 v2, v2, s0
	ds_write_b16 v20, v2 offset:48576
	v_mul_f32_e32 v2, v0, v4
	v_cvt_pk_bf16_f32 v2, v2, s0
	ds_write_b16 v20, v2 offset:15312
	v_mul_f32_e32 v2, v15, v4
	v_lshlrev_b32_e32 v9, 16, v5
	v_and_b32_e32 v5, 0xffff0000, v5
	v_cvt_pk_bf16_f32 v2, v2, s0
	v_mul_f32_e32 v26, v0, v22
	ds_write_b16 v20, v2 offset:49104
	v_mul_f32_e32 v2, v0, v9
	v_mul_f32_e32 v0, v0, v5
	v_cvt_pk_bf16_f32 v0, v0, s0
	ds_write_b16 v20, v0 offset:16368
	v_mul_f32_e32 v0, v15, v5
	v_cvt_pk_bf16_f32 v6, v6, s0
	v_cvt_pk_bf16_f32 v2, v2, s0
	v_cvt_pk_bf16_f32 v0, v0, s0
	ds_write_b16 v20, v6 offset:13200
	ds_write_b16 v20, v2 offset:15840
	v_mul_f32_e32 v2, v15, v9
	ds_write_b16 v20, v0 offset:50160
	v_lshlrev_b32_e32 v0, 4, v14
	v_ashrrev_i32_e32 v6, 5, v14
	v_cvt_pk_bf16_f32 v2, v2, s0
	v_and_b32_e32 v0, 0x1f0, v0
	v_ashrrev_i32_e32 v7, 31, v6
	ds_write_b16 v20, v2 offset:49632
	v_lshl_add_u64 v[8:9], s[4:5], 0, v[0:1]
	v_lshlrev_b64 v[2:3], 13, v[6:7]
	v_lshl_add_u64 v[2:3], v[8:9], 0, v[2:3]
	global_load_dwordx4 v[100:103], v[2:3], off
	s_mov_b64 s[100:101], 0x20000
	v_lshl_add_u64 v[132:133], v[2:3], 0, s[100:101]
	global_load_dwordx4 v[104:107], v[132:133], off
	v_lshl_add_u64 v[134:135], v[132:133], 0, s[100:101]
	global_load_dwordx4 v[108:111], v[134:135], off
	v_lshl_add_u64 v[136:137], v[134:135], 0, s[100:101]
	global_load_dwordx4 v[112:115], v[136:137], off
	v_lshl_add_u64 v[138:139], v[136:137], 0, s[100:101]
	global_load_dwordx4 v[116:119], v[138:139], off
	v_lshl_add_u64 v[140:141], v[138:139], 0, s[100:101]
	global_load_dwordx4 v[120:123], v[140:141], off
	v_lshl_add_u64 v[142:143], v[140:141], 0, s[100:101]
	global_load_dwordx4 v[124:127], v[142:143], off
	v_lshl_add_u64 v[144:145], v[142:143], 0, s[100:101]
	global_load_dwordx4 v[128:131], v[144:145], off
	v_add_u32_e32 v0, s2, v0
	v_cvt_pk_bf16_f32 v26, v26, s0
	v_cvt_pk_bf16_f32 v21, v21, s0
	v_cvt_pk_bf16_f32 v16, v16, s0
	v_cvt_pk_bf16_f32 v10, v10, s0
	v_mad_u64_u32 v[6:7], s[4:5], v6, s12, v[0:1]
	ds_write_b16 v20, v26
	ds_write_b16 v20, v21 offset:4224
	ds_write_b16 v20, v16 offset:8448
	ds_write_b16 v20, v10 offset:12672
	s_waitcnt vmcnt(7)
; #define MFMA32(a, b, c) __builtin_amdgcn_mfma_f32_32x32x16_bf16((a), (b), (c), 0, 0, 0)
; DI void ret_kv_item(const WsPtrs& W, int item, unsigned char* smem) {
;     ...
; #pragma unroll
;     for (int i = 0; i < 8; ++i) {
;       const int c = tid + 512 * i, row = c >> 5, kc = c & 31;
;       *(u32x4*)(VT + row * 264 + 8 * kc) = *(const u32x4*)(vp + (size_t)row * 4096 + 8 * kc);
;     }
;   }
;   __syncthreads();
;   const int tk = w >> 2, tv = w & 3;
;   f32x16 af, ab;
; #pragma unroll
;   for (int e = 0; e < 16; ++e) { af[e] = 0.f; ab[e] = 0.f; }
; #pragma unroll
;   for (int ks = 0; ks < 16; ++ks) {
;     const bf16x8 vfr = *(const bf16x8*)(VT + (32 * tv + r) * 264 + 16 * ks + 8 * h);
;     const bf16x8 kff = *(const bf16x8*)(KTf + (32 * tk + r) * 264 + 16 * ks + 8 * h);
;     const bf16x8 kfb = *(const bf16x8*)(KTb + (32 * tk + r) * 264 + 16 * ks + 8 * h);
;     af = MFMA32(kff, vfr, af);
;     ab = MFMA32(kfb, vfr, ab);
;   }
;   float* dst = W.KVS + ((size_t)((bh * 16 + qb) * 2)) * 8192 + (32 * tv + r) * 64 + 32 * tk + 4 * h;
; #pragma unroll
;   for (int g = 0; g < 4; ++g) {
;     *(f32x4*)(dst + 8 * g) = f32x4{af[4 * g], af[4 * g + 1], af[4 * g + 2], af[4 * g + 3]};
;     *(f32x4*)(dst + 8192 + 8 * g) = f32x4{ab[4 * g], ab[4 * g + 1], ab[4 * g + 2], ab[4 * g + 3]};
;   }
	ds_write_b128 v6, v[100:103]
	s_waitcnt vmcnt(6)
	ds_write_b128 v6, v[104:107] offset:8448
	s_waitcnt vmcnt(5)
	ds_write_b128 v6, v[108:111] offset:16896
	s_waitcnt vmcnt(4)
	ds_write_b128 v6, v[112:115] offset:25344
	s_waitcnt vmcnt(3)
	ds_write_b128 v6, v[116:119] offset:33792
	s_waitcnt vmcnt(2)
	ds_write_b128 v6, v[120:123] offset:42240
	s_waitcnt vmcnt(1)
	ds_write_b128 v6, v[124:127] offset:50688
	s_waitcnt vmcnt(0)
	ds_write_b128 v6, v[128:131] offset:59136
	v_bfe_u32 v0, v14, 6, 2
	v_lshl_or_b32 v2, v0, 5, v35
	v_lshrrev_b32_e32 v3, 1, v14
	v_mul_u32_u24_e32 v2, 0x210, v2
	v_and_b32_e32 v34, 16, v3
	v_add3_u32 v37, s2, v2, v34
	v_ashrrev_i32_e32 v2, 3, v14
	s_movk_i32 s2, 0xffe0
	v_and_b32_e32 v36, 0xffffffe0, v2
	v_bfi_b32 v2, s2, v2, v14
	v_mul_lo_u32 v2, v2, s12
	v_add3_u32 v50, 64, v2, v34
	s_waitcnt lgkmcnt(0)
	s_barrier
	ds_read_b128 v[2:5], v50 offset:33792
	ds_read_b128 v[6:9], v37
	ds_read_b128 v[38:41], v37 offset:32
	ds_read_b128 v[10:13], v50
	ds_read_b128 v[42:45], v50 offset:32
	s_waitcnt lgkmcnt(1)
	v_mfma_f32_32x32x16_bf16 v[18:33], v[10:13], v[6:9], 0
	ds_read_b128 v[46:49], v50 offset:33824
	s_lshl_b32 s2, s11, 1
	s_lshl_b64 s[4:5], s[2:3], 15
	s_add_u32 s4, s8, s4
	v_lshlrev_b32_e32 v35, 8, v35
	s_addc_u32 s5, s9, s5
	v_lshl_or_b32 v0, v0, 13, v35
	v_mfma_f32_32x32x16_bf16 v[2:17], v[2:5], v[6:9], 0
	v_mov_b32_e32 v35, v1
	s_mov_b32 s2, 0x8000
	s_waitcnt lgkmcnt(1)
	v_mfma_f32_32x32x16_bf16 v[18:33], v[42:45], v[38:41], v[18:33]
	s_waitcnt lgkmcnt(0)
	v_mfma_f32_32x32x16_bf16 v[2:17], v[46:49], v[38:41], v[2:17]
	ds_read_b128 v[38:41], v37 offset:64
	ds_read_b128 v[42:45], v50 offset:64
	ds_read_b128 v[46:49], v50 offset:33856
	s_waitcnt lgkmcnt(1)
	v_mfma_f32_32x32x16_bf16 v[18:33], v[42:45], v[38:41], v[18:33]
	s_waitcnt lgkmcnt(0)
	v_mfma_f32_32x32x16_bf16 v[2:17], v[46:49], v[38:41], v[2:17]
	ds_read_b128 v[38:41], v37 offset:96
	ds_read_b128 v[42:45], v50 offset:96
	ds_read_b128 v[46:49], v50 offset:33888
	s_waitcnt lgkmcnt(1)
	v_mfma_f32_32x32x16_bf16 v[18:33], v[42:45], v[38:41], v[18:33]
	s_waitcnt lgkmcnt(0)
	v_mfma_f32_32x32x16_bf16 v[2:17], v[46:49], v[38:41], v[2:17]
	ds_read_b128 v[38:41], v37 offset:128
	ds_read_b128 v[42:45], v50 offset:128
	ds_read_b128 v[46:49], v50 offset:33920
	s_waitcnt lgkmcnt(1)
	v_mfma_f32_32x32x16_bf16 v[18:33], v[42:45], v[38:41], v[18:33]
	s_waitcnt lgkmcnt(0)
	v_mfma_f32_32x32x16_bf16 v[2:17], v[46:49], v[38:41], v[2:17]
	ds_read_b128 v[38:41], v37 offset:160
	ds_read_b128 v[42:45], v50 offset:160
	ds_read_b128 v[46:49], v50 offset:33952
	s_waitcnt lgkmcnt(1)
	v_mfma_f32_32x32x16_bf16 v[18:33], v[42:45], v[38:41], v[18:33]
	s_waitcnt lgkmcnt(0)
	v_mfma_f32_32x32x16_bf16 v[2:17], v[46:49], v[38:41], v[2:17]
	ds_read_b128 v[38:41], v37 offset:192
	ds_read_b128 v[42:45], v50 offset:192
	ds_read_b128 v[46:49], v50 offset:33984
	s_waitcnt lgkmcnt(1)
	v_mfma_f32_32x32x16_bf16 v[18:33], v[42:45], v[38:41], v[18:33]
	s_waitcnt lgkmcnt(0)
	v_mfma_f32_32x32x16_bf16 v[2:17], v[46:49], v[38:41], v[2:17]
	ds_read_b128 v[38:41], v37 offset:224
	ds_read_b128 v[42:45], v50 offset:224
	ds_read_b128 v[46:49], v50 offset:34016
	s_waitcnt lgkmcnt(1)
	v_mfma_f32_32x32x16_bf16 v[18:33], v[42:45], v[38:41], v[18:33]
	s_waitcnt lgkmcnt(0)
	v_mfma_f32_32x32x16_bf16 v[2:17], v[46:49], v[38:41], v[2:17]
	ds_read_b128 v[38:41], v37 offset:256
	ds_read_b128 v[42:45], v50 offset:256
	ds_read_b128 v[46:49], v50 offset:34048
	s_waitcnt lgkmcnt(1)
	v_mfma_f32_32x32x16_bf16 v[18:33], v[42:45], v[38:41], v[18:33]
	s_waitcnt lgkmcnt(0)
	v_mfma_f32_32x32x16_bf16 v[2:17], v[46:49], v[38:41], v[2:17]
	ds_read_b128 v[38:41], v37 offset:288
	ds_read_b128 v[42:45], v50 offset:288
	ds_read_b128 v[46:49], v50 offset:34080
	s_waitcnt lgkmcnt(1)
	v_mfma_f32_32x32x16_bf16 v[18:33], v[42:45], v[38:41], v[18:33]
	s_waitcnt lgkmcnt(0)
	v_mfma_f32_32x32x16_bf16 v[2:17], v[46:49], v[38:41], v[2:17]
	ds_read_b128 v[38:41], v37 offset:320
	ds_read_b128 v[42:45], v50 offset:320
	ds_read_b128 v[46:49], v50 offset:34112
	s_waitcnt lgkmcnt(1)
	v_mfma_f32_32x32x16_bf16 v[18:33], v[42:45], v[38:41], v[18:33]
	s_waitcnt lgkmcnt(0)
	v_mfma_f32_32x32x16_bf16 v[2:17], v[46:49], v[38:41], v[2:17]
	ds_read_b128 v[38:41], v37 offset:352
	ds_read_b128 v[42:45], v50 offset:352
	ds_read_b128 v[46:49], v50 offset:34144
	s_waitcnt lgkmcnt(1)
	v_mfma_f32_32x32x16_bf16 v[18:33], v[42:45], v[38:41], v[18:33]
	s_waitcnt lgkmcnt(0)
	v_mfma_f32_32x32x16_bf16 v[2:17], v[46:49], v[38:41], v[2:17]
	ds_read_b128 v[38:41], v37 offset:384
	ds_read_b128 v[42:45], v50 offset:384
	ds_read_b128 v[46:49], v50 offset:34176
	s_waitcnt lgkmcnt(1)
	v_mfma_f32_32x32x16_bf16 v[18:33], v[42:45], v[38:41], v[18:33]
	s_waitcnt lgkmcnt(0)
	v_mfma_f32_32x32x16_bf16 v[2:17], v[46:49], v[38:41], v[2:17]
	ds_read_b128 v[38:41], v37 offset:416
	ds_read_b128 v[42:45], v50 offset:416
	ds_read_b128 v[46:49], v50 offset:34208
	s_waitcnt lgkmcnt(1)
	v_mfma_f32_32x32x16_bf16 v[18:33], v[42:45], v[38:41], v[18:33]
	s_waitcnt lgkmcnt(0)
	v_mfma_f32_32x32x16_bf16 v[2:17], v[46:49], v[38:41], v[2:17]
	ds_read_b128 v[38:41], v37 offset:448
	ds_read_b128 v[42:45], v50 offset:448
	ds_read_b128 v[46:49], v50 offset:34240
	s_waitcnt lgkmcnt(1)
	v_mfma_f32_32x32x16_bf16 v[18:33], v[42:45], v[38:41], v[18:33]
	s_waitcnt lgkmcnt(0)
	v_mfma_f32_32x32x16_bf16 v[2:17], v[46:49], v[38:41], v[2:17]
	ds_read_b128 v[38:41], v37 offset:480
	ds_read_b128 v[42:45], v50 offset:480
	ds_read_b128 v[46:49], v50 offset:34272
	v_ashrrev_i32_e32 v37, 31, v36
	s_waitcnt lgkmcnt(1)
	v_mfma_f32_32x32x16_bf16 v[18:33], v[42:45], v[38:41], v[18:33]
	s_waitcnt lgkmcnt(0)
	v_mfma_f32_32x32x16_bf16 v[2:17], v[46:49], v[38:41], v[2:17]
	v_lshl_add_u64 v[38:39], s[4:5], 0, v[0:1]
	v_lshl_add_u64 v[36:37], v[36:37], 2, v[38:39]
	v_lshl_add_u64 v[34:35], v[36:37], 0, v[34:35]
	s_nop 6
	global_store_dwordx4 v[34:35], v[18:21], off
	s_mov_b64 s[4:5], 0
	s_nop 0
	v_add_co_u32_e32 v18, vcc, s2, v34
	s_nop 1
	v_addc_co_u32_e32 v19, vcc, 0, v35, vcc
	global_store_dwordx4 v[18:19], v[2:5], off
	global_store_dwordx4 v[34:35], v[22:25], off offset:32
	global_store_dwordx4 v[18:19], v[6:9], off offset:32
	global_store_dwordx4 v[34:35], v[26:29], off offset:64
	global_store_dwordx4 v[18:19], v[10:13], off offset:64
	global_store_dwordx4 v[34:35], v[30:33], off offset:96
	global_store_dwordx4 v[18:19], v[14:17], off offset:96

; DI float bflo(u32 v) { return __uint_as_float(v << 16); }
; DI float bfhi(u32 v) { return __uint_as_float(v & 0xffff0000u); }
; DI void mla_up_tile8(const WsPtrs& W, int layer, int item, int mtiles, unsigned char* smem) {
;     ...
;   __syncthreads();
;   {
;     int row = tid >> 1, half = tid & 1, kh = K >> 1;
;     const u16* p = A + (size_t)(m0 + row) * LDY + half * kh;
;     float ss = 0.f;
;     for (int c = 0; c < kh; c += 8) {
;       u32x4 v = *(const u32x4*)(p + c);
;       float a;
;       a = bflo(v.x); ss += a * a; a = bfhi(v.x); ss += a * a; a = bflo(v.y); ss += a * a; a = bfhi(v.y); ss += a * a;
;       a = bflo(v.z); ss += a * a; a = bfhi(v.z); ss += a * a; a = bflo(v.w); ss += a * a; a = bfhi(v.w); ss += a * a;
;     }
.LBB0_388:
	s_ashr_i32 s21, s20, 31
	s_lshl_b64 s[14:15], s[20:21], 14
	s_add_u32 s19, s14, 0x7046100
	s_addc_u32 s22, s15, 0
	s_lshl_b32 s2, s2, 8
	s_add_u32 s8, s62, s19
	s_addc_u32 s9, s63, s22
	s_add_u32 s10, s8, s12
	s_addc_u32 s11, s9, s13
	v_ashrrev_i32_e32 v4, 1, v0
	v_and_b32_e32 v5, 1, v0
	s_lshr_b32 s8, s29, 1
	v_add_u32_e32 v0, s2, v4
	v_mov_b64_e32 v[2:3], s[10:11]
	v_mad_i64_i32 v[2:3], s[24:25], v0, s33, v[2:3]
	v_mul_u32_u24_e32 v0, s8, v5
	v_lshlrev_b32_e32 v0, 1, v0
	v_lshl_add_u64 v[2:3], v[2:3], 0, v[0:1]
	s_mov_b32 s9, 0
	v_mov_b32_e32 v0, 0
	s_barrier
	global_load_dwordx4 v[8:11], v[2:3], off
	global_load_dwordx4 v[12:15], v[2:3], off offset:16
	global_load_dwordx4 v[16:19], v[2:3], off offset:32
	global_load_dwordx4 v[20:23], v[2:3], off offset:48
	global_load_dwordx4 v[24:27], v[2:3], off offset:64
	global_load_dwordx4 v[28:31], v[2:3], off offset:80
	global_load_dwordx4 v[32:35], v[2:3], off offset:96
	global_load_dwordx4 v[36:39], v[2:3], off offset:112
	global_load_dwordx4 v[40:43], v[2:3], off offset:128
	global_load_dwordx4 v[44:47], v[2:3], off offset:144
	global_load_dwordx4 v[48:51], v[2:3], off offset:160
	global_load_dwordx4 v[52:55], v[2:3], off offset:176
	global_load_dwordx4 v[56:59], v[2:3], off offset:192
	global_load_dwordx4 v[60:63], v[2:3], off offset:208
	global_load_dwordx4 v[64:67], v[2:3], off offset:224
	global_load_dwordx4 v[68:71], v[2:3], off offset:240
	s_cmp_lt_u32 s8, 0xc0
	s_cbranch_scc1 .Lmu_rinv_a
	global_load_dwordx4 v[72:75], v[2:3], off offset:256
	global_load_dwordx4 v[76:79], v[2:3], off offset:272
	global_load_dwordx4 v[80:83], v[2:3], off offset:288
	global_load_dwordx4 v[84:87], v[2:3], off offset:304
	global_load_dwordx4 v[88:91], v[2:3], off offset:320
	global_load_dwordx4 v[92:95], v[2:3], off offset:336
	global_load_dwordx4 v[96:99], v[2:3], off offset:352
	global_load_dwordx4 v[100:103], v[2:3], off offset:368
	s_waitcnt vmcnt(8)
	s_branch .Lmu_rinv_b
.Lmu_rinv_a:
	s_waitcnt vmcnt(0)
.Lmu_rinv_b:
	v_lshlrev_b32_e32 v104, 16, v8
	v_fmac_f32_e32 v0, v104, v104
	v_lshlrev_b32_e32 v105, 16, v9
	v_and_b32_e32 v104, 0xffff0000, v8
	v_pk_mul_f32 v[104:105], v[104:105], v[104:105]
	s_nop 0
	v_add_f32_e32 v0, v104, v0
	v_add_f32_e32 v0, v105, v0
	v_lshlrev_b32_e32 v105, 16, v10
	v_and_b32_e32 v104, 0xffff0000, v9
	v_pk_mul_f32 v[104:105], v[104:105], v[104:105]
	s_nop 0
	v_add_f32_e32 v0, v104, v0
	v_add_f32_e32 v0, v105, v0
	v_lshlrev_b32_e32 v105, 16, v11
	v_and_b32_e32 v104, 0xffff0000, v10
	v_pk_mul_f32 v[104:105], v[104:105], v[104:105]
	s_nop 0
	v_add_f32_e32 v0, v104, v0
	v_add_f32_e32 v0, v105, v0
	v_and_b32_e32 v104, 0xffff0000, v11
	v_fmac_f32_e32 v0, v104, v104
	v_lshlrev_b32_e32 v104, 16, v12
	v_fmac_f32_e32 v0, v104, v104
	v_lshlrev_b32_e32 v105, 16, v13
	v_and_b32_e32 v104, 0xffff0000, v12
	v_pk_mul_f32 v[104:105], v[104:105], v[104:105]
	s_nop 0
	v_add_f32_e32 v0, v104, v0
	v_add_f32_e32 v0, v105, v0
	v_lshlrev_b32_e32 v105, 16, v14
	v_and_b32_e32 v104, 0xffff0000, v13
	v_pk_mul_f32 v[104:105], v[104:105], v[104:105]
	s_nop 0
	v_add_f32_e32 v0, v104, v0
	v_add_f32_e32 v0, v105, v0
	v_lshlrev_b32_e32 v105, 16, v15
	v_and_b32_e32 v104, 0xffff0000, v14
	v_pk_mul_f32 v[104:105], v[104:105], v[104:105]
	s_nop 0
	v_add_f32_e32 v0, v104, v0
	v_add_f32_e32 v0, v105, v0
	v_and_b32_e32 v104, 0xffff0000, v15
	v_fmac_f32_e32 v0, v104, v104
	v_lshlrev_b32_e32 v104, 16, v16
	v_fmac_f32_e32 v0, v104, v104
	v_lshlrev_b32_e32 v105, 16, v17
	v_and_b32_e32 v104, 0xffff0000, v16
	v_pk_mul_f32 v[104:105], v[104:105], v[104:105]
	s_nop 0
	v_add_f32_e32 v0, v104, v0
	v_add_f32_e32 v0, v105, v0
	v_lshlrev_b32_e32 v105, 16, v18
	v_and_b32_e32 v104, 0xffff0000, v17
	v_pk_mul_f32 v[104:105], v[104:105], v[104:105]
	s_nop 0
	v_add_f32_e32 v0, v104, v0
	v_add_f32_e32 v0, v105, v0
	v_lshlrev_b32_e32 v105, 16, v19
	v_and_b32_e32 v104, 0xffff0000, v18
	v_pk_mul_f32 v[104:105], v[104:105], v[104:105]
	s_nop 0
	v_add_f32_e32 v0, v104, v0
	v_add_f32_e32 v0, v105, v0
	v_and_b32_e32 v104, 0xffff0000, v19
	v_fmac_f32_e32 v0, v104, v104
	v_lshlrev_b32_e32 v104, 16, v20
	v_fmac_f32_e32 v0, v104, v104
	v_lshlrev_b32_e32 v105, 16, v21
	v_and_b32_e32 v104, 0xffff0000, v20
	v_pk_mul_f32 v[104:105], v[104:105], v[104:105]
	s_nop 0
	v_add_f32_e32 v0, v104, v0
	v_add_f32_e32 v0, v105, v0
	v_lshlrev_b32_e32 v105, 16, v22
	v_and_b32_e32 v104, 0xffff0000, v21
	v_pk_mul_f32 v[104:105], v[104:105], v[104:105]
	s_nop 0
	v_add_f32_e32 v0, v104, v0
	v_add_f32_e32 v0, v105, v0
	v_lshlrev_b32_e32 v105, 16, v23
	v_and_b32_e32 v104, 0xffff0000, v22
	v_pk_mul_f32 v[104:105], v[104:105], v[104:105]
	s_nop 0
	v_add_f32_e32 v0, v104, v0
	v_add_f32_e32 v0, v105, v0
	v_and_b32_e32 v104, 0xffff0000, v23
	v_fmac_f32_e32 v0, v104, v104
	v_lshlrev_b32_e32 v104, 16, v24
	v_fmac_f32_e32 v0, v104, v104
	v_lshlrev_b32_e32 v105, 16, v25
	v_and_b32_e32 v104, 0xffff0000, v24
	v_pk_mul_f32 v[104:105], v[104:105], v[104:105]
	s_nop 0
	v_add_f32_e32 v0, v104, v0
	v_add_f32_e32 v0, v105, v0
	v_lshlrev_b32_e32 v105, 16, v26
	v_and_b32_e32 v104, 0xffff0000, v25
	v_pk_mul_f32 v[104:105], v[104:105], v[104:105]
	s_nop 0
	v_add_f32_e32 v0, v104, v0
	v_add_f32_e32 v0, v105, v0
	v_lshlrev_b32_e32 v105, 16, v27
	v_and_b32_e32 v104, 0xffff0000, v26
	v_pk_mul_f32 v[104:105], v[104:105], v[104:105]
	s_nop 0
	v_add_f32_e32 v0, v104, v0
	v_add_f32_e32 v0, v105, v0
	v_and_b32_e32 v104, 0xffff0000, v27
	v_fmac_f32_e32 v0, v104, v104
	v_lshlrev_b32_e32 v104, 16, v28
	v_fmac_f32_e32 v0, v104, v104
	v_lshlrev_b32_e32 v105, 16, v29
	v_and_b32_e32 v104, 0xffff0000, v28
	v_pk_mul_f32 v[104:105], v[104:105], v[104:105]
	s_nop 0
	v_add_f32_e32 v0, v104, v0
; DI float bflo(u32 v) { return __uint_as_float(v << 16); }
; DI float bfhi(u32 v) { return __uint_as_float(v & 0xffff0000u); }
; DI void mla_up_tile8(const WsPtrs& W, int layer, int item, int mtiles, unsigned char* smem) {
;     ...
;     for (int c = 0; c < kh; c += 8) {
;       u32x4 v = *(const u32x4*)(p + c);
;       float a;
;       a = bflo(v.x); ss += a * a; a = bfhi(v.x); ss += a * a; a = bflo(v.y); ss += a * a; a = bfhi(v.y); ss += a * a;
;       a = bflo(v.z); ss += a * a; a = bfhi(v.z); ss += a * a; a = bflo(v.w); ss += a * a; a = bfhi(v.w); ss += a * a;
;     }
	v_add_f32_e32 v0, v105, v0
	v_lshlrev_b32_e32 v105, 16, v30
	v_and_b32_e32 v104, 0xffff0000, v29
	v_pk_mul_f32 v[104:105], v[104:105], v[104:105]
	s_nop 0
	v_add_f32_e32 v0, v104, v0
	v_add_f32_e32 v0, v105, v0
	v_lshlrev_b32_e32 v105, 16, v31
	v_and_b32_e32 v104, 0xffff0000, v30
	v_pk_mul_f32 v[104:105], v[104:105], v[104:105]
	s_nop 0
	v_add_f32_e32 v0, v104, v0
	v_add_f32_e32 v0, v105, v0
	v_and_b32_e32 v104, 0xffff0000, v31
	v_fmac_f32_e32 v0, v104, v104
	v_lshlrev_b32_e32 v104, 16, v32
	v_fmac_f32_e32 v0, v104, v104
	v_lshlrev_b32_e32 v105, 16, v33
	v_and_b32_e32 v104, 0xffff0000, v32
	v_pk_mul_f32 v[104:105], v[104:105], v[104:105]
	s_nop 0
	v_add_f32_e32 v0, v104, v0
	v_add_f32_e32 v0, v105, v0
	v_lshlrev_b32_e32 v105, 16, v34
	v_and_b32_e32 v104, 0xffff0000, v33
	v_pk_mul_f32 v[104:105], v[104:105], v[104:105]
	s_nop 0
	v_add_f32_e32 v0, v104, v0
	v_add_f32_e32 v0, v105, v0
	v_lshlrev_b32_e32 v105, 16, v35
	v_and_b32_e32 v104, 0xffff0000, v34
	v_pk_mul_f32 v[104:105], v[104:105], v[104:105]
	s_nop 0
	v_add_f32_e32 v0, v104, v0
	v_add_f32_e32 v0, v105, v0
	v_and_b32_e32 v104, 0xffff0000, v35
	v_fmac_f32_e32 v0, v104, v104
	v_lshlrev_b32_e32 v104, 16, v36
	v_fmac_f32_e32 v0, v104, v104
	v_lshlrev_b32_e32 v105, 16, v37
	v_and_b32_e32 v104, 0xffff0000, v36
	v_pk_mul_f32 v[104:105], v[104:105], v[104:105]
	s_nop 0
	v_add_f32_e32 v0, v104, v0
	v_add_f32_e32 v0, v105, v0
	v_lshlrev_b32_e32 v105, 16, v38
	v_and_b32_e32 v104, 0xffff0000, v37
	v_pk_mul_f32 v[104:105], v[104:105], v[104:105]
	s_nop 0
	v_add_f32_e32 v0, v104, v0
	v_add_f32_e32 v0, v105, v0
	v_lshlrev_b32_e32 v105, 16, v39
	v_and_b32_e32 v104, 0xffff0000, v38
	v_pk_mul_f32 v[104:105], v[104:105], v[104:105]
	s_nop 0
	v_add_f32_e32 v0, v104, v0
	v_add_f32_e32 v0, v105, v0
	v_and_b32_e32 v104, 0xffff0000, v39
	v_fmac_f32_e32 v0, v104, v104
	v_lshlrev_b32_e32 v104, 16, v40
	v_fmac_f32_e32 v0, v104, v104
	v_lshlrev_b32_e32 v105, 16, v41
	v_and_b32_e32 v104, 0xffff0000, v40
	v_pk_mul_f32 v[104:105], v[104:105], v[104:105]
	s_nop 0
	v_add_f32_e32 v0, v104, v0
	v_add_f32_e32 v0, v105, v0
	v_lshlrev_b32_e32 v105, 16, v42
	v_and_b32_e32 v104, 0xffff0000, v41
	v_pk_mul_f32 v[104:105], v[104:105], v[104:105]
	s_nop 0
	v_add_f32_e32 v0, v104, v0
	v_add_f32_e32 v0, v105, v0
	v_lshlrev_b32_e32 v105, 16, v43
	v_and_b32_e32 v104, 0xffff0000, v42
	v_pk_mul_f32 v[104:105], v[104:105], v[104:105]
	s_nop 0
	v_add_f32_e32 v0, v104, v0
	v_add_f32_e32 v0, v105, v0
	v_and_b32_e32 v104, 0xffff0000, v43
	v_fmac_f32_e32 v0, v104, v104
	v_lshlrev_b32_e32 v104, 16, v44
	v_fmac_f32_e32 v0, v104, v104
	v_lshlrev_b32_e32 v105, 16, v45
	v_and_b32_e32 v104, 0xffff0000, v44
	v_pk_mul_f32 v[104:105], v[104:105], v[104:105]
	s_nop 0
	v_add_f32_e32 v0, v104, v0
	v_add_f32_e32 v0, v105, v0
	v_lshlrev_b32_e32 v105, 16, v46
	v_and_b32_e32 v104, 0xffff0000, v45
	v_pk_mul_f32 v[104:105], v[104:105], v[104:105]
	s_nop 0
	v_add_f32_e32 v0, v104, v0
	v_add_f32_e32 v0, v105, v0
	v_lshlrev_b32_e32 v105, 16, v47
	v_and_b32_e32 v104, 0xffff0000, v46
	v_pk_mul_f32 v[104:105], v[104:105], v[104:105]
	s_nop 0
	v_add_f32_e32 v0, v104, v0
	v_add_f32_e32 v0, v105, v0
	v_and_b32_e32 v104, 0xffff0000, v47
	v_fmac_f32_e32 v0, v104, v104
	v_lshlrev_b32_e32 v104, 16, v48
	v_fmac_f32_e32 v0, v104, v104
	v_lshlrev_b32_e32 v105, 16, v49
	v_and_b32_e32 v104, 0xffff0000, v48
	v_pk_mul_f32 v[104:105], v[104:105], v[104:105]
	s_nop 0
	v_add_f32_e32 v0, v104, v0
	v_add_f32_e32 v0, v105, v0
	v_lshlrev_b32_e32 v105, 16, v50
	v_and_b32_e32 v104, 0xffff0000, v49
	v_pk_mul_f32 v[104:105], v[104:105], v[104:105]
	s_nop 0
	v_add_f32_e32 v0, v104, v0
	v_add_f32_e32 v0, v105, v0
	v_lshlrev_b32_e32 v105, 16, v51
	v_and_b32_e32 v104, 0xffff0000, v50
	v_pk_mul_f32 v[104:105], v[104:105], v[104:105]
	s_nop 0
	v_add_f32_e32 v0, v104, v0
	v_add_f32_e32 v0, v105, v0
	v_and_b32_e32 v104, 0xffff0000, v51
	v_fmac_f32_e32 v0, v104, v104
	v_lshlrev_b32_e32 v104, 16, v52
	v_fmac_f32_e32 v0, v104, v104
	v_lshlrev_b32_e32 v105, 16, v53
	v_and_b32_e32 v104, 0xffff0000, v52
	v_pk_mul_f32 v[104:105], v[104:105], v[104:105]
	s_nop 0
	v_add_f32_e32 v0, v104, v0
	v_add_f32_e32 v0, v105, v0
	v_lshlrev_b32_e32 v105, 16, v54
	v_and_b32_e32 v104, 0xffff0000, v53
	v_pk_mul_f32 v[104:105], v[104:105], v[104:105]
	s_nop 0
	v_add_f32_e32 v0, v104, v0
	v_add_f32_e32 v0, v105, v0
	v_lshlrev_b32_e32 v105, 16, v55
	v_and_b32_e32 v104, 0xffff0000, v54
	v_pk_mul_f32 v[104:105], v[104:105], v[104:105]
	s_nop 0
	v_add_f32_e32 v0, v104, v0
	v_add_f32_e32 v0, v105, v0
	v_and_b32_e32 v104, 0xffff0000, v55
	v_fmac_f32_e32 v0, v104, v104
	v_lshlrev_b32_e32 v104, 16, v56
	v_fmac_f32_e32 v0, v104, v104
	v_lshlrev_b32_e32 v105, 16, v57
	v_and_b32_e32 v104, 0xffff0000, v56
	v_pk_mul_f32 v[104:105], v[104:105], v[104:105]
	s_nop 0
	v_add_f32_e32 v0, v104, v0
	v_add_f32_e32 v0, v105, v0
	v_lshlrev_b32_e32 v105, 16, v58
	v_and_b32_e32 v104, 0xffff0000, v57
	v_pk_mul_f32 v[104:105], v[104:105], v[104:105]
	s_nop 0
	v_add_f32_e32 v0, v104, v0
	v_add_f32_e32 v0, v105, v0
	v_lshlrev_b32_e32 v105, 16, v59
	v_and_b32_e32 v104, 0xffff0000, v58
	v_pk_mul_f32 v[104:105], v[104:105], v[104:105]
	s_nop 0
	v_add_f32_e32 v0, v104, v0
	v_add_f32_e32 v0, v105, v0
	v_and_b32_e32 v104, 0xffff0000, v59
	v_fmac_f32_e32 v0, v104, v104
	v_lshlrev_b32_e32 v104, 16, v60
	v_fmac_f32_e32 v0, v104, v104
	v_lshlrev_b32_e32 v105, 16, v61
	v_and_b32_e32 v104, 0xffff0000, v60
	v_pk_mul_f32 v[104:105], v[104:105], v[104:105]
	s_nop 0
	v_add_f32_e32 v0, v104, v0
	v_add_f32_e32 v0, v105, v0
	v_lshlrev_b32_e32 v105, 16, v62
	v_and_b32_e32 v104, 0xffff0000, v61
	v_pk_mul_f32 v[104:105], v[104:105], v[104:105]
	s_nop 0
; DI float bflo(u32 v) { return __uint_as_float(v << 16); }
; DI float bfhi(u32 v) { return __uint_as_float(v & 0xffff0000u); }
; DI void mla_up_tile8(const WsPtrs& W, int layer, int item, int mtiles, unsigned char* smem) {
;     ...
;     for (int c = 0; c < kh; c += 8) {
;       u32x4 v = *(const u32x4*)(p + c);
;       float a;
;       a = bflo(v.x); ss += a * a; a = bfhi(v.x); ss += a * a; a = bflo(v.y); ss += a * a; a = bfhi(v.y); ss += a * a;
;       a = bflo(v.z); ss += a * a; a = bfhi(v.z); ss += a * a; a = bflo(v.w); ss += a * a; a = bfhi(v.w); ss += a * a;
;     }
	v_add_f32_e32 v0, v104, v0
	v_add_f32_e32 v0, v105, v0
	v_lshlrev_b32_e32 v105, 16, v63
	v_and_b32_e32 v104, 0xffff0000, v62
	v_pk_mul_f32 v[104:105], v[104:105], v[104:105]
	s_nop 0
	v_add_f32_e32 v0, v104, v0
	v_add_f32_e32 v0, v105, v0
	v_and_b32_e32 v104, 0xffff0000, v63
	v_fmac_f32_e32 v0, v104, v104
	v_lshlrev_b32_e32 v104, 16, v64
	v_fmac_f32_e32 v0, v104, v104
	v_lshlrev_b32_e32 v105, 16, v65
	v_and_b32_e32 v104, 0xffff0000, v64
	v_pk_mul_f32 v[104:105], v[104:105], v[104:105]
	s_nop 0
	v_add_f32_e32 v0, v104, v0
	v_add_f32_e32 v0, v105, v0
	v_lshlrev_b32_e32 v105, 16, v66
	v_and_b32_e32 v104, 0xffff0000, v65
	v_pk_mul_f32 v[104:105], v[104:105], v[104:105]
	s_nop 0
	v_add_f32_e32 v0, v104, v0
	v_add_f32_e32 v0, v105, v0
	v_lshlrev_b32_e32 v105, 16, v67
	v_and_b32_e32 v104, 0xffff0000, v66
	v_pk_mul_f32 v[104:105], v[104:105], v[104:105]
	s_nop 0
	v_add_f32_e32 v0, v104, v0
	v_add_f32_e32 v0, v105, v0
	v_and_b32_e32 v104, 0xffff0000, v67
	v_fmac_f32_e32 v0, v104, v104
	v_lshlrev_b32_e32 v104, 16, v68
	v_fmac_f32_e32 v0, v104, v104
	v_lshlrev_b32_e32 v105, 16, v69
	v_and_b32_e32 v104, 0xffff0000, v68
	v_pk_mul_f32 v[104:105], v[104:105], v[104:105]
	s_nop 0
	v_add_f32_e32 v0, v104, v0
	v_add_f32_e32 v0, v105, v0
	v_lshlrev_b32_e32 v105, 16, v70
	v_and_b32_e32 v104, 0xffff0000, v69
	v_pk_mul_f32 v[104:105], v[104:105], v[104:105]
	s_nop 0
	v_add_f32_e32 v0, v104, v0
	v_add_f32_e32 v0, v105, v0
	v_lshlrev_b32_e32 v105, 16, v71
	v_and_b32_e32 v104, 0xffff0000, v70
	v_pk_mul_f32 v[104:105], v[104:105], v[104:105]
	s_nop 0
	v_add_f32_e32 v0, v104, v0
	v_add_f32_e32 v0, v105, v0
	v_and_b32_e32 v104, 0xffff0000, v71
	v_fmac_f32_e32 v0, v104, v104
	s_cmp_lt_u32 s8, 0xc0
	s_cbranch_scc1 .Lmu_rinv_done
; DI float bflo(u32 v) { return __uint_as_float(v << 16); }
; DI float bfhi(u32 v) { return __uint_as_float(v & 0xffff0000u); }
; DI float shx(float v, int k) { return __int_as_float(__builtin_amdgcn_ds_bpermute((lane_id_l() ^ k) << 2, __float_as_int(v))); }
; DI void mla_up_tile8(const WsPtrs& W, int layer, int item, int mtiles, unsigned char* smem) {
;     ...
;     for (int c = 0; c < kh; c += 8) {
;       u32x4 v = *(const u32x4*)(p + c);
;       float a;
;       a = bflo(v.x); ss += a * a; a = bfhi(v.x); ss += a * a; a = bflo(v.y); ss += a * a; a = bfhi(v.y); ss += a * a;
;       a = bflo(v.z); ss += a * a; a = bfhi(v.z); ss += a * a; a = bflo(v.w); ss += a * a; a = bfhi(v.w); ss += a * a;
;     }
;     ss += shx(ss, 1);
;     if (half == 0) rs[row] = rsqrtf(ss / (float)K + EPSV);
;   }
	s_waitcnt vmcnt(0)
	v_lshlrev_b32_e32 v104, 16, v72
	v_fmac_f32_e32 v0, v104, v104
	v_lshlrev_b32_e32 v105, 16, v73
	v_and_b32_e32 v104, 0xffff0000, v72
	v_pk_mul_f32 v[104:105], v[104:105], v[104:105]
	s_nop 0
	v_add_f32_e32 v0, v104, v0
	v_add_f32_e32 v0, v105, v0
	v_lshlrev_b32_e32 v105, 16, v74
	v_and_b32_e32 v104, 0xffff0000, v73
	v_pk_mul_f32 v[104:105], v[104:105], v[104:105]
	s_nop 0
	v_add_f32_e32 v0, v104, v0
	v_add_f32_e32 v0, v105, v0
	v_lshlrev_b32_e32 v105, 16, v75
	v_and_b32_e32 v104, 0xffff0000, v74
	v_pk_mul_f32 v[104:105], v[104:105], v[104:105]
	s_nop 0
	v_add_f32_e32 v0, v104, v0
	v_add_f32_e32 v0, v105, v0
	v_and_b32_e32 v104, 0xffff0000, v75
	v_fmac_f32_e32 v0, v104, v104
	v_lshlrev_b32_e32 v104, 16, v76
	v_fmac_f32_e32 v0, v104, v104
	v_lshlrev_b32_e32 v105, 16, v77
	v_and_b32_e32 v104, 0xffff0000, v76
	v_pk_mul_f32 v[104:105], v[104:105], v[104:105]
	s_nop 0
	v_add_f32_e32 v0, v104, v0
	v_add_f32_e32 v0, v105, v0
	v_lshlrev_b32_e32 v105, 16, v78
	v_and_b32_e32 v104, 0xffff0000, v77
	v_pk_mul_f32 v[104:105], v[104:105], v[104:105]
	s_nop 0
	v_add_f32_e32 v0, v104, v0
	v_add_f32_e32 v0, v105, v0
	v_lshlrev_b32_e32 v105, 16, v79
	v_and_b32_e32 v104, 0xffff0000, v78
	v_pk_mul_f32 v[104:105], v[104:105], v[104:105]
	s_nop 0
	v_add_f32_e32 v0, v104, v0
	v_add_f32_e32 v0, v105, v0
	v_and_b32_e32 v104, 0xffff0000, v79
	v_fmac_f32_e32 v0, v104, v104
	v_lshlrev_b32_e32 v104, 16, v80
	v_fmac_f32_e32 v0, v104, v104
	v_lshlrev_b32_e32 v105, 16, v81
	v_and_b32_e32 v104, 0xffff0000, v80
	v_pk_mul_f32 v[104:105], v[104:105], v[104:105]
	s_nop 0
	v_add_f32_e32 v0, v104, v0
	v_add_f32_e32 v0, v105, v0
	v_lshlrev_b32_e32 v105, 16, v82
	v_and_b32_e32 v104, 0xffff0000, v81
	v_pk_mul_f32 v[104:105], v[104:105], v[104:105]
	s_nop 0
	v_add_f32_e32 v0, v104, v0
	v_add_f32_e32 v0, v105, v0
	v_lshlrev_b32_e32 v105, 16, v83
	v_and_b32_e32 v104, 0xffff0000, v82
	v_pk_mul_f32 v[104:105], v[104:105], v[104:105]
	s_nop 0
	v_add_f32_e32 v0, v104, v0
	v_add_f32_e32 v0, v105, v0
	v_and_b32_e32 v104, 0xffff0000, v83
	v_fmac_f32_e32 v0, v104, v104
	v_lshlrev_b32_e32 v104, 16, v84
	v_fmac_f32_e32 v0, v104, v104
	v_lshlrev_b32_e32 v105, 16, v85
	v_and_b32_e32 v104, 0xffff0000, v84
	v_pk_mul_f32 v[104:105], v[104:105], v[104:105]
	s_nop 0
	v_add_f32_e32 v0, v104, v0
	v_add_f32_e32 v0, v105, v0
	v_lshlrev_b32_e32 v105, 16, v86
	v_and_b32_e32 v104, 0xffff0000, v85
	v_pk_mul_f32 v[104:105], v[104:105], v[104:105]
	s_nop 0
	v_add_f32_e32 v0, v104, v0
	v_add_f32_e32 v0, v105, v0
	v_lshlrev_b32_e32 v105, 16, v87
	v_and_b32_e32 v104, 0xffff0000, v86
	v_pk_mul_f32 v[104:105], v[104:105], v[104:105]
	s_nop 0
	v_add_f32_e32 v0, v104, v0
	v_add_f32_e32 v0, v105, v0
	v_and_b32_e32 v104, 0xffff0000, v87
	v_fmac_f32_e32 v0, v104, v104
	v_lshlrev_b32_e32 v104, 16, v88
	v_fmac_f32_e32 v0, v104, v104
	v_lshlrev_b32_e32 v105, 16, v89
	v_and_b32_e32 v104, 0xffff0000, v88
	v_pk_mul_f32 v[104:105], v[104:105], v[104:105]
	s_nop 0
	v_add_f32_e32 v0, v104, v0
	v_add_f32_e32 v0, v105, v0
	v_lshlrev_b32_e32 v105, 16, v90
	v_and_b32_e32 v104, 0xffff0000, v89
	v_pk_mul_f32 v[104:105], v[104:105], v[104:105]
	s_nop 0
	v_add_f32_e32 v0, v104, v0
	v_add_f32_e32 v0, v105, v0
	v_lshlrev_b32_e32 v105, 16, v91
	v_and_b32_e32 v104, 0xffff0000, v90
	v_pk_mul_f32 v[104:105], v[104:105], v[104:105]
	s_nop 0
	v_add_f32_e32 v0, v104, v0
	v_add_f32_e32 v0, v105, v0
	v_and_b32_e32 v104, 0xffff0000, v91
	v_fmac_f32_e32 v0, v104, v104
	v_lshlrev_b32_e32 v104, 16, v92
	v_fmac_f32_e32 v0, v104, v104
	v_lshlrev_b32_e32 v105, 16, v93
	v_and_b32_e32 v104, 0xffff0000, v92
	v_pk_mul_f32 v[104:105], v[104:105], v[104:105]
	s_nop 0
	v_add_f32_e32 v0, v104, v0
	v_add_f32_e32 v0, v105, v0
	v_lshlrev_b32_e32 v105, 16, v94
	v_and_b32_e32 v104, 0xffff0000, v93
	v_pk_mul_f32 v[104:105], v[104:105], v[104:105]
	s_nop 0
	v_add_f32_e32 v0, v104, v0
	v_add_f32_e32 v0, v105, v0
	v_lshlrev_b32_e32 v105, 16, v95
	v_and_b32_e32 v104, 0xffff0000, v94
	v_pk_mul_f32 v[104:105], v[104:105], v[104:105]
	s_nop 0
	v_add_f32_e32 v0, v104, v0
	v_add_f32_e32 v0, v105, v0
	v_and_b32_e32 v104, 0xffff0000, v95
	v_fmac_f32_e32 v0, v104, v104
	v_lshlrev_b32_e32 v104, 16, v96
	v_fmac_f32_e32 v0, v104, v104
	v_lshlrev_b32_e32 v105, 16, v97
	v_and_b32_e32 v104, 0xffff0000, v96
	v_pk_mul_f32 v[104:105], v[104:105], v[104:105]
	s_nop 0
	v_add_f32_e32 v0, v104, v0
	v_add_f32_e32 v0, v105, v0
	v_lshlrev_b32_e32 v105, 16, v98
	v_and_b32_e32 v104, 0xffff0000, v97
	v_pk_mul_f32 v[104:105], v[104:105], v[104:105]
	s_nop 0
	v_add_f32_e32 v0, v104, v0
	v_add_f32_e32 v0, v105, v0
	v_lshlrev_b32_e32 v105, 16, v99
	v_and_b32_e32 v104, 0xffff0000, v98
	v_pk_mul_f32 v[104:105], v[104:105], v[104:105]
	s_nop 0
	v_add_f32_e32 v0, v104, v0
	v_add_f32_e32 v0, v105, v0
	v_and_b32_e32 v104, 0xffff0000, v99
	v_fmac_f32_e32 v0, v104, v104
	v_lshlrev_b32_e32 v104, 16, v100
	v_fmac_f32_e32 v0, v104, v104
	v_lshlrev_b32_e32 v105, 16, v101
	v_and_b32_e32 v104, 0xffff0000, v100
	v_pk_mul_f32 v[104:105], v[104:105], v[104:105]
	s_nop 0
	v_add_f32_e32 v0, v104, v0
	v_add_f32_e32 v0, v105, v0
	v_lshlrev_b32_e32 v105, 16, v102
	v_and_b32_e32 v104, 0xffff0000, v101
	v_pk_mul_f32 v[104:105], v[104:105], v[104:105]
	s_nop 0
	v_add_f32_e32 v0, v104, v0
	v_add_f32_e32 v0, v105, v0
	v_lshlrev_b32_e32 v105, 16, v103
	v_and_b32_e32 v104, 0xffff0000, v102
	v_pk_mul_f32 v[104:105], v[104:105], v[104:105]
	s_nop 0
	v_add_f32_e32 v0, v104, v0
	v_add_f32_e32 v0, v105, v0
	v_and_b32_e32 v104, 0xffff0000, v103
	v_fmac_f32_e32 v0, v104, v104
.Lmu_rinv_done:
	v_mov_b32_e32 v2, v229
	v_cmp_eq_u32_e32 vcc, 0, v5
	v_lshlrev_b32_e32 v2, 2, v2
	v_xor_b32_e32 v2, 4, v2
	ds_bpermute_b32 v2, v2, v0
	s_and_saveexec_b64 s[8:9], vcc
	s_cbranch_execz .LBB0_392
	v_cvt_f32_u32_e32 v3, s29
	s_waitcnt lgkmcnt(0)
	v_add_f32_e32 v0, v0, v2
	s_mov_b32 s23, 0x800000
	v_div_scale_f32 v2, s[24:25], v3, v3, v0
	v_rcp_f32_e32 v5, v2
	v_div_scale_f32 v6, vcc, v0, v3, v0
	v_fma_f32 v7, -v2, v5, 1.0
	v_fmac_f32_e32 v5, v7, v5
	v_mul_f32_e32 v7, v6, v5
	v_fma_f32 v8, -v2, v7, v6
	v_fmac_f32_e32 v7, v8, v5
	v_fma_f32 v2, -v2, v7, v6
	v_div_fmas_f32 v2, v2, v5, v7
	v_div_fixup_f32 v0, v2, v3, v0
	v_add_f32_e32 v0, 0x358637bd, v0
	v_mul_f32_e32 v2, 0x4b800000, v0
	v_cmp_gt_f32_e32 vcc, s23, v0
	s_nop 1
	v_cndmask_b32_e32 v0, v0, v2, vcc
	v_rsq_f32_e32 v0, v0
	v_lshl_add_u32 v2, v4, 2, 64
	v_add_u32_e32 v2, 0x24000, v2
	v_mul_f32_e32 v3, 0x45800000, v0
	v_cndmask_b32_e32 v0, v0, v3, vcc
	ds_write_b32 v2, v0

; DI float shx(float v, int k) { return __int_as_float(__builtin_amdgcn_ds_bpermute((lane_id_l() ^ k) << 2, __float_as_int(v))); }
; DI int get_tid() { int t = threadIdx.x; asm volatile("" : "+v"(t)); return t; }
; DI void diff_attn_item(const Params& P, const WsPtrs& W, int layer, int item, unsigned char* smem) {
;   const int w = get_tid() >> 6, lane = get_tid() & 63, r = lane & 31, h = lane >> 5;
;   int bh = item >> 5, qb = item & 31, bl = bh >> 3, hh = bh & 7;
;   int sub = w >> 2;
;   int q0 = qb * 128 + 32 * (w & 3);
;   size_t tokb = (size_t)bl * 4096;
;   f32x16 o[4]; float l;
;   float gq = fabsf(P.in[I_DQG][layer * 64 + lane]), gk = fabsf(P.in[I_DKG][layer * 64 + lane]);
; #pragma unroll
;   for (int of = 32; of > 0; of >>= 1) { gq = fmaxf(gq, shx(gq, of)); gk = fmaxf(gk, shx(gk, of)); }
;   const float M = 11.5416f * gq * gk * 1.02f + 1.f;
;   if (M <= 56.f)
;     attn_core<128, 64, 1>(W.Y + (tokb + q0) * LDY + O_BQ + hh * 128 + sub * 64, LDY, W.Y + tokb * LDY + O_BK + hh * 128, LDY,
;                           W.BVT + (size_t)bh * 128 * 4096, sub * 64, q0, M, o, l, smem);
.LBB0_558:
	v_readlane_b32 s2, v253, 10
	s_mov_b32 s8, s2
	v_mov_b32_e32 v161, v250
	s_waitcnt vmcnt(1)
	v_mov_b32_e32 v162, v250
	v_readlane_b32 s6, v255, 17
	v_and_b32_e32 v163, 63, v162
	v_readlane_b32 s20, v254, 49
	v_or_b32_e32 v0, s6, v163
	v_lshlrev_b64 v[2:3], 2, v[0:1]
	v_readlane_b32 s21, v254, 50
	v_readlane_b32 s22, v254, 51
	v_readlane_b32 s23, v254, 52
	v_lshl_add_u64 v[4:5], s[20:21], 0, v[2:3]
	global_load_dword v0, v[4:5], off
	v_lshl_add_u64 v[2:3], s[22:23], 0, v[2:3]
	global_load_dword v2, v[2:3], off
	v_mov_b32_e32 v3, v229
	v_mov_b32_e32 v4, v229
	v_mov_b32_e32 v5, v229
	v_lshlrev_b32_e32 v3, 2, v3
	v_lshlrev_b32_e32 v4, 2, v4
	v_xor_b32_e32 v3, 0x80, v3
	v_xor_b32_e32 v4, 0x80, v4
	v_mov_b32_e32 v6, v229
	v_mov_b32_e32 v7, v229
	v_lshlrev_b32_e32 v5, 2, v5
	v_lshlrev_b32_e32 v6, 2, v6
	v_xor_b32_e32 v5, 64, v5
	v_xor_b32_e32 v6, 64, v6
	v_mov_b32_e32 v8, v229
	v_mov_b32_e32 v9, v229
	v_lshlrev_b32_e32 v7, 2, v7
	v_lshlrev_b32_e32 v8, 2, v8
	v_xor_b32_e32 v7, 32, v7
	v_xor_b32_e32 v8, 32, v8
	v_mov_b32_e32 v10, v229
	v_mov_b32_e32 v11, v229
	v_lshlrev_b32_e32 v9, 2, v9
	v_lshlrev_b32_e32 v10, 2, v10
	v_xor_b32_e32 v9, 16, v9
	v_xor_b32_e32 v10, 16, v10
	v_mov_b32_e32 v12, v229
	v_mov_b32_e32 v13, v229
	v_lshlrev_b32_e32 v11, 2, v11
	v_lshlrev_b32_e32 v12, 2, v12
	v_xor_b32_e32 v11, 8, v11
	v_xor_b32_e32 v12, 8, v12
	v_mov_b32_e32 v14, v229
	s_ashr_i32 s9, s8, 31
	s_lshl_b64 s[10:11], s[8:9], 14
	v_lshlrev_b32_e32 v13, 2, v13
	s_add_u32 s22, s10, 0x7046100
	v_lshlrev_b32_e32 v14, 2, v14
	v_xor_b32_e32 v13, 4, v13
	s_addc_u32 s23, s11, 0
	v_xor_b32_e32 v14, 4, v14
	v_readlane_b32 s7, v255, 18
	s_add_u32 s12, s62, s22
	s_mul_i32 s21, s8, 0x6600000
	s_addc_u32 s13, s63, s23
	s_lshl_b64 s[6:7], s[8:9], 24
	s_mul_hi_i32 s20, s8, 0x6600000
	s_add_u32 s2, s12, s21
	v_readlane_b32 s26, v254, 55
	s_addc_u32 s14, s13, s20
	v_readlane_b32 s27, v254, 56
	s_add_u32 s26, s2, s6
	s_addc_u32 s27, s14, s7
	s_lshr_b32 s2, s19, 2
	s_bfe_i32 s14, s19, 0x180005
	s_lshl_b32 s6, s19, 7
	v_bfe_u32 v164, v161, 6, 2
	s_and_b32 s19, s2, 0x7fffff8
	s_ashr_i32 s15, s14, 31
	s_and_b32 s2, s6, 0xf80
	v_lshl_or_b32 v168, v164, 5, s2
	s_lshl_b64 s[6:7], s[14:15], 12
	s_mov_b32 s2, 0x3f828f5c
	v_readlane_b32 s24, v254, 53
	v_readlane_b32 s25, v254, 54
	v_ashrrev_i32_e32 v165, 8, v161
	s_waitcnt vmcnt(1)
	v_and_b32_e32 v15, 0x7fffffff, v0
	ds_bpermute_b32 v3, v3, v15
	s_waitcnt vmcnt(0)
	v_and_b32_e32 v16, 0x7fffffff, v2
	ds_bpermute_b32 v4, v4, v16
	v_max_f32_e64 v0, |v0|, |v0|
	v_max_f32_e64 v2, |v2|, |v2|
	s_waitcnt lgkmcnt(1)
	v_max_f32_e32 v3, v3, v3
	v_max_f32_e32 v0, v0, v3
	s_waitcnt lgkmcnt(0)
	v_max_f32_e32 v4, v4, v4
	v_max_f32_e32 v4, v2, v4
	ds_bpermute_b32 v5, v5, v0
	ds_bpermute_b32 v6, v6, v4
	v_mov_b64_e32 v[2:3], s[12:13]
	v_lshlrev_b32_e32 v146, 6, v165
	v_ashrrev_i32_e32 v147, 31, v146
	s_waitcnt lgkmcnt(1)
	v_max_f32_e32 v5, v5, v5
	s_waitcnt lgkmcnt(0)
	v_max_f32_e32 v6, v6, v6
	v_max_f32_e32 v0, v0, v5
	v_max_f32_e32 v4, v4, v6
	ds_bpermute_b32 v5, v7, v0
	ds_bpermute_b32 v6, v8, v4
	v_or_b32_e32 v7, s6, v168
	v_mad_u64_u32 v[2:3], s[24:25], v7, s33, v[2:3]
	s_waitcnt lgkmcnt(1)
	v_max_f32_e32 v5, v5, v5
	s_waitcnt lgkmcnt(0)
	v_max_f32_e32 v6, v6, v6
	v_max_f32_e32 v0, v0, v5
	v_max_f32_e32 v4, v4, v6
	ds_bpermute_b32 v5, v9, v0
	ds_bpermute_b32 v6, v10, v4
	s_or_b32 s16, s19, s81
	s_mov_b64 s[24:25], 0x1000
	s_bfe_i32 s16, s16, 0x1b0000
	s_waitcnt lgkmcnt(1)
	v_max_f32_e32 v5, v5, v5
	s_waitcnt lgkmcnt(0)
	v_max_f32_e32 v6, v6, v6
	v_max_f32_e32 v0, v0, v5
	v_max_f32_e32 v4, v4, v6
	ds_bpermute_b32 v5, v11, v0
	ds_bpermute_b32 v6, v12, v4
	s_waitcnt lgkmcnt(1)
	v_max_f32_e32 v5, v5, v5
	s_waitcnt lgkmcnt(0)
	v_max_f32_e32 v6, v6, v6
	v_max_f32_e32 v0, v0, v5
	v_max_f32_e32 v4, v4, v6
	ds_bpermute_b32 v5, v13, v0
	ds_bpermute_b32 v6, v14, v4
	s_waitcnt lgkmcnt(1)
	v_max_f32_e32 v5, v5, v5
	s_waitcnt lgkmcnt(0)
	v_max_f32_e32 v6, v6, v6
	v_max_f32_e32 v0, v0, v5
	v_max_f32_e32 v4, v4, v6
	v_mul_f32_e32 v0, 0x4138aa65, v0
	v_mul_f32_e32 v0, v0, v4
	v_fma_f32 v0, v0, s2, 1.0
	s_mov_b32 s2, 0x42600000
	v_cmp_ge_f32_e32 vcc, s2, v0
	v_mov_b32_e32 v4, 0x6600
	v_readlane_b32 s2, v255, 41
	v_mad_i32_i24 v3, s7, v4, v3
	s_lshl_b32 s2, s2, 1
	v_lshl_add_u64 v[2:3], v[2:3], 0, s[2:3]
	v_lshl_add_u64 v[2:3], v[146:147], 1, v[2:3]
	v_lshl_add_u64 v[82:83], v[2:3], 0, s[24:25]
	s_mul_i32 s25, s14, 0x6600000
	s_mul_hi_i32 s24, s14, 0x6600000
	s_add_u32 s12, s12, s25
	s_addc_u32 s13, s13, s24
	s_add_u32 s12, s12, s2
	s_addc_u32 s13, s13, 0
	s_add_u32 s12, s12, 0x1800
	s_addc_u32 s13, s13, 0
	s_ashr_i32 s17, s16, 31
	s_lshl_b64 s[14:15], s[16:17], 20
	s_add_u32 s14, s26, s14
	s_addc_u32 s15, s27, s15
	s_mul_hi_i32 s26, s8, 0x7604000
	s_mul_i32 s27, s8, 0x7604000
	s_and_saveexec_b64 s[16:17], vcc
	s_xor_b64 s[16:17], exec, s[16:17]
	s_cbranch_execz .LBB0_567
;     ...
;   float m_run = -1e30f, l_run = 0.f;
;   u32x4 rk[NKL], rv[2];
;   u32 koff[NKL]; int klds[NKL];
; #pragma unroll
;   for (int i = 0; i < NKL; ++i) { int c = tid + NTHR * i; int row = c / KCH, kc = c % KCH; koff[i] = (u32)(row * ldk + 8 * kc) * 2u; klds[i] = row * KST + 8 * kc; }
;   const u32 voff = (u32)((tid >> 3) * 4096 + 8 * (tid & 7)) * 2u;
;   const int vlds = 64 * KST + (tid >> 3) * 72 + 8 * (tid & 7);
;   auto gload = [&](int k0) __attribute__((always_inline)) {
;     const char* kb = (const char*)Kg + (size_t)k0 * ldk * 2;
; #pragma unroll
;     for (int i = 0; i < NKL; ++i) rk[i] = *(const u32x4*)(kb + koff[i]);
;     const char* vb = (const char*)VTg + (size_t)k0 * 2;
; #pragma unroll
;     for (int i = 0; i < 2; ++i) rv[i] = *(const u32x4*)(vb + (size_t)i * 64 * 4096 * 2 + voff);
;   };
;   auto lstore = [&](int b) __attribute__((always_inline)) {
;     u16* St = S0 + b * STG;
; #pragma unroll
;     for (int i = 0; i < NKL; ++i) *(u32x4*)(St + klds[i]) = rk[i];
; #pragma unroll
;     for (int i = 0; i < 2; ++i) *(u32x4*)(St + vlds + i * 64 * 72) = rv[i];
;   };
;   gload(kt0 * 64);
;   __syncthreads();
;   lstore(0);
;   gload((kt0 + 1) * 64);
;   __syncthreads();
	v_mov_b32_e32 v19, v250
	v_xor_b32_e32 v66, 0x80000000, v0
	v_ashrrev_i32_e32 v2, 31, v19
	v_lshrrev_b32_e32 v2, 28, v2
	v_add_u32_e32 v2, v19, v2
	v_ashrrev_i32_e32 v23, 4, v2
	v_and_b32_e32 v2, 0x1ffffff0, v2
	v_sub_u32_e32 v2, v19, v2
	v_mul_lo_u32 v3, v23, s56
	v_lshl_add_u32 v18, v2, 3, v3
	v_add_u32_e32 v2, 0x200, v19
	v_ashrrev_i32_e32 v3, 31, v2
	v_lshrrev_b32_e32 v3, 28, v3
	v_add_u32_e32 v3, v2, v3
	v_ashrrev_i32_e32 v32, 4, v3
	v_and_b32_e32 v3, 0x1ffffff0, v3
	v_sub_u32_e32 v2, v2, v3
	v_mul_lo_u32 v3, v32, s56
	v_lshl_add_u32 v22, v2, 3, v3
	v_ashrrev_i32_e32 v27, 3, v19
	v_lshlrev_b32_e32 v2, 3, v19
	v_and_b32_e32 v33, 31, v19
	v_and_b32_e32 v26, 56, v2
	v_lshlrev_b32_e32 v2, 13, v27
	v_lshrrev_b32_e32 v0, 2, v19
	v_mul_u32_u24_e32 v19, 0x3300, v33
	v_lshl_or_b32 v28, v26, 1, v2
	v_mov_b32_e32 v29, v1
	v_and_b32_e32 v34, 8, v0
	v_lshlrev_b32_e32 v0, 1, v19
	s_movk_i32 s71, 0x48
	v_lshl_add_u64 v[10:11], s[14:15], 0, v[28:29]
	s_mov_b32 s70, 0x80000
	s_add_u32 s74, s12, 0x198000
	v_mad_u64_u32 v[148:149], s[84:85], v27, s71, v[26:27]
	v_lshl_add_u64 v[26:27], v[82:83], 0, v[0:1]
	v_lshlrev_b32_e32 v0, 1, v34
	v_lshlrev_b32_e32 v20, 1, v18
	v_add_co_u32_e32 v30, vcc, s70, v10
	s_addc_u32 s75, s13, 0
	v_lshl_add_u64 v[26:27], v[26:27], 0, v[0:1]
	v_lshlrev_b32_e32 v24, 1, v22
	global_load_dwordx4 v[2:5], v20, s[12:13]
	global_load_dwordx4 v[6:9], v24, s[12:13]
	v_addc_co_u32_e32 v31, vcc, 0, v11, vcc
	global_load_dwordx4 v[10:13], v28, s[14:15]
	global_load_dwordx4 v[14:17], v[30:31], off
	global_load_dwordx4 v[114:117], v[26:27], off
	global_load_dwordx4 v[118:121], v[26:27], off offset:32
	global_load_dwordx4 v[122:125], v[26:27], off offset:64
	global_load_dwordx4 v[126:129], v[26:27], off offset:96
	s_barrier
	global_load_dwordx4 v[130:133], v20, s[74:75]
	global_load_dwordx4 v[134:137], v24, s[74:75]
	global_load_dwordx4 v[138:141], v28, s[14:15] offset:128
	global_load_dwordx4 v[142:145], v[30:31], off offset:128
	v_lshl_add_u32 v19, v148, 1, 64
	s_movk_i32 s71, 0xcd88
	v_mad_u64_u32 v[150:151], s[84:85], v23, s71, v[18:19]
	v_mad_u64_u32 v[152:153], s[84:85], v32, s71, v[22:23]
	v_readlane_b32 s71, v255, 25
	s_or_b32 s71, s71, s19
	s_bfe_i32 s75, s71, 0x1001a
	s_bfe_i32 s74, s71, 0x1b0000
	s_lshl_b64 s[74:75], s[74:75], 20
	s_add_u32 s74, s27, s74
	s_addc_u32 s75, s26, s75
	v_readlane_b32 s71, v255, 44
	v_lshl_add_u64 v[154:155], s[74:75], 0, v[28:29]
	s_add_u32 s71, s71, s25
	v_readlane_b32 s74, v255, 45
	s_addc_u32 s75, s74, s24
	v_lshl_add_u32 v18, v150, 1, 64
	s_add_u32 s74, s71, s10
	v_mov_b32_e32 v21, v1
	v_mov_b32_e32 v25, v1
	v_lshl_add_u32 v22, v152, 1, 64
	s_addc_u32 s75, s75, s11
	v_mov_b32_e32 v147, 0
	s_mov_b32 s70, 0
	v_mov_b32_e32 v67, v66
	v_mov_b32_e32 v68, v66
	v_mov_b32_e32 v69, v66
	v_mov_b32_e32 v70, v66
	v_mov_b32_e32 v71, v66
	v_mov_b32_e32 v72, v66
	v_mov_b32_e32 v73, v66
	v_mov_b32_e32 v74, v66
	v_mov_b32_e32 v75, v66
	v_mov_b32_e32 v76, v66
	v_mov_b32_e32 v77, v66
	v_mov_b32_e32 v78, v66
	v_mov_b32_e32 v79, v66
	v_mov_b32_e32 v80, v66
	v_mov_b32_e32 v81, v66
	v_mul_u32_u24_e32 v149, 0x110, v33
	v_lshl_add_u64 v[156:157], s[74:75], 0, v[20:21]
	s_waitcnt vmcnt(11)
	ds_write_b128 v18, v[2:5]
	s_waitcnt vmcnt(10)
	ds_write_b128 v22, v[6:9]
	s_waitcnt vmcnt(9)
	ds_write_b128 v19, v[10:13] offset:17408
	s_waitcnt vmcnt(8)
	ds_write_b128 v19, v[14:17] offset:26624
	v_mul_u32_u24_e32 v2, 0x48, v33
	v_lshl_add_u64 v[158:159], s[74:75], 0, v[24:25]
	v_lshlrev_b32_e32 v151, 1, v2
	v_mov_b32_e32 v18, 0
	v_mov_b32_e32 v19, v147
	v_mov_b32_e32 v20, v147
	v_mov_b32_e32 v21, v147
	v_mov_b32_e32 v22, v147
	v_mov_b32_e32 v23, v147
	v_mov_b32_e32 v24, v147
	v_mov_b32_e32 v25, v147
	v_mov_b32_e32 v26, v147
	v_mov_b32_e32 v27, v147
	v_mov_b32_e32 v28, v147
	v_mov_b32_e32 v29, v147
	v_mov_b32_e32 v30, v147
	v_mov_b32_e32 v31, v147
	v_mov_b32_e32 v32, v147
	v_mov_b32_e32 v33, v147
	v_mov_b32_e32 v34, 0
	v_mov_b32_e32 v35, v147
	v_mov_b32_e32 v36, v147
	v_mov_b32_e32 v37, v147
	v_mov_b32_e32 v38, v147
	v_mov_b32_e32 v39, v147
	v_mov_b32_e32 v40, v147
	v_mov_b32_e32 v41, v147
	v_mov_b32_e32 v42, v147
	v_mov_b32_e32 v43, v147
	v_mov_b32_e32 v44, v147
	v_mov_b32_e32 v45, v147
	v_mov_b32_e32 v46, v147
	v_mov_b32_e32 v47, v147
	v_mov_b32_e32 v48, v147
	v_mov_b32_e32 v49, v147
	v_mov_b32_e32 v50, 0
	v_mov_b32_e32 v51, v147
	v_mov_b32_e32 v52, v147
	v_mov_b32_e32 v53, v147
	v_mov_b32_e32 v54, v147
	v_mov_b32_e32 v55, v147
	v_mov_b32_e32 v56, v147
	v_mov_b32_e32 v57, v147
	v_mov_b32_e32 v58, v147
	v_mov_b32_e32 v59, v147
	v_mov_b32_e32 v60, v147
	v_mov_b32_e32 v61, v147
	v_mov_b32_e32 v62, v147
	v_mov_b32_e32 v63, v147
	v_mov_b32_e32 v64, v147
	v_mov_b32_e32 v65, v147
	v_mov_b32_e32 v2, 0
	v_mov_b32_e32 v3, v147
	v_mov_b32_e32 v4, v147
	v_mov_b32_e32 v5, v147
	v_mov_b32_e32 v6, v147
	v_mov_b32_e32 v7, v147
	v_mov_b32_e32 v8, v147
	v_mov_b32_e32 v9, v147
	v_mov_b32_e32 v10, v147
	v_mov_b32_e32 v11, v147
	v_mov_b32_e32 v12, v147
	v_mov_b32_e32 v13, v147
	v_mov_b32_e32 v14, v147
	v_mov_b32_e32 v15, v147
	v_mov_b32_e32 v16, v147
	v_mov_b32_e32 v17, v147
	s_waitcnt lgkmcnt(0)
	s_barrier
	v_mov_b32_e32 v170, 0
	v_mov_b32_e32 v171, 0
	v_mov_b32_e32 v172, 0
	v_mov_b32_e32 v173, 0
	v_mov_b32_e32 v174, 0
	v_mov_b32_e32 v175, 0
	v_mov_b32_e32 v176, 0
	v_mov_b32_e32 v177, 0
	v_mov_b32_e32 v178, 0
	v_mov_b32_e32 v179, 0
	v_mov_b32_e32 v180, 0
	v_mov_b32_e32 v181, 0
	v_mov_b32_e32 v182, 0
	v_mov_b32_e32 v183, 0
	v_mov_b32_e32 v184, 0
	v_mov_b32_e32 v185, 0
	v_mov_b32_e32 v246, 0
	v_mov_b32_e32 v247, 0
	v_mov_b32_e32 v248, 0
	v_mov_b32_e32 v249, 0
	v_mov_b32_e32 v82, 0
	v_mov_b32_e32 v83, 0
	v_mov_b32_e32 v84, 0
	v_mov_b32_e32 v85, 0
	v_mov_b32_e32 v86, 0
	v_mov_b32_e32 v87, 0
	v_mov_b32_e32 v88, 0
	v_mov_b32_e32 v89, 0
	v_mov_b32_e32 v90, 0
	v_mov_b32_e32 v91, 0
	v_mov_b32_e32 v92, 0
	v_mov_b32_e32 v93, 0
	v_mov_b32_e32 v94, 0
	v_mov_b32_e32 v95, 0
	v_mov_b32_e32 v96, 0
	v_mov_b32_e32 v97, 0
; #define MFMA32(a, b, c) __builtin_amdgcn_mfma_f32_32x32x16_bf16((a), (b), (c), 0, 0, 0)
; DI u32 pack2(float a, float b) { f2_t v = {a, b}; bf2_t r = __builtin_convertvector(v, bf2_t); return __builtin_bit_cast(u32, r); }
;     ...
;       bf16x8 kf[2][4];
; #pragma unroll
;       for (int i = 0; i < 4; ++i) kf[0][i] = *(const bf16x8*)(Ks + r * KST + kcol_off + 16 * i + 8 * h);
; #pragma unroll
;       for (int g = 0; g < NBAT; ++g) {
;         if (g + 1 < NBAT) {
;           const int t2n = (g + 1) / BPT, bn = (g + 1) % BPT;
; #pragma unroll
;           for (int i = 0; i < 4; ++i) kf[(g + 1) & 1][i] = *(const bf16x8*)(Ks + (32 * t2n + r) * KST + kcol_off + 16 * (4 * bn + i) + 8 * h);
;         }
;         __builtin_amdgcn_sched_barrier(0);
;         const int t2 = g / BPT, b = g % BPT;
; #pragma unroll
;         for (int i = 0; i < 4; ++i) st[t2] = MFMA32(kf[g & 1][i], qf[4 * b + i], st[t2]);
;         __builtin_amdgcn_sched_barrier(0);
;       }
;     ...
;     for (int c = 0; c < 4; ++c) {
;       const int t2 = c >> 1, s2 = c & 1;
;       if (c + 1 < 4) {
; #pragma unroll
;         for (int dt = 0; dt < 4; ++dt) vf[(c + 1) & 1][dt] = *(const bf16x8*)(Vs + (32 * dt + r) * 72 + 16 * (c + 1) + 8 * h);
;       }
;       u32x4 pk;
;       pk.x = pack2(st[t2][8 * s2], st[t2][8 * s2 + 1]); pk.y = pack2(st[t2][8 * s2 + 2], st[t2][8 * s2 + 3]);
;       pk.z = pack2(st[t2][8 * s2 + 4], st[t2][8 * s2 + 5]); pk.w = pack2(st[t2][8 * s2 + 6], st[t2][8 * s2 + 7]);
;       bf16x8 pf = __builtin_bit_cast(bf16x8, pk);
;       __builtin_amdgcn_sched_barrier(0);
; #pragma unroll
;       for (int dt = 0; dt < 4; ++dt) o[dt] = MFMA32(vf[c & 1][dt], pf, o[dt]);
;       __builtin_amdgcn_sched_barrier(0);
;     }
.LBB0_560:
	s_bitcmp1_b32 s70, 0
	s_cselect_b32 s71, 0x8c00, 0
	s_add_i32 s71, s71, 64
	v_add_u32_e32 v160, s71, v149
	v_lshlrev_b32_e32 v166, 1, v146
	v_add3_u32 v160, v160, v166, v0
	v_add3_u32 v153, s71, v0, v151
	ds_read_b128 v[186:189], v160
	ds_read_b128 v[190:193], v160 offset:32
	ds_read_b128 v[194:197], v160 offset:64
	ds_read_b128 v[198:201], v160 offset:96
	s_add_i32 s71, s70, 1
	s_bitcmp1_b32 s71, 0
	s_cselect_b32 s74, 0x8c00, 0
	s_add_i32 s74, s74, 64
	v_mfma_f32_32x32x16_bf16 v[2:17], v[170:173], v[246:249], v[2:17]
	ds_read_b128 v[170:173], v160 offset:8704
	v_lshl_add_u32 v202, v150, 1, s74
	v_lshl_add_u32 v203, v152, 1, s74
	v_lshl_add_u32 v204, v148, 1, s74
	v_add_f32_e32 v166, v82, v83
	v_mfma_f32_32x32x16_bf16 v[50:65], v[174:177], v[246:249], v[50:65]
	ds_read_b128 v[174:177], v160 offset:8736
	s_waitcnt vmcnt(0)
	v_add_f32_e32 v166, v84, v166
	v_add_f32_e32 v166, v85, v166
	v_add_f32_e32 v166, v86, v166
	v_add_f32_e32 v166, v87, v166
	s_waitcnt lgkmcnt(5)
	v_mfma_f32_32x32x16_bf16 v[98:113], v[186:189], v[114:117], v[66:81]
	ds_read_b128 v[186:189], v153 offset:17408
	ds_write_b128 v202, v[130:133]
	ds_write_b128 v203, v[134:137]
	v_add_f32_e32 v166, v88, v166
	v_add_f32_e32 v166, v89, v166
	s_waitcnt lgkmcnt(7)
	v_mfma_f32_32x32x16_bf16 v[98:113], v[190:193], v[118:121], v[98:113]
	ds_read_b128 v[190:193], v153 offset:22016
	ds_write_b128 v204, v[138:141] offset:17408
	ds_write_b128 v204, v[142:145] offset:26624
	v_add_f32_e32 v166, v90, v166
	v_add_f32_e32 v166, v91, v166
	s_waitcnt lgkmcnt(9)
	v_mfma_f32_32x32x16_bf16 v[98:113], v[194:197], v[122:125], v[98:113]
	ds_read_b128 v[194:197], v153 offset:26624
	s_cmp_gt_u32 s70, 61
	s_cbranch_scc1 .Ldiff_skip_ga
	v_lshl_add_u64 v[138:139], s[62:63], 0, v[154:155]
	v_add_co_u32_e32 v140, vcc, 0x7046000, v138
	v_lshl_add_u64 v[130:131], s[62:63], 0, v[156:157]
	s_nop 0
	v_addc_co_u32_e32 v141, vcc, 0, v139, vcc
	v_add_co_u32_e32 v142, vcc, 0x70c6000, v138
	v_lshl_add_u64 v[134:135], s[62:63], 0, v[158:159]
	s_nop 0
	v_addc_co_u32_e32 v143, vcc, 0, v139, vcc
.Ldiff_skip_ga:
	s_waitcnt lgkmcnt(9)
	v_mfma_f32_32x32x16_bf16 v[98:113], v[198:201], v[126:129], v[98:113]
	ds_read_b128 v[198:201], v153 offset:31232
	s_cmp_gt_u32 s70, 61
	s_cbranch_scc1 .Ldiff_skip_gb
	global_load_dwordx4 v[130:133], v[130:131], off
	s_nop 0
	global_load_dwordx4 v[134:137], v[134:135], off
	s_nop 0
	global_load_dwordx4 v[138:141], v[140:141], off offset:512
	s_nop 0
	global_load_dwordx4 v[142:145], v[142:143], off offset:512
; #define MFMA32(a, b, c) __builtin_amdgcn_mfma_f32_32x32x16_bf16((a), (b), (c), 0, 0, 0)
; DI u32 pack2(float a, float b) { f2_t v = {a, b}; bf2_t r = __builtin_convertvector(v, bf2_t); return __builtin_bit_cast(u32, r); }
;     ...
;     } else if (MODE == 1) {
;       float ls = 0.f;
; #pragma unroll
;       for (int t2 = 0; t2 < 2; ++t2)
; #pragma unroll
;         for (int e = 0; e < 16; ++e) { float p = __builtin_amdgcn_exp2f(st[t2][e]); st[t2][e] = p; ls += p; }
;       l_run += ls;
;     ...
; #pragma unroll
;     for (int c = 0; c < 4; ++c) {
;       const int t2 = c >> 1, s2 = c & 1;
;       if (c + 1 < 4) {
; #pragma unroll
;         for (int dt = 0; dt < 4; ++dt) vf[(c + 1) & 1][dt] = *(const bf16x8*)(Vs + (32 * dt + r) * 72 + 16 * (c + 1) + 8 * h);
;       }
;       u32x4 pk;
;       pk.x = pack2(st[t2][8 * s2], st[t2][8 * s2 + 1]); pk.y = pack2(st[t2][8 * s2 + 2], st[t2][8 * s2 + 3]);
;       pk.z = pack2(st[t2][8 * s2 + 4], st[t2][8 * s2 + 5]); pk.w = pack2(st[t2][8 * s2 + 6], st[t2][8 * s2 + 7]);
;       bf16x8 pf = __builtin_bit_cast(bf16x8, pk);
;       __builtin_amdgcn_sched_barrier(0);
; #pragma unroll
;       for (int dt = 0; dt < 4; ++dt) o[dt] = MFMA32(vf[c & 1][dt], pf, o[dt]);
;       __builtin_amdgcn_sched_barrier(0);
;     }
;     if (kt + 1 < nkt) lstore((kt + 1) & 1);
;     if (kt + 2 < nkt) gload((kt0 + kt + 2) * 64);
;     __syncthreads();
;   }
.Ldiff_skip_gb:
	v_mfma_f32_32x32x16_bf16 v[34:49], v[178:181], v[246:249], v[34:49]
	ds_read_b128 v[178:181], v160 offset:8768
	v_lshl_add_u64 v[154:155], v[154:155], 0, s[30:31]
	v_lshl_add_u64 v[156:157], v[156:157], 0, s[90:91]
	v_lshl_add_u64 v[158:159], v[158:159], 0, s[90:91]
	v_add_f32_e32 v166, v92, v166
	v_add_f32_e32 v166, v93, v166
	v_mfma_f32_32x32x16_bf16 v[18:33], v[182:185], v[246:249], v[18:33]
	ds_read_b128 v[182:185], v160 offset:8800
	v_add_f32_e32 v166, v94, v166
	v_add_f32_e32 v166, v95, v166
	v_add_f32_e32 v166, v96, v166
	v_add_f32_e32 v166, v97, v166
	v_add_f32_e32 v147, v147, v166
	s_waitcnt lgkmcnt(11)
	v_mfma_f32_32x32x16_bf16 v[82:97], v[170:173], v[114:117], v[66:81]
	v_exp_f32_e32 v98, v98
	v_exp_f32_e32 v99, v99
	v_exp_f32_e32 v100, v100
	s_waitcnt lgkmcnt(10)
	v_mfma_f32_32x32x16_bf16 v[82:97], v[174:177], v[118:121], v[82:97]
	ds_read_b128 v[170:173], v153 offset:17440
	v_exp_f32_e32 v101, v101
	v_exp_f32_e32 v102, v102
	v_exp_f32_e32 v103, v103
	s_waitcnt lgkmcnt(2)
	v_mfma_f32_32x32x16_bf16 v[82:97], v[178:181], v[122:125], v[82:97]
	ds_read_b128 v[174:177], v153 offset:22048
	v_exp_f32_e32 v104, v104
	v_exp_f32_e32 v105, v105
	v_cvt_pk_bf16_f32 v202, v98, v99
	v_cvt_pk_bf16_f32 v203, v100, v101
	v_cvt_pk_bf16_f32 v204, v102, v103
	v_cvt_pk_bf16_f32 v205, v104, v105
	s_waitcnt lgkmcnt(2)
	v_mfma_f32_32x32x16_bf16 v[82:97], v[182:185], v[126:129], v[82:97]
	ds_read_b128 v[178:181], v153 offset:26656
	v_exp_f32_e32 v106, v106
	v_exp_f32_e32 v107, v107
	v_exp_f32_e32 v108, v108
	v_mfma_f32_32x32x16_bf16 v[2:17], v[186:189], v[202:205], v[2:17]
	ds_read_b128 v[182:185], v153 offset:31264
	ds_read_b128 v[186:189], v153 offset:17472
	v_exp_f32_e32 v109, v109
	v_exp_f32_e32 v110, v110
	v_exp_f32_e32 v111, v111
	v_mfma_f32_32x32x16_bf16 v[50:65], v[190:193], v[202:205], v[50:65]
	ds_read_b128 v[190:193], v153 offset:22080
	v_exp_f32_e32 v112, v112
	v_exp_f32_e32 v113, v113
	v_add_f32_e32 v160, v98, v99
	v_add_f32_e32 v160, v100, v160
	v_mfma_f32_32x32x16_bf16 v[34:49], v[194:197], v[202:205], v[34:49]
	ds_read_b128 v[194:197], v153 offset:26688
	v_cvt_pk_bf16_f32 v246, v106, v107
	v_cvt_pk_bf16_f32 v247, v108, v109
	v_cvt_pk_bf16_f32 v248, v110, v111
	v_cvt_pk_bf16_f32 v249, v112, v113
	v_add_f32_e32 v160, v101, v160
	v_add_f32_e32 v160, v102, v160
	v_mfma_f32_32x32x16_bf16 v[18:33], v[198:201], v[202:205], v[18:33]
	ds_read_b128 v[198:201], v153 offset:31296
	v_exp_f32_e32 v82, v82
	v_exp_f32_e32 v83, v83
	v_exp_f32_e32 v84, v84
	s_waitcnt lgkmcnt(7)
	v_mfma_f32_32x32x16_bf16 v[2:17], v[170:173], v[246:249], v[2:17]
	ds_read_b128 v[170:173], v153 offset:17504
	v_exp_f32_e32 v85, v85
	v_exp_f32_e32 v86, v86
	v_exp_f32_e32 v87, v87
	s_waitcnt lgkmcnt(7)
	v_mfma_f32_32x32x16_bf16 v[50:65], v[174:177], v[246:249], v[50:65]
	ds_read_b128 v[174:177], v153 offset:22112
	v_exp_f32_e32 v88, v88
	v_exp_f32_e32 v89, v89
	v_cvt_pk_bf16_f32 v202, v82, v83
	v_add_f32_e32 v160, v103, v160
	s_waitcnt lgkmcnt(7)
	v_mfma_f32_32x32x16_bf16 v[34:49], v[178:181], v[246:249], v[34:49]
	ds_read_b128 v[178:181], v153 offset:26720
	v_cvt_pk_bf16_f32 v203, v84, v85
	v_cvt_pk_bf16_f32 v204, v86, v87
	v_cvt_pk_bf16_f32 v205, v88, v89
	v_exp_f32_e32 v90, v90
	v_add_f32_e32 v160, v104, v160
	s_waitcnt lgkmcnt(7)
	v_mfma_f32_32x32x16_bf16 v[18:33], v[182:185], v[246:249], v[18:33]
	ds_read_b128 v[182:185], v153 offset:31328
	v_exp_f32_e32 v91, v91
	v_exp_f32_e32 v92, v92
	v_exp_f32_e32 v93, v93
	s_waitcnt lgkmcnt(7)
	v_mfma_f32_32x32x16_bf16 v[2:17], v[186:189], v[202:205], v[2:17]
	v_exp_f32_e32 v94, v94
	v_exp_f32_e32 v95, v95
	v_exp_f32_e32 v96, v96
	s_waitcnt lgkmcnt(6)
	v_mfma_f32_32x32x16_bf16 v[50:65], v[190:193], v[202:205], v[50:65]
	v_exp_f32_e32 v97, v97
	v_add_f32_e32 v160, v105, v160
	v_add_f32_e32 v160, v106, v160
	v_add_f32_e32 v160, v107, v160
	v_add_f32_e32 v160, v108, v160
	v_add_f32_e32 v160, v109, v160
	s_waitcnt lgkmcnt(5)
	v_mfma_f32_32x32x16_bf16 v[34:49], v[194:197], v[202:205], v[34:49]
	v_cvt_pk_bf16_f32 v246, v90, v91
	v_cvt_pk_bf16_f32 v247, v92, v93
	v_cvt_pk_bf16_f32 v248, v94, v95
	v_cvt_pk_bf16_f32 v249, v96, v97
	v_add_f32_e32 v160, v110, v160
	v_add_f32_e32 v160, v111, v160
	s_waitcnt lgkmcnt(4)
	v_mfma_f32_32x32x16_bf16 v[18:33], v[198:201], v[202:205], v[18:33]
	v_add_f32_e32 v160, v112, v160
	v_add_f32_e32 v160, v113, v160
	v_add_f32_e32 v147, v147, v160
	s_cmp_lg_u32 s71, 64
	s_waitcnt lgkmcnt(0)
	s_barrier
	s_cbranch_scc0 .Ldiff_tail
	s_mov_b32 s70, s71
	s_branch .LBB0_560
.Ldiff_tail:
	v_mfma_f32_32x32x16_bf16 v[2:17], v[170:173], v[246:249], v[2:17]
	v_mfma_f32_32x32x16_bf16 v[50:65], v[174:177], v[246:249], v[50:65]
	v_mfma_f32_32x32x16_bf16 v[34:49], v[178:181], v[246:249], v[34:49]
	v_mfma_f32_32x32x16_bf16 v[18:33], v[182:185], v[246:249], v[18:33]
	v_add_f32_e32 v166, v82, v83
	v_add_f32_e32 v166, v84, v166
	v_add_f32_e32 v166, v85, v166
	v_add_f32_e32 v166, v86, v166
	v_add_f32_e32 v166, v87, v166
	v_add_f32_e32 v166, v88, v166
	v_add_f32_e32 v166, v89, v166
	v_add_f32_e32 v166, v90, v166
	v_add_f32_e32 v166, v91, v166
	v_add_f32_e32 v166, v92, v166
	v_add_f32_e32 v166, v93, v166
	v_add_f32_e32 v166, v94, v166
	v_add_f32_e32 v166, v95, v166
	v_add_f32_e32 v166, v96, v166
	v_add_f32_e32 v166, v97, v166
	v_add_f32_e32 v147, v147, v166
	s_branch .LBB0_566

; DI float shx(float v, int k) { return __int_as_float(__builtin_amdgcn_ds_bpermute((lane_id_l() ^ k) << 2, __float_as_int(v))); }
; DI void mla_attn_item(const WsPtrs& W, const float* pgq, const float* pgk, int item, unsigned char* smem) {
;     ...
;   for (int i = lane; i < 192; i += 64) { gq = fmaxf(gq, fabsf(pgq[i])); gk = fmaxf(gk, fabsf(pgk[i])); }
; #pragma unroll
;   for (int of = 32; of > 0; of >>= 1) { gq = fmaxf(gq, shx(gq, of)); gk = fmaxf(gk, shx(gk, of)); }
;   const float M = 19.99f * gq * gk * 1.02f + 1.f;
;   bf16x8 qn[12];
;   {
;     const u16* Qr = W.QC + (tokb + q0 + r) * 1536 + hh * 192 + 8 * h;
;     u32x4 raw[12];
; #pragma unroll
;     for (int ks = 0; ks < 12; ++ks) raw[ks] = *(const u32x4*)(Qr + 16 * ks);
.LBB0_587:
	global_load_dword v11, v[2:3], off
	v_max_f32_e32 v0, v0, v0
	v_add_u32_e32 v10, 64, v10
	s_movk_i32 s2, 0x7f
	v_max_f32_e32 v8, v8, v8
	v_cmp_lt_u32_e32 vcc, s2, v10
	v_lshl_add_u64 v[2:3], v[2:3], 0, s[76:77]
	s_or_b64 s[6:7], vcc, s[6:7]
	s_waitcnt vmcnt(0)
	v_max_f32_e64 v11, |v11|, |v11|
	v_max_f32_e32 v0, v0, v11
	global_load_dword v11, v[4:5], off
	v_lshl_add_u64 v[4:5], v[4:5], 0, s[76:77]
	s_waitcnt vmcnt(0)
	v_max_f32_e64 v11, |v11|, |v11|
	v_max_f32_e32 v8, v8, v11
	s_andn2_b64 exec, exec, s[6:7]
	s_cbranch_execnz .LBB0_587
	s_or_b64 exec, exec, s[6:7]
	v_readlane_b32 s2, v254, 28
	s_ashr_i32 s5, s4, 31
	s_sub_i32 s16, s18, s2
	s_lshl_b64 s[6:7], s[4:5], 23
	s_lshl_b64 s[8:9], s[4:5], 25
	s_mul_i32 s5, s4, 0x6604000
	s_mul_hi_i32 s2, s4, 0x6604000
	s_add_u32 s5, s8, s5
	s_addc_u32 s2, s9, s2
	s_add_u32 s5, s5, 0x7046100
	s_addc_u32 s14, s2, 0
	s_add_u32 s6, s5, s6
	s_addc_u32 s7, s14, s7
	s_add_u32 s8, s62, s6
	v_mov_b32_e32 v3, v229
	s_mul_i32 s10, s4, 0xc00000
	s_addc_u32 s9, s63, s7
	v_mov_b32_e32 v4, v229
	s_mul_hi_i32 s2, s4, 0xc00000
	s_add_u32 s11, s8, s10
	v_lshlrev_b32_e32 v3, 2, v3
	s_addc_u32 s12, s9, s2
	s_lshr_b32 s6, s16, 1
	v_xor_b32_e32 v3, 0x80, v3
	v_lshlrev_b32_e32 v4, 2, v4
	s_and_b32 s13, s6, 0xffffff8
	ds_bpermute_b32 v3, v3, v0
	v_xor_b32_e32 v4, 0x80, v4
	s_or_b32 s15, s13, s81
	s_bfe_i32 s6, s16, 0x190004
	ds_bpermute_b32 v4, v4, v8
	s_add_u32 s5, s62, s5
	v_ashrrev_i32_e32 v2, 1, v9
	s_addc_u32 s14, s63, s14
	s_lshl_b32 s16, s16, 8
	v_and_b32_e32 v2, 0xffffffe0, v2
	s_and_b32 s16, s16, 0xf00
	v_add_u32_e32 v10, s16, v2
	s_waitcnt lgkmcnt(1)
	v_max_f32_e32 v2, v3, v3
	v_max_f32_e32 v0, v0, v0
	v_max_f32_e32 v9, v0, v2
	s_waitcnt lgkmcnt(0)
	v_max_f32_e32 v0, v4, v4
	v_max_f32_e32 v2, v8, v8
	v_max_f32_e32 v8, v2, v0
	v_mov_b32_e32 v0, v229
	s_ashr_i32 s7, s6, 31
	v_lshlrev_b32_e32 v0, 2, v0
	v_xor_b32_e32 v0, 64, v0
	s_lshl_b64 s[16:17], s[6:7], 12
	v_ashrrev_i32_e32 v11, 31, v10
	ds_bpermute_b32 v12, v0, v9
	v_mov_b32_e32 v0, v229
	v_and_b32_e32 v22, 31, v7
	v_lshl_add_u64 v[182:183], s[16:17], 0, v[10:11]
	v_or_b32_e32 v182, v182, v22
	v_mov_b64_e32 v[2:3], s[8:9]
	s_movk_i32 s7, 0xc00
	v_readlane_b32 s20, v255, 23
	v_lshlrev_b32_e32 v0, 2, v0
	v_mad_u64_u32 v[2:3], s[8:9], v182, s7, v[2:3]
	v_readlane_b32 s21, v255, 24
	v_lshrrev_b32_e32 v223, 5, v6
	v_xor_b32_e32 v0, 64, v0
	v_mad_i32_i24 v3, v183, s7, v3
	s_mov_b32 s21, s3
	ds_bpermute_b32 v13, v0, v8
	v_lshl_add_u64 v[2:3], v[2:3], 0, s[20:21]
	v_lshlrev_b32_e32 v0, 4, v223
	v_readlane_b32 s8, v253, 54
	v_mov_b32_e32 v14, v229
	v_mov_b32_e32 v15, v229
	v_mov_b32_e32 v16, v229
	v_mov_b32_e32 v17, v229
	v_mov_b32_e32 v18, v229
	v_mov_b32_e32 v19, v229
	v_mov_b32_e32 v20, v229
	v_mov_b32_e32 v21, v229
	v_lshl_add_u64 v[2:3], v[2:3], 0, v[0:1]
	v_mov_b32_e32 v11, v229
	v_and_b32_e32 v154, 32, v6
	v_readlane_b32 s9, v253, 55
	global_load_dwordx4 v[98:101], v[2:3], off
	global_load_dwordx4 v[106:109], v[2:3], off offset:32
	global_load_dwordx4 v[110:113], v[2:3], off offset:64
	global_load_dwordx4 v[114:117], v[2:3], off offset:96
	global_load_dwordx4 v[118:121], v[2:3], off offset:128
	global_load_dwordx4 v[122:125], v[2:3], off offset:160
	global_load_dwordx4 v[126:129], v[2:3], off offset:192
	global_load_dwordx4 v[130:133], v[2:3], off offset:224
	global_load_dwordx4 v[138:141], v[2:3], off offset:256
	global_load_dwordx4 v[146:149], v[2:3], off offset:288
	global_load_dwordx4 v[134:137], v[2:3], off offset:320
	global_load_dwordx4 v[142:145], v[2:3], off offset:352
	global_load_dwordx4 v[2:5], v154, s[8:9] offset:32
	s_waitcnt lgkmcnt(0)
	v_max_f32_e32 v6, v13, v13
	v_max_f32_e32 v0, v12, v12
	v_max_f32_e32 v12, v8, v6
	v_lshlrev_b32_e32 v6, 2, v14
	v_max_f32_e32 v0, v9, v0
	v_xor_b32_e32 v6, 32, v6
	ds_bpermute_b32 v13, v6, v0
	v_lshlrev_b32_e32 v6, 2, v15
	v_xor_b32_e32 v6, 32, v6
	ds_bpermute_b32 v14, v6, v12
	global_load_dwordx4 v[6:9], v154, s[8:9] offset:48
	global_load_dwordx4 v[168:171], v154, s[8:9] offset:96
	global_load_dwordx4 v[102:105], v154, s[8:9] offset:112
	s_waitcnt lgkmcnt(1)
	v_max_f32_e32 v13, v13, v13
	v_max_f32_e32 v0, v0, v13
	s_waitcnt lgkmcnt(0)
	v_max_f32_e32 v13, v14, v14
	v_or_b32_e32 v10, v10, v22
	v_max_f32_e32 v12, v12, v13
	v_lshlrev_b32_e32 v13, 2, v16
	v_cvt_f32_i32_e32 v224, v10
	v_xor_b32_e32 v13, 16, v13
	v_lshlrev_b32_e32 v14, 2, v17
	ds_bpermute_b32 v13, v13, v0
	v_xor_b32_e32 v14, 16, v14
	ds_bpermute_b32 v14, v14, v12
	v_lshlrev_b32_e32 v11, 2, v11
	v_xor_b32_e32 v155, 0x80, v11
	s_waitcnt lgkmcnt(1)
	v_max_f32_e32 v13, v13, v13
	v_max_f32_e32 v0, v0, v13
	s_waitcnt lgkmcnt(0)
	v_max_f32_e32 v13, v14, v14
	v_max_f32_e32 v12, v12, v13
	v_lshlrev_b32_e32 v13, 2, v18
	v_xor_b32_e32 v13, 8, v13
	v_lshlrev_b32_e32 v14, 2, v19
	ds_bpermute_b32 v13, v13, v0
	v_xor_b32_e32 v14, 8, v14
	ds_bpermute_b32 v14, v14, v12
	global_load_dwordx4 v[90:93], v154, s[52:53] offset:16
	global_load_dwordx4 v[94:97], v154, s[52:53]
	global_load_dwordx4 v[82:85], v154, s[52:53] offset:80
	global_load_dwordx4 v[86:89], v154, s[52:53] offset:64
	global_load_dwordx4 v[74:77], v154, s[52:53] offset:144
	global_load_dwordx4 v[78:81], v154, s[52:53] offset:128
	global_load_dwordx4 v[66:69], v154, s[52:53] offset:208
	global_load_dwordx4 v[70:73], v154, s[52:53] offset:192
	global_load_dwordx4 v[58:61], v154, s[52:53] offset:272
	global_load_dwordx4 v[62:65], v154, s[52:53] offset:256
	global_load_dwordx4 v[50:53], v154, s[52:53] offset:336
	global_load_dwordx4 v[54:57], v154, s[52:53] offset:320
	global_load_dwordx4 v[42:45], v154, s[52:53] offset:400
	global_load_dwordx4 v[46:49], v154, s[52:53] offset:384
	global_load_dwordx4 v[34:37], v154, s[52:53] offset:464
	global_load_dwordx4 v[38:41], v154, s[52:53] offset:448
	s_mov_b32 s7, 0x800000
	s_waitcnt lgkmcnt(1)
; DI u32 pack2(float a, float b) { f2_t v = {a, b}; bf2_t r = __builtin_convertvector(v, bf2_t); return __builtin_bit_cast(u32, r); }
; DI float bflo(u32 v) { return __uint_as_float(v << 16); }
; DI void mla_attn_item(const WsPtrs& W, const float* pgq, const float* pgk, int item, unsigned char* smem) {
;     ...
;   for (int of = 32; of > 0; of >>= 1) { gq = fmaxf(gq, shx(gq, of)); gk = fmaxf(gk, shx(gk, of)); }
;   const float M = 19.99f * gq * gk * 1.02f + 1.f;
;   bf16x8 qn[12];
;   {
;     const u16* Qr = W.QC + (tokb + q0 + r) * 1536 + hh * 192 + 8 * h;
;     u32x4 raw[12];
; #pragma unroll
;     for (int ks = 0; ks < 12; ++ks) raw[ks] = *(const u32x4*)(Qr + 16 * ks);
;     float ss = 0.f;
; #pragma unroll
;     for (int ks = 0; ks < 12; ++ks) {
;       float a;
;       a = bflo(raw[ks].x); ss += a * a; a = bfhi(raw[ks].x); ss += a * a; a = bflo(raw[ks].y); ss += a * a; a = bfhi(raw[ks].y); ss += a * a;
;       a = bflo(raw[ks].z); ss += a * a; a = bfhi(raw[ks].z); ss += a * a; a = bflo(raw[ks].w); ss += a * a; a = bfhi(raw[ks].w); ss += a * a;
;     }
;     ss += shx(ss, 32);
;     const float sc = rsqrtf(ss * (1.f / 192.f) + EPSV) * (0.07216878364870322f * LOG2E);
;     const float pos = (float)(q0 + r);
;     auto scaled = [&](int ks, float (&v)[8]) __attribute__((always_inline)) {
;       const f32x4 g0 = *(const f32x4*)(pgq + 16 * ks + 8 * h), g1 = *(const f32x4*)(pgq + 16 * ks + 8 * h + 4);
;       v[0] = bflo(raw[ks].x) * sc * g0.x; v[1] = bfhi(raw[ks].x) * sc * g0.y; v[2] = bflo(raw[ks].y) * sc * g0.z; v[3] = bfhi(raw[ks].y) * sc * g0.w;
;       v[4] = bflo(raw[ks].z) * sc * g1.x; v[5] = bfhi(raw[ks].z) * sc * g1.y; v[6] = bflo(raw[ks].w) * sc * g1.z; v[7] = bfhi(raw[ks].w) * sc * g1.w;
;     };
;     auto packed = [&](const float (&v)[8]) __attribute__((always_inline)) {
;       u32x4 p; p.x = pack2(v[0], v[1]); p.y = pack2(v[2], v[3]); p.z = pack2(v[4], v[5]); p.w = pack2(v[6], v[7]);
;       return __builtin_bit_cast(bf16x8, p);
;     };
; #pragma unroll
;     for (int ks = 0; ks < 8; ++ks) { float v[8]; scaled(ks, v); qn[ks] = packed(v); }
; #pragma unroll
;     for (int ks = 8; ks < 10; ++ks) {
;       float x1[8], x2[8]; scaled(ks, x1); scaled(ks + 2, x2);
; #pragma unroll
;       for (int i = 0; i < 8; ++i) {
;         float c, sn; rot_cs(pos, W.rope[8 + 16 * (ks - 8) + 8 * h + i], c, sn);
	v_max_f32_e32 v13, v13, v13
	v_max_f32_e32 v0, v0, v13
	s_waitcnt lgkmcnt(0)
	v_max_f32_e32 v13, v14, v14
	v_max_f32_e32 v12, v12, v13
	v_lshlrev_b32_e32 v13, 2, v20
	v_xor_b32_e32 v13, 4, v13
	v_lshlrev_b32_e32 v14, 2, v21
	ds_bpermute_b32 v13, v13, v0
	v_xor_b32_e32 v14, 4, v14
	ds_bpermute_b32 v14, v14, v12
	global_load_dwordx4 v[30:33], v154, s[52:53] offset:512
	global_load_dwordx4 v[26:29], v154, s[52:53] offset:528
	global_load_dwordx4 v[22:25], v154, s[52:53] offset:640
	global_load_dwordx4 v[18:21], v154, s[52:53] offset:656
	s_bfe_i32 s8, s15, 0x1c0000
	s_waitcnt lgkmcnt(1)
	v_max_f32_e32 v13, v13, v13
	v_max_f32_e32 v0, v0, v13
	s_waitcnt lgkmcnt(0)
	v_max_f32_e32 v13, v14, v14
	v_max_f32_e32 v12, v12, v13
	v_mul_f32_e32 v0, 0x419feb85, v0
	v_mul_f32_e32 v0, v0, v12
	s_mul_i32 s16, s6, 0xc00000
	s_mul_hi_i32 s15, s6, 0xc00000
	s_add_u32 s6, s11, s16
	s_mov_b32 s22, s20
	v_writelane_b32 v255, s22, 23
	s_mul_hi_i32 s19, s4, 0x8604000
	s_mul_i32 s17, s4, 0x9a04000
	v_writelane_b32 v255, s23, 24
	s_waitcnt vmcnt(35)
	v_and_b32_e32 v225, 0xffff0000, v98
	s_waitcnt vmcnt(33)
	v_lshlrev_b32_e32 v216, 16, v110
	v_and_b32_e32 v217, 0xffff0000, v110
	s_waitcnt vmcnt(31)
	v_lshlrev_b32_e32 v208, 16, v119
	s_waitcnt vmcnt(30)
	v_lshlrev_b32_e32 v204, 16, v123
	v_and_b32_e32 v205, 0xffff0000, v123
	s_waitcnt vmcnt(28)
	v_lshlrev_b32_e32 v196, 16, v131
	v_and_b32_e32 v197, 0xffff0000, v131
	s_waitcnt vmcnt(26)
	v_lshlrev_b32_e32 v176, 16, v147
	v_and_b32_e32 v177, 0xffff0000, v147
	s_waitcnt vmcnt(24)
	v_lshlrev_b32_e32 v174, 16, v143
	v_and_b32_e32 v175, 0xffff0000, v143
	s_waitcnt vmcnt(23)
	v_mul_f32_e32 v10, v2, v224
	v_floor_f32_e32 v10, v10
	v_fma_f32 v2, v2, v224, -v10
	v_cos_f32_e32 v150, v2
	v_sin_f32_e32 v156, v2
	v_mul_f32_e32 v2, v3, v224
	v_floor_f32_e32 v2, v2
	v_fma_f32 v2, v3, v224, -v2
	v_cos_f32_e32 v151, v2
	v_sin_f32_e32 v157, v2
	v_mul_f32_e32 v2, v4, v224
	v_floor_f32_e32 v2, v2
	v_fma_f32 v2, v4, v224, -v2
	v_cos_f32_e32 v152, v2
	v_sin_f32_e32 v160, v2
	v_mul_f32_e32 v2, v5, v224
	v_floor_f32_e32 v2, v2
	v_fma_f32 v2, v5, v224, -v2
	v_cos_f32_e32 v153, v2
	v_sin_f32_e32 v161, v2
	s_waitcnt vmcnt(22)
	v_mul_f32_e32 v2, v6, v224
	v_floor_f32_e32 v2, v2
	v_fma_f32 v2, v6, v224, -v2
	v_cos_f32_e32 v158, v2
	v_sin_f32_e32 v164, v2
	v_mul_f32_e32 v2, v7, v224
	v_floor_f32_e32 v2, v2
	v_fma_f32 v2, v7, v224, -v2
	v_cos_f32_e32 v159, v2
	v_sin_f32_e32 v165, v2
	v_mul_f32_e32 v2, v8, v224
	v_floor_f32_e32 v2, v2
	v_fma_f32 v2, v8, v224, -v2
	v_cos_f32_e32 v162, v2
	v_sin_f32_e32 v166, v2
	v_mul_f32_e32 v2, v9, v224
	v_floor_f32_e32 v2, v2
	v_fma_f32 v2, v9, v224, -v2
	v_cos_f32_e32 v163, v2
	v_sin_f32_e32 v167, v2
	global_load_dwordx4 v[14:17], v154, s[52:53] offset:576
	global_load_dwordx4 v[10:13], v154, s[52:53] offset:592
	global_load_dwordx4 v[6:9], v154, s[52:53] offset:704
	global_load_dwordx4 v[2:5], v154, s[52:53] offset:720
	s_waitcnt vmcnt(25)
	v_mul_f32_e32 v154, v168, v224
	v_floor_f32_e32 v154, v154
	v_fma_f32 v220, v168, v224, -v154
	v_mul_f32_e32 v168, v169, v224
	v_floor_f32_e32 v168, v168
	v_fma_f32 v239, v169, v224, -v168
	v_mul_f32_e32 v168, v170, v224
	v_floor_f32_e32 v168, v168
	v_fma_f32 v218, v170, v224, -v168
	v_mul_f32_e32 v168, v171, v224
	v_floor_f32_e32 v168, v168
	v_fma_f32 v238, v171, v224, -v168
	s_waitcnt vmcnt(24)
	v_mul_f32_e32 v168, v102, v224
	v_floor_f32_e32 v168, v168
	v_fma_f32 v219, v102, v224, -v168
	v_mul_f32_e32 v102, v103, v224
	v_floor_f32_e32 v102, v102
	v_fma_f32 v221, v103, v224, -v102
	v_lshlrev_b32_e32 v102, 16, v145
	v_and_b32_e32 v103, 0xffff0000, v145
	v_lshlrev_b32_e32 v170, 16, v144
	v_and_b32_e32 v171, 0xffff0000, v144
	v_lshlrev_b32_e32 v180, 16, v146
	v_and_b32_e32 v181, 0xffff0000, v146
	v_lshlrev_b32_e32 v178, 16, v142
	v_and_b32_e32 v179, 0xffff0000, v142
	v_lshlrev_b32_e32 v146, 16, v137
	v_and_b32_e32 v147, 0xffff0000, v137
	v_lshlrev_b32_e32 v184, 16, v136
	v_and_b32_e32 v185, 0xffff0000, v136
	v_lshlrev_b32_e32 v188, 16, v135
	v_and_b32_e32 v189, 0xffff0000, v135
	v_lshlrev_b32_e32 v192, 16, v134
	v_and_b32_e32 v193, 0xffff0000, v134
	v_lshlrev_b32_e32 v142, 16, v133
	v_and_b32_e32 v143, 0xffff0000, v133
	v_lshlrev_b32_e32 v144, 16, v132
	v_and_b32_e32 v145, 0xffff0000, v132
	v_lshlrev_b32_e32 v198, 16, v130
	v_and_b32_e32 v199, 0xffff0000, v130
	v_lshlrev_b32_e32 v134, 16, v125
	v_and_b32_e32 v135, 0xffff0000, v125
	v_lshlrev_b32_e32 v136, 16, v124
	v_and_b32_e32 v137, 0xffff0000, v124
	v_lshlrev_b32_e32 v206, 16, v122
	v_and_b32_e32 v207, 0xffff0000, v122
	v_lshlrev_b32_e32 v130, 16, v121
	v_and_b32_e32 v131, 0xffff0000, v121
	v_lshlrev_b32_e32 v132, 16, v120
	v_and_b32_e32 v133, 0xffff0000, v120
	v_and_b32_e32 v209, 0xffff0000, v119
	v_lshlrev_b32_e32 v210, 16, v118
	v_and_b32_e32 v211, 0xffff0000, v118
	v_lshlrev_b32_e32 v122, 16, v113
	v_and_b32_e32 v123, 0xffff0000, v113
	v_lshlrev_b32_e32 v124, 16, v112
	v_and_b32_e32 v125, 0xffff0000, v112
	v_lshlrev_b32_e32 v112, 16, v111
	v_and_b32_e32 v113, 0xffff0000, v111
	v_lshlrev_b32_e32 v110, 16, v109
	v_and_b32_e32 v111, 0xffff0000, v109
	v_lshlrev_b32_e32 v118, 16, v108
	v_and_b32_e32 v119, 0xffff0000, v108
	v_lshlrev_b32_e32 v108, 16, v107
	v_and_b32_e32 v109, 0xffff0000, v107
	v_lshlrev_b32_e32 v120, 16, v106
	v_and_b32_e32 v121, 0xffff0000, v106
	v_lshlrev_b32_e32 v106, 16, v101
	v_and_b32_e32 v107, 0xffff0000, v101
	v_mul_f32_e32 v101, v104, v224
	v_floor_f32_e32 v101, v101
	v_fma_f32 v227, v104, v224, -v101
	v_mul_f32_e32 v101, v105, v224
	v_floor_f32_e32 v101, v101
	v_fma_f32 v230, v105, v224, -v101
	v_lshlrev_b32_e32 v224, 16, v98
	v_lshlrev_b32_e32 v168, 16, v149
	v_and_b32_e32 v169, 0xffff0000, v149
; DI float bflo(u32 v) { return __uint_as_float(v << 16); }
; DI float bfhi(u32 v) { return __uint_as_float(v & 0xffff0000u); }
; DI float shx(float v, int k) { return __int_as_float(__builtin_amdgcn_ds_bpermute((lane_id_l() ^ k) << 2, __float_as_int(v))); }
; DI void mla_attn_item(const WsPtrs& W, const float* pgq, const float* pgk, int item, unsigned char* smem) {
;     ...
;     float ss = 0.f;
; #pragma unroll
;     for (int ks = 0; ks < 12; ++ks) {
;       float a;
;       a = bflo(raw[ks].x); ss += a * a; a = bfhi(raw[ks].x); ss += a * a; a = bflo(raw[ks].y); ss += a * a; a = bfhi(raw[ks].y); ss += a * a;
;       a = bflo(raw[ks].z); ss += a * a; a = bfhi(raw[ks].z); ss += a * a; a = bflo(raw[ks].w); ss += a * a; a = bfhi(raw[ks].w); ss += a * a;
;     }
;     ss += shx(ss, 32);
	v_lshlrev_b32_e32 v172, 16, v148
	v_and_b32_e32 v173, 0xffff0000, v148
	v_lshlrev_b32_e32 v148, 16, v141
	v_and_b32_e32 v149, 0xffff0000, v141
	v_lshlrev_b32_e32 v186, 16, v140
	v_and_b32_e32 v187, 0xffff0000, v140
	v_lshlrev_b32_e32 v190, 16, v139
	v_and_b32_e32 v191, 0xffff0000, v139
	v_lshlrev_b32_e32 v194, 16, v138
	v_and_b32_e32 v195, 0xffff0000, v138
	v_lshlrev_b32_e32 v138, 16, v129
	v_and_b32_e32 v139, 0xffff0000, v129
	v_lshlrev_b32_e32 v140, 16, v128
	v_and_b32_e32 v141, 0xffff0000, v128
	v_lshlrev_b32_e32 v200, 16, v127
	v_and_b32_e32 v201, 0xffff0000, v127
	v_lshlrev_b32_e32 v202, 16, v126
	v_and_b32_e32 v203, 0xffff0000, v126
	v_lshlrev_b32_e32 v126, 16, v117
	v_and_b32_e32 v127, 0xffff0000, v117
	v_lshlrev_b32_e32 v128, 16, v116
	v_and_b32_e32 v129, 0xffff0000, v116
	v_lshlrev_b32_e32 v116, 16, v99
	v_and_b32_e32 v117, 0xffff0000, v99
	v_pk_mul_f32 v[98:99], v[224:225], v[224:225]
	v_lshlrev_b32_e32 v212, 16, v115
	v_and_b32_e32 v213, 0xffff0000, v115
	v_lshlrev_b32_e32 v214, 16, v114
	v_and_b32_e32 v215, 0xffff0000, v114
	v_lshlrev_b32_e32 v114, 16, v100
	v_and_b32_e32 v115, 0xffff0000, v100
	v_add_f32_e32 v100, v99, v98
	v_pk_mul_f32 v[98:99], v[116:117], v[116:117]
	v_cos_f32_e32 v154, v220
	v_add_f32_e32 v98, v98, v100
	v_add_f32_e32 v100, v99, v98
	v_pk_mul_f32 v[98:99], v[114:115], v[114:115]
	v_sin_f32_e32 v101, v239
	v_add_f32_e32 v98, v98, v100
	v_add_f32_e32 v100, v99, v98
	v_pk_mul_f32 v[98:99], v[106:107], v[106:107]
	v_sin_f32_e32 v105, v238
	v_add_f32_e32 v98, v98, v100
	v_add_f32_e32 v100, v99, v98
	v_pk_mul_f32 v[98:99], v[120:121], v[120:121]
	s_nop 0
	v_add_f32_e32 v98, v98, v100
	v_add_f32_e32 v100, v99, v98
	v_pk_mul_f32 v[98:99], v[108:109], v[108:109]
	s_nop 0
	v_add_f32_e32 v98, v98, v100
	v_add_f32_e32 v100, v99, v98
	v_pk_mul_f32 v[98:99], v[118:119], v[118:119]
	s_nop 0
	v_add_f32_e32 v98, v98, v100
	v_add_f32_e32 v100, v99, v98
	v_pk_mul_f32 v[98:99], v[110:111], v[110:111]
	s_nop 0
	v_add_f32_e32 v98, v98, v100
	v_add_f32_e32 v100, v99, v98
	v_pk_mul_f32 v[98:99], v[216:217], v[216:217]
	s_nop 0
	v_add_f32_e32 v98, v98, v100
	v_add_f32_e32 v100, v99, v98
	v_pk_mul_f32 v[98:99], v[112:113], v[112:113]
	s_nop 0
	v_add_f32_e32 v98, v98, v100
	v_add_f32_e32 v100, v99, v98
	v_pk_mul_f32 v[98:99], v[124:125], v[124:125]
	s_nop 0
	v_add_f32_e32 v98, v98, v100
	v_add_f32_e32 v100, v99, v98
	v_pk_mul_f32 v[98:99], v[122:123], v[122:123]
	s_nop 0
	v_add_f32_e32 v98, v98, v100
	v_add_f32_e32 v100, v99, v98
	v_pk_mul_f32 v[98:99], v[214:215], v[214:215]
	s_nop 0
	v_add_f32_e32 v98, v98, v100
	v_add_f32_e32 v100, v99, v98
	v_pk_mul_f32 v[98:99], v[212:213], v[212:213]
	s_nop 0
	v_add_f32_e32 v98, v98, v100
	v_add_f32_e32 v100, v99, v98
	v_pk_mul_f32 v[98:99], v[128:129], v[128:129]
	s_nop 0
	v_add_f32_e32 v98, v98, v100
	v_add_f32_e32 v100, v99, v98
	v_pk_mul_f32 v[98:99], v[126:127], v[126:127]
	s_nop 0
	v_add_f32_e32 v98, v98, v100
	v_add_f32_e32 v100, v99, v98
	v_pk_mul_f32 v[98:99], v[210:211], v[210:211]
	s_nop 0
	v_add_f32_e32 v98, v98, v100
	v_add_f32_e32 v100, v99, v98
	v_pk_mul_f32 v[98:99], v[208:209], v[208:209]
	s_nop 0
	v_add_f32_e32 v98, v98, v100
	v_add_f32_e32 v100, v99, v98
	v_pk_mul_f32 v[98:99], v[132:133], v[132:133]
	s_nop 0
	v_add_f32_e32 v98, v98, v100
	v_add_f32_e32 v100, v99, v98
	v_pk_mul_f32 v[98:99], v[130:131], v[130:131]
	s_nop 0
	v_add_f32_e32 v98, v98, v100
	v_add_f32_e32 v100, v99, v98
	v_pk_mul_f32 v[98:99], v[206:207], v[206:207]
	s_nop 0
	v_add_f32_e32 v98, v98, v100
	v_add_f32_e32 v100, v99, v98
	v_pk_mul_f32 v[98:99], v[204:205], v[204:205]
	s_nop 0
	v_add_f32_e32 v98, v98, v100
	v_add_f32_e32 v100, v99, v98
	v_pk_mul_f32 v[98:99], v[136:137], v[136:137]
	s_nop 0
	v_add_f32_e32 v98, v98, v100
	v_add_f32_e32 v100, v99, v98
	v_pk_mul_f32 v[98:99], v[134:135], v[134:135]
	s_nop 0
	v_add_f32_e32 v98, v98, v100
	v_add_f32_e32 v100, v99, v98
	v_pk_mul_f32 v[98:99], v[202:203], v[202:203]
	s_nop 0
	v_add_f32_e32 v98, v98, v100
	v_add_f32_e32 v100, v99, v98
	v_pk_mul_f32 v[98:99], v[200:201], v[200:201]
	s_nop 0
	v_add_f32_e32 v98, v98, v100
	v_add_f32_e32 v100, v99, v98
	v_pk_mul_f32 v[98:99], v[140:141], v[140:141]
	s_nop 0
	v_add_f32_e32 v98, v98, v100
	v_add_f32_e32 v100, v99, v98
	v_pk_mul_f32 v[98:99], v[138:139], v[138:139]
	s_nop 0
	v_add_f32_e32 v98, v98, v100
	v_add_f32_e32 v100, v99, v98
	v_pk_mul_f32 v[98:99], v[198:199], v[198:199]
	s_nop 0
	v_add_f32_e32 v98, v98, v100
	v_add_f32_e32 v100, v99, v98
	v_pk_mul_f32 v[98:99], v[196:197], v[196:197]
	s_nop 0
	v_add_f32_e32 v98, v98, v100
	v_add_f32_e32 v100, v99, v98
	v_pk_mul_f32 v[98:99], v[144:145], v[144:145]
	s_nop 0
	v_add_f32_e32 v98, v98, v100
	v_add_f32_e32 v100, v99, v98
	v_pk_mul_f32 v[98:99], v[142:143], v[142:143]
	s_nop 0
	v_add_f32_e32 v98, v98, v100
	v_add_f32_e32 v100, v99, v98
	v_pk_mul_f32 v[98:99], v[194:195], v[194:195]
	s_nop 0
	v_add_f32_e32 v98, v98, v100
	v_add_f32_e32 v100, v99, v98
	v_pk_mul_f32 v[98:99], v[190:191], v[190:191]
	s_nop 0
	v_add_f32_e32 v98, v98, v100
	v_add_f32_e32 v100, v99, v98
	v_pk_mul_f32 v[98:99], v[186:187], v[186:187]
	s_nop 0
	v_add_f32_e32 v98, v98, v100
	v_add_f32_e32 v100, v99, v98
	v_pk_mul_f32 v[98:99], v[148:149], v[148:149]
	s_nop 0
	v_add_f32_e32 v98, v98, v100
	v_add_f32_e32 v100, v99, v98
	v_pk_mul_f32 v[98:99], v[180:181], v[180:181]
	s_nop 0
	v_add_f32_e32 v98, v98, v100
	v_add_f32_e32 v100, v99, v98
	v_pk_mul_f32 v[98:99], v[176:177], v[176:177]
	s_nop 0
	v_add_f32_e32 v98, v98, v100
	v_add_f32_e32 v100, v99, v98
	v_pk_mul_f32 v[98:99], v[172:173], v[172:173]
	s_nop 0
	v_add_f32_e32 v98, v98, v100
	v_add_f32_e32 v100, v99, v98
	v_pk_mul_f32 v[98:99], v[168:169], v[168:169]
	s_nop 0
	v_add_f32_e32 v98, v98, v100
	v_add_f32_e32 v100, v99, v98
	v_pk_mul_f32 v[98:99], v[192:193], v[192:193]
	s_nop 0
	v_add_f32_e32 v98, v98, v100
	v_add_f32_e32 v100, v99, v98
	v_pk_mul_f32 v[98:99], v[188:189], v[188:189]
	s_nop 0
	v_add_f32_e32 v98, v98, v100
	v_add_f32_e32 v100, v99, v98
	v_pk_mul_f32 v[98:99], v[184:185], v[184:185]
	s_nop 0
	v_add_f32_e32 v98, v98, v100
	v_add_f32_e32 v100, v99, v98
	v_pk_mul_f32 v[98:99], v[146:147], v[146:147]
	s_nop 0
	v_add_f32_e32 v98, v98, v100
	v_add_f32_e32 v100, v99, v98
	v_pk_mul_f32 v[98:99], v[178:179], v[178:179]
	s_nop 0
	v_add_f32_e32 v98, v98, v100
	v_add_f32_e32 v100, v99, v98
	v_pk_mul_f32 v[98:99], v[174:175], v[174:175]
	s_nop 0
	v_add_f32_e32 v98, v98, v100
	v_add_f32_e32 v100, v99, v98
	v_pk_mul_f32 v[98:99], v[170:171], v[170:171]
	s_nop 0
	v_add_f32_e32 v98, v98, v100
	v_add_f32_e32 v100, v99, v98
	v_pk_mul_f32 v[98:99], v[102:103], v[102:103]
	s_nop 0
	v_add_f32_e32 v98, v98, v100
	v_add_f32_e32 v99, v99, v98
	ds_bpermute_b32 v104, v155, v99
	v_sin_f32_e32 v100, v220
	v_cos_f32_e32 v98, v218
	v_cos_f32_e32 v155, v239
	s_waitcnt lgkmcnt(0)
; DI u32 pack2(float a, float b) { f2_t v = {a, b}; bf2_t r = __builtin_convertvector(v, bf2_t); return __builtin_bit_cast(u32, r); }
; DI float bflo(u32 v) { return __uint_as_float(v << 16); }
; DI float bfhi(u32 v) { return __uint_as_float(v & 0xffff0000u); }
; DI void mla_attn_item(const WsPtrs& W, const float* pgq, const float* pgk, int item, unsigned char* smem) {
;     ...
;     const float sc = rsqrtf(ss * (1.f / 192.f) + EPSV) * (0.07216878364870322f * LOG2E);
;     const float pos = (float)(q0 + r);
;     auto scaled = [&](int ks, float (&v)[8]) __attribute__((always_inline)) {
;       const f32x4 g0 = *(const f32x4*)(pgq + 16 * ks + 8 * h), g1 = *(const f32x4*)(pgq + 16 * ks + 8 * h + 4);
;       v[0] = bflo(raw[ks].x) * sc * g0.x; v[1] = bfhi(raw[ks].x) * sc * g0.y; v[2] = bflo(raw[ks].y) * sc * g0.z; v[3] = bfhi(raw[ks].y) * sc * g0.w;
;       v[4] = bflo(raw[ks].z) * sc * g1.x; v[5] = bfhi(raw[ks].z) * sc * g1.y; v[6] = bflo(raw[ks].w) * sc * g1.z; v[7] = bfhi(raw[ks].w) * sc * g1.w;
;     };
;     auto packed = [&](const float (&v)[8]) __attribute__((always_inline)) {
;       u32x4 p; p.x = pack2(v[0], v[1]); p.y = pack2(v[2], v[3]); p.z = pack2(v[4], v[5]); p.w = pack2(v[6], v[7]);
;       return __builtin_bit_cast(bf16x8, p);
;     };
; #pragma unroll
;     for (int ks = 0; ks < 8; ++ks) { float v[8]; scaled(ks, v); qn[ks] = packed(v); }
; #pragma unroll
;     for (int ks = 8; ks < 10; ++ks) {
;       float x1[8], x2[8]; scaled(ks, x1); scaled(ks + 2, x2);
; #pragma unroll
;       for (int i = 0; i < 8; ++i) {
;         float c, sn; rot_cs(pos, W.rope[8 + 16 * (ks - 8) + 8 * h + i], c, sn);
;         const float a = x1[i] * c - x2[i] * sn, b = x2[i] * c + x1[i] * sn;
;         x1[i] = a; x2[i] = b;
;       }
;       qn[ks] = packed(x1); qn[ks + 2] = packed(x2);
;     }
;   }
;   if (M <= 56.f)
	v_add_f32_e32 v99, v99, v104
	v_fmamk_f32 v99, v99, 0x3baaaaab, v228
	v_mul_f32_e32 v104, 0x4b800000, v99
	v_cmp_gt_f32_e32 vcc, s7, v99
	s_mov_b32 s7, 0x3f828f5c
	s_nop 0
	v_cndmask_b32_e32 v99, v99, v104, vcc
	v_rsq_f32_e32 v220, v99
	v_sin_f32_e32 v104, v218
	v_cos_f32_e32 v99, v238
	v_mul_f32_e32 v218, 0x45800000, v220
	v_cndmask_b32_e32 v218, v220, v218, vcc
	v_mul_f32_e32 v226, 0x3dd53b94, v218
	v_pk_mul_f32 v[224:225], v[226:227], v[224:225] op_sel_hi:[0,1]
	s_waitcnt vmcnt(22)
	v_pk_mul_f32 v[224:225], v[94:95], v[224:225]
	v_pk_mul_f32 v[94:95], v[226:227], v[116:117] op_sel_hi:[0,1]
	v_pk_mul_f32 v[114:115], v[226:227], v[114:115] op_sel_hi:[0,1]
	v_pk_mul_f32 v[116:117], v[96:97], v[94:95]
	v_pk_mul_f32 v[90:91], v[90:91], v[114:115]
	v_cvt_pk_bf16_f32 v115, v116, v117
	v_cvt_pk_bf16_f32 v116, v90, v91
	v_pk_mul_f32 v[90:91], v[226:227], v[120:121] op_sel_hi:[0,1]
	s_waitcnt vmcnt(20)
	v_pk_mul_f32 v[86:87], v[86:87], v[90:91]
	v_pk_mul_f32 v[90:91], v[226:227], v[108:109] op_sel_hi:[0,1]
	v_pk_mul_f32 v[88:89], v[88:89], v[90:91]
	v_pk_mul_f32 v[90:91], v[226:227], v[118:119] op_sel_hi:[0,1]
	v_pk_mul_f32 v[82:83], v[82:83], v[90:91]
	v_cos_f32_e32 v218, v219
	v_cvt_pk_bf16_f32 v120, v82, v83
	v_pk_mul_f32 v[82:83], v[226:227], v[216:217] op_sel_hi:[0,1]
	s_waitcnt vmcnt(18)
	v_pk_mul_f32 v[78:79], v[78:79], v[82:83]
	v_pk_mul_f32 v[82:83], v[226:227], v[112:113] op_sel_hi:[0,1]
	v_pk_mul_f32 v[80:81], v[80:81], v[82:83]
	v_pk_mul_f32 v[82:83], v[226:227], v[124:125] op_sel_hi:[0,1]
	v_pk_mul_f32 v[74:75], v[74:75], v[82:83]
	v_sin_f32_e32 v220, v219
	v_cvt_pk_bf16_f32 v124, v74, v75
	v_pk_mul_f32 v[74:75], v[226:227], v[214:215] op_sel_hi:[0,1]
	s_waitcnt vmcnt(16)
	v_pk_mul_f32 v[70:71], v[70:71], v[74:75]
	v_pk_mul_f32 v[74:75], v[226:227], v[212:213] op_sel_hi:[0,1]
	v_pk_mul_f32 v[72:73], v[72:73], v[74:75]
	v_pk_mul_f32 v[74:75], v[226:227], v[128:129] op_sel_hi:[0,1]
	v_pk_mul_f32 v[66:67], v[66:67], v[74:75]
	v_cos_f32_e32 v219, v221
	v_cvt_pk_bf16_f32 v128, v66, v67
	v_pk_mul_f32 v[66:67], v[226:227], v[210:211] op_sel_hi:[0,1]
	s_waitcnt vmcnt(14)
	v_pk_mul_f32 v[62:63], v[62:63], v[66:67]
	v_pk_mul_f32 v[66:67], v[226:227], v[208:209] op_sel_hi:[0,1]
	v_pk_mul_f32 v[64:65], v[64:65], v[66:67]
	v_pk_mul_f32 v[66:67], v[226:227], v[132:133] op_sel_hi:[0,1]
	v_pk_mul_f32 v[58:59], v[58:59], v[66:67]
	v_sin_f32_e32 v221, v221
	v_cvt_pk_bf16_f32 v132, v58, v59
	v_pk_mul_f32 v[58:59], v[226:227], v[206:207] op_sel_hi:[0,1]
	s_waitcnt vmcnt(12)
	v_pk_mul_f32 v[54:55], v[54:55], v[58:59]
	v_pk_mul_f32 v[58:59], v[226:227], v[204:205] op_sel_hi:[0,1]
	v_pk_mul_f32 v[56:57], v[56:57], v[58:59]
	v_pk_mul_f32 v[58:59], v[226:227], v[136:137] op_sel_hi:[0,1]
	v_pk_mul_f32 v[50:51], v[50:51], v[58:59]
	v_sin_f32_e32 v96, v227
	v_cvt_pk_bf16_f32 v136, v50, v51
	v_pk_mul_f32 v[50:51], v[226:227], v[202:203] op_sel_hi:[0,1]
	s_waitcnt vmcnt(10)
	v_pk_mul_f32 v[46:47], v[46:47], v[50:51]
	v_pk_mul_f32 v[50:51], v[226:227], v[200:201] op_sel_hi:[0,1]
	v_pk_mul_f32 v[48:49], v[48:49], v[50:51]
	v_pk_mul_f32 v[50:51], v[226:227], v[140:141] op_sel_hi:[0,1]
	v_pk_mul_f32 v[42:43], v[42:43], v[50:51]
	v_sin_f32_e32 v97, v230
	v_cvt_pk_bf16_f32 v140, v42, v43
	v_pk_mul_f32 v[42:43], v[226:227], v[198:199] op_sel_hi:[0,1]
	s_waitcnt vmcnt(8)
	v_pk_mul_f32 v[38:39], v[38:39], v[42:43]
	v_pk_mul_f32 v[42:43], v[226:227], v[196:197] op_sel_hi:[0,1]
	v_pk_mul_f32 v[40:41], v[40:41], v[42:43]
	v_pk_mul_f32 v[42:43], v[226:227], v[144:145] op_sel_hi:[0,1]
	v_pk_mul_f32 v[34:35], v[34:35], v[42:43]
	v_pk_mul_f32 v[66:67], v[226:227], v[130:131] op_sel_hi:[0,1]
	v_cvt_pk_bf16_f32 v144, v34, v35
	v_pk_mul_f32 v[34:35], v[226:227], v[194:195] op_sel_hi:[0,1]
	s_waitcnt vmcnt(7)
	v_pk_mul_f32 v[30:31], v[30:31], v[34:35]
	v_pk_mul_f32 v[34:35], v[226:227], v[190:191] op_sel_hi:[0,1]
	v_pk_mul_f32 v[32:33], v[32:33], v[34:35]
	v_pk_mul_f32 v[34:35], v[226:227], v[186:187] op_sel_hi:[0,1]
	s_waitcnt vmcnt(6)
	v_pk_mul_f32 v[26:27], v[26:27], v[34:35]
	v_pk_mul_f32 v[34:35], v[226:227], v[148:149] op_sel_hi:[0,1]
	v_pk_mul_f32 v[28:29], v[28:29], v[34:35]
	v_pk_mul_f32 v[34:35], v[226:227], v[192:193] op_sel_hi:[0,1]
	s_waitcnt vmcnt(5)
	v_pk_mul_f32 v[22:23], v[22:23], v[34:35]
	v_pk_mul_f32 v[34:35], v[226:227], v[188:189] op_sel_hi:[0,1]
	v_pk_mul_f32 v[24:25], v[24:25], v[34:35]
	v_pk_mul_f32 v[34:35], v[226:227], v[184:185] op_sel_hi:[0,1]
	s_waitcnt vmcnt(4)
	v_pk_mul_f32 v[18:19], v[18:19], v[34:35]
	v_pk_mul_f32 v[34:35], v[226:227], v[146:147] op_sel_hi:[0,1]
	v_pk_mul_f32 v[20:21], v[20:21], v[34:35]
	v_pk_mul_f32 v[34:35], v[156:157], v[30:31]
	v_cos_f32_e32 v94, v227
	v_pk_fma_f32 v[34:35], v[150:151], v[22:23], v[34:35]
	v_pk_mul_f32 v[22:23], v[156:157], v[22:23]
	v_cos_f32_e32 v95, v230
	v_pk_fma_f32 v[22:23], v[150:151], v[30:31], v[22:23] neg_lo:[0,0,1] neg_hi:[0,0,1]
	v_pk_mul_f32 v[30:31], v[160:161], v[32:33]
	v_pk_mul_f32 v[60:61], v[60:61], v[66:67]
	v_pk_fma_f32 v[30:31], v[152:153], v[24:25], v[30:31]
	v_pk_mul_f32 v[24:25], v[160:161], v[24:25]
	v_fma_f32 v66, v0, s7, 1.0
	v_pk_fma_f32 v[24:25], v[152:153], v[32:33], v[24:25] neg_lo:[0,0,1] neg_hi:[0,0,1]
	v_pk_mul_f32 v[32:33], v[164:165], v[26:27]
	s_mov_b32 s7, 0x42600000
	v_pk_fma_f32 v[32:33], v[158:159], v[18:19], v[32:33]
	v_pk_mul_f32 v[18:19], v[164:165], v[18:19]
	v_cmp_ge_f32_e32 vcc, s7, v66
	v_pk_fma_f32 v[18:19], v[158:159], v[26:27], v[18:19] neg_lo:[0,0,1] neg_hi:[0,0,1]
	s_addc_u32 s7, s12, s15
	v_cvt_pk_bf16_f32 v148, v18, v19
	v_pk_mul_f32 v[18:19], v[226:227], v[180:181] op_sel_hi:[0,1]
	s_waitcnt vmcnt(3)
; DI u32 pack2(float a, float b) { f2_t v = {a, b}; bf2_t r = __builtin_convertvector(v, bf2_t); return __builtin_bit_cast(u32, r); }
;     ...
; #pragma unroll
;   for (int i = 0; i < NKL; ++i) { int c = tid + NTHR * i; int row = c / KCH, kc = c % KCH; koff[i] = (u32)(row * ldk + 8 * kc) * 2u; klds[i] = row * KST + 8 * kc; }
;   const u32 voff = (u32)((tid >> 3) * 4096 + 8 * (tid & 7)) * 2u;
;   const int vlds = 64 * KST + (tid >> 3) * 72 + 8 * (tid & 7);
;   auto gload = [&](int k0) __attribute__((always_inline)) {
;     const char* kb = (const char*)Kg + (size_t)k0 * ldk * 2;
; #pragma unroll
;     for (int i = 0; i < NKL; ++i) rk[i] = *(const u32x4*)(kb + koff[i]);
;     const char* vb = (const char*)VTg + (size_t)k0 * 2;
; #pragma unroll
;     for (int i = 0; i < 2; ++i) rv[i] = *(const u32x4*)(vb + (size_t)i * 64 * 4096 * 2 + voff);
;   };
;   auto lstore = [&](int b) __attribute__((always_inline)) {
;     u16* St = S0 + b * STG;
; #pragma unroll
;     for (int i = 0; i < NKL; ++i) *(u32x4*)(St + klds[i]) = rk[i];
; #pragma unroll
;     for (int i = 0; i < 2; ++i) *(u32x4*)(St + vlds + i * 64 * 72) = rv[i];
;   };
;   gload(kt0 * 64);
;   __syncthreads();
;   lstore(0);
; DI void mla_attn_item(const WsPtrs& W, const float* pgq, const float* pgk, int item, unsigned char* smem) {
;     ...
;     auto packed = [&](const float (&v)[8]) __attribute__((always_inline)) {
;       u32x4 p; p.x = pack2(v[0], v[1]); p.y = pack2(v[2], v[3]); p.z = pack2(v[4], v[5]); p.w = pack2(v[6], v[7]);
;       return __builtin_bit_cast(bf16x8, p);
;     };
; #pragma unroll
;     for (int ks = 0; ks < 8; ++ks) { float v[8]; scaled(ks, v); qn[ks] = packed(v); }
; #pragma unroll
;     for (int ks = 8; ks < 10; ++ks) {
;       float x1[8], x2[8]; scaled(ks, x1); scaled(ks + 2, x2);
; #pragma unroll
;       for (int i = 0; i < 8; ++i) {
;         float c, sn; rot_cs(pos, W.rope[8 + 16 * (ks - 8) + 8 * h + i], c, sn);
;         const float a = x1[i] * c - x2[i] * sn, b = x2[i] * c + x1[i] * sn;
;         x1[i] = a; x2[i] = b;
;       }
;       qn[ks] = packed(x1); qn[ks + 2] = packed(x2);
;     }
;   }
;   if (M <= 56.f)
;     attn_core<192, 192, 1>(W.QC + (tokb + q0) * 1536 + hh * 192, 1536, W.KC + tokb * 1536 + hh * 192, 1536,
;                            W.CVT + (size_t)bh * 128 * 4096, 0, q0, M, o, l, smem, 0, 64, true, qn);
	v_pk_mul_f32 v[14:15], v[14:15], v[18:19]
	v_pk_mul_f32 v[18:19], v[226:227], v[176:177] op_sel_hi:[0,1]
	v_pk_mul_f32 v[16:17], v[16:17], v[18:19]
	v_pk_mul_f32 v[18:19], v[226:227], v[172:173] op_sel_hi:[0,1]
	s_waitcnt vmcnt(2)
	v_pk_mul_f32 v[10:11], v[10:11], v[18:19]
	v_pk_mul_f32 v[18:19], v[226:227], v[168:169] op_sel_hi:[0,1]
	v_pk_mul_f32 v[12:13], v[12:13], v[18:19]
	v_pk_mul_f32 v[18:19], v[226:227], v[178:179] op_sel_hi:[0,1]
	s_waitcnt vmcnt(1)
	v_pk_mul_f32 v[6:7], v[6:7], v[18:19]
	v_pk_mul_f32 v[18:19], v[226:227], v[174:175] op_sel_hi:[0,1]
	v_pk_mul_f32 v[8:9], v[8:9], v[18:19]
	v_pk_mul_f32 v[18:19], v[226:227], v[170:171] op_sel_hi:[0,1]
	s_waitcnt vmcnt(0)
	v_pk_mul_f32 v[2:3], v[2:3], v[18:19]
	v_pk_mul_f32 v[18:19], v[226:227], v[102:103] op_sel_hi:[0,1]
	v_pk_mul_f32 v[4:5], v[4:5], v[18:19]
	v_pk_mul_f32 v[18:19], v[100:101], v[14:15]
	s_add_u32 s6, s6, s20
	v_pk_fma_f32 v[18:19], v[154:155], v[6:7], v[18:19]
	v_pk_mul_f32 v[6:7], v[100:101], v[6:7]
	v_pk_mul_f32 v[26:27], v[166:167], v[28:29]
	v_pk_fma_f32 v[6:7], v[154:155], v[14:15], v[6:7] neg_lo:[0,0,1] neg_hi:[0,0,1]
	v_pk_mul_f32 v[14:15], v[104:105], v[16:17]
	s_addc_u32 s7, s7, 0
	v_pk_fma_f32 v[14:15], v[98:99], v[8:9], v[14:15]
	v_pk_mul_f32 v[8:9], v[104:105], v[8:9]
	s_ashr_i32 s9, s8, 31
	v_pk_fma_f32 v[8:9], v[98:99], v[16:17], v[8:9] neg_lo:[0,0,1] neg_hi:[0,0,1]
	v_pk_mul_f32 v[16:17], v[220:221], v[10:11]
	v_pk_mul_f32 v[106:107], v[226:227], v[106:107] op_sel_hi:[0,1]
	v_pk_fma_f32 v[16:17], v[218:219], v[2:3], v[16:17]
	v_pk_mul_f32 v[2:3], v[220:221], v[2:3]
	v_pk_mul_f32 v[90:91], v[226:227], v[110:111] op_sel_hi:[0,1]
	v_pk_fma_f32 v[2:3], v[218:219], v[10:11], v[2:3] neg_lo:[0,0,1] neg_hi:[0,0,1]
	v_pk_mul_f32 v[10:11], v[96:97], v[12:13]
	v_pk_mul_f32 v[82:83], v[226:227], v[122:123] op_sel_hi:[0,1]
	v_pk_mul_f32 v[74:75], v[226:227], v[126:127] op_sel_hi:[0,1]
	v_pk_mul_f32 v[58:59], v[226:227], v[134:135] op_sel_hi:[0,1]
	v_pk_mul_f32 v[50:51], v[226:227], v[138:139] op_sel_hi:[0,1]
	v_pk_mul_f32 v[42:43], v[226:227], v[142:143] op_sel_hi:[0,1]
	v_pk_fma_f32 v[26:27], v[162:163], v[20:21], v[26:27]
	v_pk_mul_f32 v[20:21], v[166:167], v[20:21]
	v_pk_fma_f32 v[10:11], v[94:95], v[4:5], v[10:11]
	v_pk_mul_f32 v[4:5], v[96:97], v[4:5]
	s_lshl_b64 s[8:9], s[8:9], 20
	v_pk_mul_f32 v[92:93], v[92:93], v[106:107]
	v_pk_mul_f32 v[84:85], v[84:85], v[90:91]
	v_pk_mul_f32 v[76:77], v[76:77], v[82:83]
	v_pk_mul_f32 v[68:69], v[68:69], v[74:75]
	v_pk_mul_f32 v[52:53], v[52:53], v[58:59]
	v_pk_mul_f32 v[44:45], v[44:45], v[50:51]
	v_pk_mul_f32 v[36:37], v[36:37], v[42:43]
	v_pk_fma_f32 v[20:21], v[162:163], v[28:29], v[20:21] neg_lo:[0,0,1] neg_hi:[0,0,1]
	v_pk_fma_f32 v[4:5], v[94:95], v[12:13], v[4:5] neg_lo:[0,0,1] neg_hi:[0,0,1]
	s_add_u32 s8, s5, s8
	v_cvt_pk_bf16_f32 v114, v224, v225
	v_cvt_pk_bf16_f32 v117, v92, v93
	v_cvt_pk_bf16_f32 v118, v86, v87
	v_cvt_pk_bf16_f32 v119, v88, v89
	v_cvt_pk_bf16_f32 v121, v84, v85
	v_cvt_pk_bf16_f32 v122, v78, v79
	v_cvt_pk_bf16_f32 v123, v80, v81
	v_cvt_pk_bf16_f32 v125, v76, v77
	v_cvt_pk_bf16_f32 v126, v70, v71
	v_cvt_pk_bf16_f32 v127, v72, v73
	v_cvt_pk_bf16_f32 v129, v68, v69
	v_cvt_pk_bf16_f32 v130, v62, v63
	v_cvt_pk_bf16_f32 v131, v64, v65
	v_cvt_pk_bf16_f32 v133, v60, v61
	v_cvt_pk_bf16_f32 v134, v54, v55
	v_cvt_pk_bf16_f32 v135, v56, v57
	v_cvt_pk_bf16_f32 v137, v52, v53
	v_cvt_pk_bf16_f32 v138, v46, v47
	v_cvt_pk_bf16_f32 v139, v48, v49
	v_cvt_pk_bf16_f32 v141, v44, v45
	v_cvt_pk_bf16_f32 v142, v38, v39
	v_cvt_pk_bf16_f32 v143, v40, v41
	v_cvt_pk_bf16_f32 v145, v36, v37
	v_cvt_pk_bf16_f32 v146, v22, v23
	v_cvt_pk_bf16_f32 v147, v24, v25
	v_cvt_pk_bf16_f32 v149, v20, v21
	v_cvt_pk_bf16_f32 v150, v34, v35
	v_cvt_pk_bf16_f32 v151, v30, v31
	v_cvt_pk_bf16_f32 v152, v32, v33
	v_cvt_pk_bf16_f32 v153, v26, v27
	v_cvt_pk_bf16_f32 v154, v6, v7
	v_cvt_pk_bf16_f32 v155, v8, v9
	v_cvt_pk_bf16_f32 v156, v2, v3
	v_cvt_pk_bf16_f32 v157, v4, v5
	v_cvt_pk_bf16_f32 v158, v18, v19
	v_cvt_pk_bf16_f32 v159, v14, v15
	v_cvt_pk_bf16_f32 v160, v16, v17
	v_cvt_pk_bf16_f32 v161, v10, v11
	s_addc_u32 s9, s14, s9
	s_mul_i32 s20, s4, 0x8604000
	s_mul_hi_i32 s14, s4, 0x9a04000
	s_and_saveexec_b64 s[4:5], vcc
	s_xor_b64 s[4:5], exec, s[4:5]
	s_cbranch_execz .LBB0_597
	v_mov_b32_e32 v23, v250
	s_mov_b32 s22, 0x2aaaaaab
	s_movk_i32 s21, 0x600
	v_mul_hi_i32 v0, v23, s22
	v_lshrrev_b32_e32 v2, 31, v0
	v_ashrrev_i32_e32 v0, 2, v0
	v_add_u32_e32 v25, v0, v2
	v_mul_lo_u32 v0, v25, 24
	v_sub_u32_e32 v0, v23, v0
	v_mul_lo_u32 v2, v25, s21
	v_lshl_add_u32 v22, v0, 3, v2
	v_add_u32_e32 v2, 0x200, v23
	v_mul_hi_i32 v3, v2, s22
	v_lshrrev_b32_e32 v4, 31, v3
	v_ashrrev_i32_e32 v3, 2, v3
	v_add_u32_e32 v29, v3, v4
	v_mul_lo_u32 v3, v29, 24
	v_sub_u32_e32 v2, v2, v3
	v_mul_lo_u32 v3, v29, s21
	v_lshl_add_u32 v24, v2, 3, v3
	v_add_u32_e32 v2, 0x400, v23
	v_mul_hi_i32 v3, v2, s22
	v_lshrrev_b32_e32 v4, 31, v3
	v_ashrrev_i32_e32 v3, 2, v3
	v_add_u32_e32 v33, v3, v4
	v_mul_lo_u32 v3, v33, 24
	v_sub_u32_e32 v2, v2, v3
	v_mul_lo_u32 v3, v33, s21
	v_lshl_add_u32 v28, v2, 3, v3
	v_ashrrev_i32_e32 v38, 3, v23
	v_lshlrev_b32_e32 v2, 3, v23
	v_and_b32_e32 v32, 56, v2
	v_lshlrev_b32_e32 v2, 13, v38
	v_lshl_or_b32 v34, v32, 1, v2
	v_mov_b32_e32 v35, v1
	v_lshl_add_u64 v[18:19], s[8:9], 0, v[34:35]
	s_mov_b32 s21, 0x80000
	v_add_co_u32_e32 v36, vcc, s21, v18
	s_add_u32 s22, s6, 0x30000
	v_lshlrev_b32_e32 v0, 1, v22
	v_lshlrev_b32_e32 v26, 1, v24
	v_lshlrev_b32_e32 v30, 1, v28
	v_addc_co_u32_e32 v37, vcc, 0, v19, vcc
	s_addc_u32 s23, s7, 0
	global_load_dwordx4 v[2:5], v0, s[6:7]
	global_load_dwordx4 v[6:9], v26, s[6:7]
	global_load_dwordx4 v[10:13], v30, s[6:7]
	global_load_dwordx4 v[14:17], v34, s[8:9]
	global_load_dwordx4 v[18:21], v[36:37], off
	s_barrier
; #define MFMA32(a, b, c) __builtin_amdgcn_mfma_f32_32x32x16_bf16((a), (b), (c), 0, 0, 0)
;     ...
; #pragma unroll
;   for (int i = 0; i < NKL; ++i) { int c = tid + NTHR * i; int row = c / KCH, kc = c % KCH; koff[i] = (u32)(row * ldk + 8 * kc) * 2u; klds[i] = row * KST + 8 * kc; }
;   const u32 voff = (u32)((tid >> 3) * 4096 + 8 * (tid & 7)) * 2u;
;   const int vlds = 64 * KST + (tid >> 3) * 72 + 8 * (tid & 7);
;   auto gload = [&](int k0) __attribute__((always_inline)) {
;     const char* kb = (const char*)Kg + (size_t)k0 * ldk * 2;
; #pragma unroll
;     for (int i = 0; i < NKL; ++i) rk[i] = *(const u32x4*)(kb + koff[i]);
;     const char* vb = (const char*)VTg + (size_t)k0 * 2;
; #pragma unroll
;     for (int i = 0; i < 2; ++i) rv[i] = *(const u32x4*)(vb + (size_t)i * 64 * 4096 * 2 + voff);
;   };
;   auto lstore = [&](int b) __attribute__((always_inline)) {
;     u16* St = S0 + b * STG;
; #pragma unroll
;     for (int i = 0; i < NKL; ++i) *(u32x4*)(St + klds[i]) = rk[i];
; #pragma unroll
;     for (int i = 0; i < 2; ++i) *(u32x4*)(St + vlds + i * 64 * 72) = rv[i];
;   };
;   gload(kt0 * 64);
;   __syncthreads();
;   lstore(0);
;   gload((kt0 + 1) * 64);
;   __syncthreads();
;   const float qpos = (float)(qpos0 + r);
; #pragma unroll 1
;   for (int kt = 0; kt < nkt; ++kt) {
;     const u16* Ks = S0 + (kt & 1) * STG;
;     const u16* Vs = Ks + 64 * KST;
;     f32x16 st[2];
; #pragma unroll
;     for (int t2 = 0; t2 < 2; ++t2)
; #pragma unroll
;       for (int e = 0; e < 16; ++e) st[t2][e] = (MODE == 1) ? -dl : 0.f;
;     {
;       constexpr int BPT = NQ / 4;
;       constexpr int NBAT = 2 * BPT;
;       bf16x8 kf[2][4];
; #pragma unroll
;       for (int i = 0; i < 4; ++i) kf[0][i] = *(const bf16x8*)(Ks + r * KST + kcol_off + 16 * i + 8 * h);
; #pragma unroll
;       for (int g = 0; g < NBAT; ++g) {
;         if (g + 1 < NBAT) {
;           const int t2n = (g + 1) / BPT, bn = (g + 1) % BPT;
; #pragma unroll
;           for (int i = 0; i < 4; ++i) kf[(g + 1) & 1][i] = *(const bf16x8*)(Ks + (32 * t2n + r) * KST + kcol_off + 16 * (4 * bn + i) + 8 * h);
;         }
;         __builtin_amdgcn_sched_barrier(0);
;         const int t2 = g / BPT, b = g % BPT;
; #pragma unroll
;         for (int i = 0; i < 4; ++i) st[t2] = MFMA32(kf[g & 1][i], qf[4 * b + i], st[t2]);
	global_load_dwordx4 v[162:165], v26, s[22:23]
	global_load_dwordx4 v[170:173], v30, s[22:23]
	global_load_dwordx4 v[174:177], v34, s[8:9] offset:128
	global_load_dwordx4 v[166:169], v0, s[22:23]
	global_load_dwordx4 v[178:181], v[36:37], off offset:128
	v_readlane_b32 s22, v255, 25
	s_or_b32 s22, s22, s13
	s_bfe_i32 s23, s22, 0x1001b
	s_bfe_i32 s22, s22, 0x1c0000
	s_lshl_b64 s[22:23], s[22:23], 20
	s_add_u32 s22, s20, s22
	s_addc_u32 s23, s19, s23
	v_and_b32_e32 v39, 31, v23
	v_lshrrev_b32_e32 v23, 2, v23
	v_lshl_add_u64 v[192:193], s[22:23], 0, v[34:35]
	v_readlane_b32 s22, v255, 46
	v_and_b32_e32 v23, 8, v23
	s_movk_i32 s24, 0x48
	s_movk_i32 s26, 0xfac8
	s_add_u32 s22, s22, s17
	v_readlane_b32 s23, v255, 47
	v_mad_u64_u32 v[184:185], s[24:25], v38, s24, v[32:33]
	v_mad_u64_u32 v[186:187], s[24:25], v25, s26, v[22:23]
	s_addc_u32 s23, s23, s14
	v_mad_u64_u32 v[188:189], s[24:25], v29, s26, v[24:25]
	v_mad_u64_u32 v[190:191], s[24:25], v33, s26, v[28:29]
	v_lshl_add_u32 v22, v186, 1, 64
	s_add_u32 s22, s22, s16
	v_mov_b32_e32 v27, v1
	v_mov_b32_e32 v31, v1
	v_xor_b32_e32 v66, 0x80000000, v66
	v_mul_u32_u24_e32 v40, 0xc8, v39
	v_lshl_add_u32 v32, v184, 1, 64
	v_lshl_add_u32 v24, v188, 1, 64
	v_lshl_add_u32 v25, v190, 1, 64
	s_addc_u32 s23, s23, s15
	v_mov_b32_e32 v185, 0
	s_mov_b32 s21, 0
	v_mov_b32_e32 v67, v66
	v_mov_b32_e32 v68, v66
	v_mov_b32_e32 v69, v66
	v_mov_b32_e32 v70, v66
	v_mov_b32_e32 v71, v66
	v_mov_b32_e32 v72, v66
	v_mov_b32_e32 v73, v66
	v_mov_b32_e32 v74, v66
	v_mov_b32_e32 v75, v66
	s_waitcnt vmcnt(9)
	ds_write_b128 v22, v[2:5]
	s_waitcnt vmcnt(8)
	ds_write_b128 v24, v[6:9]
	s_waitcnt vmcnt(7)
	ds_write_b128 v25, v[10:13]
	s_waitcnt vmcnt(6)
	ds_write_b128 v32, v[14:17] offset:25600
	s_waitcnt vmcnt(5)
	ds_write_b128 v32, v[18:21] offset:34816
	v_lshlrev_b32_e32 v2, 8, v39
	v_mov_b32_e32 v76, v66
	v_mov_b32_e32 v77, v66
	v_mov_b32_e32 v78, v66
	v_mov_b32_e32 v79, v66
	v_mov_b32_e32 v80, v66
	v_mov_b32_e32 v81, v66
	v_mul_u32_u24_e32 v187, 0x190, v39
	v_sub_u32_e32 v189, 0, v2
	v_lshl_add_u64 v[194:195], s[22:23], 0, v[0:1]
	v_lshl_add_u64 v[196:197], s[22:23], 0, v[26:27]
	v_lshl_add_u64 v[198:199], s[22:23], 0, v[30:31]
	v_lshlrev_b32_e32 v0, 1, v40
	v_lshlrev_b32_e32 v191, 1, v23
	v_mov_b32_e32 v50, 0
	v_mov_b32_e32 v51, v185
	v_mov_b32_e32 v52, v185
	v_mov_b32_e32 v53, v185
	v_mov_b32_e32 v54, v185
	v_mov_b32_e32 v55, v185
	v_mov_b32_e32 v56, v185
	v_mov_b32_e32 v57, v185
	v_mov_b32_e32 v58, v185
	v_mov_b32_e32 v59, v185
	v_mov_b32_e32 v60, v185
	v_mov_b32_e32 v61, v185
	v_mov_b32_e32 v62, v185
	v_mov_b32_e32 v63, v185
	v_mov_b32_e32 v64, v185
	v_mov_b32_e32 v65, v185
	v_mov_b32_e32 v34, 0
	v_mov_b32_e32 v35, v185
	v_mov_b32_e32 v36, v185
	v_mov_b32_e32 v37, v185
	v_mov_b32_e32 v38, v185
	v_mov_b32_e32 v39, v185
	v_mov_b32_e32 v40, v185
	v_mov_b32_e32 v41, v185
	v_mov_b32_e32 v42, v185
	v_mov_b32_e32 v43, v185
	v_mov_b32_e32 v44, v185
	v_mov_b32_e32 v45, v185
	v_mov_b32_e32 v46, v185
	v_mov_b32_e32 v47, v185
	v_mov_b32_e32 v48, v185
	v_mov_b32_e32 v49, v185
	v_mov_b32_e32 v18, 0
	v_mov_b32_e32 v19, v185
	v_mov_b32_e32 v20, v185
	v_mov_b32_e32 v21, v185
	v_mov_b32_e32 v22, v185
	v_mov_b32_e32 v23, v185
	v_mov_b32_e32 v24, v185
	v_mov_b32_e32 v25, v185
	v_mov_b32_e32 v26, v185
	v_mov_b32_e32 v27, v185
	v_mov_b32_e32 v28, v185
	v_mov_b32_e32 v29, v185
	v_mov_b32_e32 v30, v185
	v_mov_b32_e32 v31, v185
	v_mov_b32_e32 v32, v185
	v_mov_b32_e32 v33, v185
	v_mov_b32_e32 v2, 0
	v_mov_b32_e32 v3, v185
	v_mov_b32_e32 v4, v185
	v_mov_b32_e32 v5, v185
	v_mov_b32_e32 v6, v185
	v_mov_b32_e32 v7, v185
	v_mov_b32_e32 v8, v185
	v_mov_b32_e32 v9, v185
	v_mov_b32_e32 v10, v185
	v_mov_b32_e32 v11, v185
	v_mov_b32_e32 v12, v185
	v_mov_b32_e32 v13, v185
	v_mov_b32_e32 v14, v185
	v_mov_b32_e32 v15, v185
	v_mov_b32_e32 v16, v185
	v_mov_b32_e32 v17, v185
	s_waitcnt lgkmcnt(0)
	s_barrier
	v_mov_b32_e32 v200, 0
	v_mov_b32_e32 v201, 0
	v_mov_b32_e32 v202, 0
	v_mov_b32_e32 v203, 0
	v_mov_b32_e32 v204, 0
	v_mov_b32_e32 v205, 0
	v_mov_b32_e32 v206, 0
	v_mov_b32_e32 v207, 0
	v_mov_b32_e32 v208, 0
	v_mov_b32_e32 v209, 0
	v_mov_b32_e32 v210, 0
	v_mov_b32_e32 v211, 0
	v_mov_b32_e32 v212, 0
	v_mov_b32_e32 v213, 0
	v_mov_b32_e32 v214, 0
	v_mov_b32_e32 v215, 0
	v_mov_b32_e32 v242, 0
	v_mov_b32_e32 v243, 0
	v_mov_b32_e32 v244, 0
	v_mov_b32_e32 v245, 0
.LBB0_590:
	s_bitcmp1_b32 s21, 0
	s_cselect_b32 s22, 0xac00, 0
	s_add_i32 s22, s22, 64
	v_add3_u32 v220, s22, v0, v191
	ds_read_b128 v[98:101], v220
	ds_read_b128 v[102:105], v220 offset:32
	ds_read_b128 v[106:109], v220 offset:64
	ds_read_b128 v[110:113], v220 offset:96
	ds_read_b128 v[216:219], v220 offset:256
	ds_read_b128 v[224:227], v220 offset:288
	ds_read_b128 v[230:233], v220 offset:320
	ds_read_b128 v[238:241], v220 offset:352
	s_add_i32 s22, s21, 1
	s_bitcmp1_b32 s22, 0
	s_cselect_b32 s23, 0xac00, 0
	s_add_i32 s23, s23, 64
	v_mfma_f32_32x32x16_bf16 v[50:65], v[200:203], v[242:245], v[50:65]
	ds_read_b128 v[200:203], v220 offset:128
	v_lshl_add_u32 v246, v186, 1, s23
	v_lshl_add_u32 v247, v188, 1, s23
	v_mfma_f32_32x32x16_bf16 v[34:49], v[204:207], v[242:245], v[34:49]
	ds_read_b128 v[204:207], v220 offset:160
	v_lshl_add_u32 v248, v190, 1, s23
	v_lshl_add_u32 v249, v184, 1, s23
	s_waitcnt vmcnt(0)
	v_mfma_f32_32x32x16_bf16 v[18:33], v[208:211], v[242:245], v[18:33]
	ds_read_b128 v[208:211], v220 offset:192
	ds_write_b128 v246, v[166:169]
	ds_write_b128 v247, v[162:165]
	v_mfma_f32_32x32x16_bf16 v[2:17], v[212:215], v[242:245], v[2:17]
	ds_read_b128 v[212:215], v220 offset:224
	ds_write_b128 v248, v[170:173]
	ds_write_b128 v249, v[174:177] offset:25600
	s_waitcnt lgkmcnt(15)
	v_mfma_f32_32x32x16_bf16 v[82:97], v[98:101], v[114:117], v[66:81]
	ds_write_b128 v249, v[178:181] offset:34816
	s_waitcnt lgkmcnt(15)
	v_mfma_f32_32x32x16_bf16 v[82:97], v[102:105], v[118:121], v[82:97]
	s_cmp_gt_u32 s21, 61
	s_cbranch_scc1 .Lmla_skip_ga
	v_lshl_add_u64 v[178:179], s[62:63], 0, v[192:193]
	v_add_co_u32_e32 v174, vcc, 0x7046000, v178
	v_lshl_add_u64 v[162:163], s[62:63], 0, v[194:195]
	s_nop 0
	v_addc_co_u32_e32 v175, vcc, 0, v179, vcc
	v_add_co_u32_e32 v178, vcc, 0x70c6000, v178
	v_lshl_add_u64 v[164:165], s[62:63], 0, v[196:197]
	v_lshl_add_u64 v[170:171], s[62:63], 0, v[198:199]
	v_addc_co_u32_e32 v179, vcc, 0, v179, vcc
; #define MFMA32(a, b, c) __builtin_amdgcn_mfma_f32_32x32x16_bf16((a), (b), (c), 0, 0, 0)
;     ...
;   auto gload = [&](int k0) __attribute__((always_inline)) {
;     const char* kb = (const char*)Kg + (size_t)k0 * ldk * 2;
; #pragma unroll
;     for (int i = 0; i < NKL; ++i) rk[i] = *(const u32x4*)(kb + koff[i]);
;     const char* vb = (const char*)VTg + (size_t)k0 * 2;
; #pragma unroll
;     for (int i = 0; i < 2; ++i) rv[i] = *(const u32x4*)(vb + (size_t)i * 64 * 4096 * 2 + voff);
;   };
;     ...
;     {
;       constexpr int BPT = NQ / 4;
;       constexpr int NBAT = 2 * BPT;
;       bf16x8 kf[2][4];
; #pragma unroll
;       for (int i = 0; i < 4; ++i) kf[0][i] = *(const bf16x8*)(Ks + r * KST + kcol_off + 16 * i + 8 * h);
; #pragma unroll
;       for (int g = 0; g < NBAT; ++g) {
;         if (g + 1 < NBAT) {
;           const int t2n = (g + 1) / BPT, bn = (g + 1) % BPT;
; #pragma unroll
;           for (int i = 0; i < 4; ++i) kf[(g + 1) & 1][i] = *(const bf16x8*)(Ks + (32 * t2n + r) * KST + kcol_off + 16 * (4 * bn + i) + 8 * h);
;         }
;         __builtin_amdgcn_sched_barrier(0);
;         const int t2 = g / BPT, b = g % BPT;
; #pragma unroll
;         for (int i = 0; i < 4; ++i) st[t2] = MFMA32(kf[g & 1][i], qf[4 * b + i], st[t2]);
;         __builtin_amdgcn_sched_barrier(0);
;       }
.Lmla_skip_ga:
	s_waitcnt lgkmcnt(14)
	v_mfma_f32_32x32x16_bf16 v[82:97], v[106:109], v[122:125], v[82:97]
	s_waitcnt lgkmcnt(13)
	v_mfma_f32_32x32x16_bf16 v[82:97], v[110:113], v[126:129], v[82:97]
	s_cmp_gt_u32 s21, 61
	s_cbranch_scc1 .Lmla_skip_gb
	global_load_dwordx4 v[166:169], v[162:163], off
	s_nop 0
	global_load_dwordx4 v[162:165], v[164:165], off
	s_nop 0
	global_load_dwordx4 v[170:173], v[170:171], off
	s_nop 0
	global_load_dwordx4 v[174:177], v[174:175], off offset:512
	s_nop 0
	global_load_dwordx4 v[178:181], v[178:179], off offset:512
.Lmla_skip_gb:
	s_waitcnt lgkmcnt(8)
	v_mfma_f32_32x32x16_bf16 v[82:97], v[200:203], v[130:133], v[82:97]
	ds_read_b128 v[200:203], v220 offset:12800
	v_lshl_add_u64 v[192:193], v[192:193], 0, s[30:31]
	s_waitcnt lgkmcnt(8)
	v_mfma_f32_32x32x16_bf16 v[82:97], v[204:207], v[134:137], v[82:97]
	ds_read_b128 v[204:207], v220 offset:12832
	v_lshl_add_u64 v[194:195], v[194:195], 0, s[92:93]
	s_waitcnt lgkmcnt(8)
	v_mfma_f32_32x32x16_bf16 v[82:97], v[208:211], v[138:141], v[82:97]
	ds_read_b128 v[208:211], v220 offset:12864
	v_lshl_add_u64 v[196:197], v[196:197], 0, s[92:93]
	s_waitcnt lgkmcnt(6)
	v_mfma_f32_32x32x16_bf16 v[82:97], v[212:215], v[142:145], v[82:97]
	ds_read_b128 v[212:215], v220 offset:12896
	v_lshl_add_u64 v[198:199], v[198:199], 0, s[92:93]
	v_mfma_f32_32x32x16_bf16 v[82:97], v[216:219], v[146:149], v[82:97]
	ds_read_b128 v[216:219], v220 offset:12928
	v_mfma_f32_32x32x16_bf16 v[82:97], v[224:227], v[154:157], v[82:97]
	ds_read_b128 v[224:227], v220 offset:12960
	v_mfma_f32_32x32x16_bf16 v[82:97], v[230:233], v[150:153], v[82:97]
	ds_read_b128 v[230:233], v220 offset:12992
	v_mfma_f32_32x32x16_bf16 v[82:97], v[238:241], v[158:161], v[82:97]
	ds_read_b128 v[238:241], v220 offset:13024
	s_waitcnt lgkmcnt(7)
	v_mfma_f32_32x32x16_bf16 v[98:113], v[200:203], v[114:117], v[66:81]
	ds_read_b128 v[200:203], v220 offset:13056
	s_waitcnt lgkmcnt(7)
	v_mfma_f32_32x32x16_bf16 v[98:113], v[204:207], v[118:121], v[98:113]
	ds_read_b128 v[204:207], v220 offset:13088
	s_waitcnt lgkmcnt(7)
	v_mfma_f32_32x32x16_bf16 v[98:113], v[208:211], v[122:125], v[98:113]
	ds_read_b128 v[208:211], v220 offset:13120
	s_waitcnt lgkmcnt(7)
	v_mfma_f32_32x32x16_bf16 v[98:113], v[212:215], v[126:129], v[98:113]
	ds_read_b128 v[212:215], v220 offset:13152
	v_add_u32_e32 v220, v220, v189
	v_exp_f32_e32 v82, v82
	v_exp_f32_e32 v83, v83
	s_waitcnt lgkmcnt(7)
	v_mfma_f32_32x32x16_bf16 v[98:113], v[216:219], v[130:133], v[98:113]
	ds_read_b128 v[216:219], v220 offset:25600
	v_exp_f32_e32 v84, v84
	v_exp_f32_e32 v85, v85
	s_waitcnt lgkmcnt(7)
	v_mfma_f32_32x32x16_bf16 v[98:113], v[224:227], v[134:137], v[98:113]
	ds_read_b128 v[224:227], v220 offset:30208
	v_exp_f32_e32 v86, v86
	v_exp_f32_e32 v87, v87
	s_waitcnt lgkmcnt(7)
	v_mfma_f32_32x32x16_bf16 v[98:113], v[230:233], v[138:141], v[98:113]
	ds_read_b128 v[230:233], v220 offset:34816
	v_exp_f32_e32 v88, v88
	v_exp_f32_e32 v89, v89
	s_waitcnt lgkmcnt(7)
	v_mfma_f32_32x32x16_bf16 v[98:113], v[238:241], v[142:145], v[98:113]
	ds_read_b128 v[238:241], v220 offset:39424
	v_exp_f32_e32 v90, v90
	v_exp_f32_e32 v91, v91
	v_cvt_pk_bf16_f32 v242, v82, v83
	s_waitcnt lgkmcnt(7)
	v_mfma_f32_32x32x16_bf16 v[98:113], v[200:203], v[146:149], v[98:113]
	ds_read_b128 v[200:203], v220 offset:25632
	v_exp_f32_e32 v92, v92
	v_exp_f32_e32 v93, v93
	v_cvt_pk_bf16_f32 v243, v84, v85
	s_waitcnt lgkmcnt(7)
	v_mfma_f32_32x32x16_bf16 v[98:113], v[204:207], v[154:157], v[98:113]
	ds_read_b128 v[204:207], v220 offset:30240
	v_exp_f32_e32 v94, v94
	v_exp_f32_e32 v95, v95
	v_cvt_pk_bf16_f32 v244, v86, v87
	s_waitcnt lgkmcnt(7)
	v_mfma_f32_32x32x16_bf16 v[98:113], v[208:211], v[150:153], v[98:113]
	ds_read_b128 v[208:211], v220 offset:34848
	v_exp_f32_e32 v96, v96
	v_exp_f32_e32 v97, v97
	v_cvt_pk_bf16_f32 v245, v88, v89
	s_waitcnt lgkmcnt(7)
; #define MFMA32(a, b, c) __builtin_amdgcn_mfma_f32_32x32x16_bf16((a), (b), (c), 0, 0, 0)
; DI u32 pack2(float a, float b) { f2_t v = {a, b}; bf2_t r = __builtin_convertvector(v, bf2_t); return __builtin_bit_cast(u32, r); }
; DI float shx(float v, int k) { return __int_as_float(__builtin_amdgcn_ds_bpermute((lane_id_l() ^ k) << 2, __float_as_int(v))); }
;     ...
;     } else if (MODE == 1) {
;       float ls = 0.f;
; #pragma unroll
;       for (int t2 = 0; t2 < 2; ++t2)
; #pragma unroll
;         for (int e = 0; e < 16; ++e) { float p = __builtin_amdgcn_exp2f(st[t2][e]); st[t2][e] = p; ls += p; }
;       l_run += ls;
;     } else {
;       float mx = st[0][0];
; #pragma unroll
;       for (int t2 = 0; t2 < 2; ++t2)
; #pragma unroll
;         for (int e = 0; e < 16; ++e) mx = fmaxf(mx, st[t2][e]);
;       mx = fmaxf(mx, shx(mx, 32));
;       float mnew = fmaxf(m_run, mx);
;       float alpha = __builtin_amdgcn_exp2f(m_run - mnew);
;       const bool changed = mnew > m_run;
;       m_run = mnew;
;       float ls = 0.f;
; #pragma unroll
;       for (int t2 = 0; t2 < 2; ++t2)
; #pragma unroll
;         for (int e = 0; e < 16; ++e) { float p = __builtin_amdgcn_exp2f(st[t2][e] - mnew); st[t2][e] = p; ls += p; }
;       l_run = l_run * alpha + ls;
;       if (__any(changed)) {
; #pragma unroll
;         for (int dt = 0; dt < 4; ++dt)
; #pragma unroll
;           for (int e = 0; e < 16; ++e) o[dt][e] *= alpha;
;       }
;     }
; #pragma unroll
;     for (int c = 0; c < 4; ++c) {
;       const int t2 = c >> 1, s2 = c & 1;
;       if (c + 1 < 4) {
; #pragma unroll
;         for (int dt = 0; dt < 4; ++dt) vf[(c + 1) & 1][dt] = *(const bf16x8*)(Vs + (32 * dt + r) * 72 + 16 * (c + 1) + 8 * h);
;       }
;       u32x4 pk;
;       pk.x = pack2(st[t2][8 * s2], st[t2][8 * s2 + 1]); pk.y = pack2(st[t2][8 * s2 + 2], st[t2][8 * s2 + 3]);
;       pk.z = pack2(st[t2][8 * s2 + 4], st[t2][8 * s2 + 5]); pk.w = pack2(st[t2][8 * s2 + 6], st[t2][8 * s2 + 7]);
;       bf16x8 pf = __builtin_bit_cast(bf16x8, pk);
;       __builtin_amdgcn_sched_barrier(0);
; #pragma unroll
;       for (int dt = 0; dt < 4; ++dt) o[dt] = MFMA32(vf[c & 1][dt], pf, o[dt]);
;       __builtin_amdgcn_sched_barrier(0);
;     }
;     if (kt + 1 < nkt) lstore((kt + 1) & 1);
;     if (kt + 2 < nkt) gload((kt0 + kt + 2) * 64);
;     __syncthreads();
;   }
	v_mfma_f32_32x32x16_bf16 v[98:113], v[212:215], v[158:161], v[98:113]
	ds_read_b128 v[212:215], v220 offset:39456
	v_add_f32_e32 v246, v90, v91
	v_add_f32_e32 v246, v92, v246
	v_add_f32_e32 v246, v93, v246
	v_add_f32_e32 v246, v94, v246
	s_waitcnt lgkmcnt(7)
	v_mfma_f32_32x32x16_bf16 v[50:65], v[216:219], v[242:245], v[50:65]
	ds_read_b128 v[216:219], v220 offset:25664
	v_add_f32_e32 v246, v95, v246
	v_add_f32_e32 v246, v96, v246
	v_add_f32_e32 v246, v97, v246
	v_cvt_pk_bf16_f32 v90, v90, v91
	v_cvt_pk_bf16_f32 v91, v92, v93
	s_waitcnt lgkmcnt(7)
	v_mfma_f32_32x32x16_bf16 v[34:49], v[224:227], v[242:245], v[34:49]
	ds_read_b128 v[224:227], v220 offset:30272
	v_cvt_pk_bf16_f32 v92, v94, v95
	v_cvt_pk_bf16_f32 v93, v96, v97
	v_exp_f32_e32 v98, v98
	v_exp_f32_e32 v99, v99
	s_waitcnt lgkmcnt(7)
	v_mfma_f32_32x32x16_bf16 v[18:33], v[230:233], v[242:245], v[18:33]
	ds_read_b128 v[230:233], v220 offset:34880
	v_exp_f32_e32 v100, v100
	v_exp_f32_e32 v101, v101
	v_exp_f32_e32 v102, v102
	s_waitcnt lgkmcnt(7)
	v_mfma_f32_32x32x16_bf16 v[2:17], v[238:241], v[242:245], v[2:17]
	ds_read_b128 v[238:241], v220 offset:39488
	v_exp_f32_e32 v103, v103
	v_exp_f32_e32 v104, v104
	v_exp_f32_e32 v105, v105
	s_waitcnt lgkmcnt(7)
	v_mfma_f32_32x32x16_bf16 v[50:65], v[200:203], v[90:93], v[50:65]
	ds_read_b128 v[200:203], v220 offset:25696
	v_cvt_pk_bf16_f32 v94, v98, v99
	v_cvt_pk_bf16_f32 v95, v100, v101
	v_cvt_pk_bf16_f32 v96, v102, v103
	v_cvt_pk_bf16_f32 v97, v104, v105
	v_exp_f32_e32 v106, v106
	s_waitcnt lgkmcnt(7)
	v_mfma_f32_32x32x16_bf16 v[34:49], v[204:207], v[90:93], v[34:49]
	ds_read_b128 v[204:207], v220 offset:30304
	v_exp_f32_e32 v107, v107
	v_exp_f32_e32 v108, v108
	v_exp_f32_e32 v109, v109
	v_add_f32_e32 v246, v82, v246
	s_waitcnt lgkmcnt(7)
	v_mfma_f32_32x32x16_bf16 v[18:33], v[208:211], v[90:93], v[18:33]
	ds_read_b128 v[208:211], v220 offset:34912
	v_exp_f32_e32 v110, v110
	v_exp_f32_e32 v111, v111
	v_exp_f32_e32 v112, v112
	v_add_f32_e32 v246, v83, v246
	s_waitcnt lgkmcnt(7)
	v_mfma_f32_32x32x16_bf16 v[2:17], v[212:215], v[90:93], v[2:17]
	ds_read_b128 v[212:215], v220 offset:39520
	v_exp_f32_e32 v113, v113
	v_add_f32_e32 v247, v106, v107
	v_add_f32_e32 v247, v108, v247
	v_add_f32_e32 v246, v84, v246
	s_waitcnt lgkmcnt(7)
	v_mfma_f32_32x32x16_bf16 v[50:65], v[216:219], v[94:97], v[50:65]
	v_add_f32_e32 v247, v109, v247
	v_add_f32_e32 v247, v110, v247
	v_add_f32_e32 v247, v111, v247
	v_add_f32_e32 v247, v112, v247
	v_add_f32_e32 v247, v113, v247
	v_add_f32_e32 v246, v85, v246
	s_waitcnt lgkmcnt(6)
	v_mfma_f32_32x32x16_bf16 v[34:49], v[224:227], v[94:97], v[34:49]
	v_cvt_pk_bf16_f32 v242, v106, v107
	v_cvt_pk_bf16_f32 v243, v108, v109
	v_cvt_pk_bf16_f32 v244, v110, v111
	v_cvt_pk_bf16_f32 v245, v112, v113
	v_add_f32_e32 v247, v98, v247
	v_add_f32_e32 v246, v86, v246
	v_add_f32_e32 v247, v99, v247
	s_waitcnt lgkmcnt(5)
	v_mfma_f32_32x32x16_bf16 v[18:33], v[230:233], v[94:97], v[18:33]
	v_add_f32_e32 v247, v100, v247
	v_add_f32_e32 v246, v87, v246
	v_add_f32_e32 v247, v101, v247
	v_add_f32_e32 v246, v88, v246
	v_add_f32_e32 v247, v102, v247
	v_add_f32_e32 v246, v89, v246
	v_add_f32_e32 v247, v103, v247
	s_waitcnt lgkmcnt(4)
	v_mfma_f32_32x32x16_bf16 v[2:17], v[238:241], v[94:97], v[2:17]
	v_add_f32_e32 v247, v104, v247
	v_add_f32_e32 v247, v105, v247
	v_add_f32_e32 v246, v247, v246
	v_add_f32_e32 v185, v185, v246
	s_cmp_lg_u32 s22, 64
	s_waitcnt lgkmcnt(0)
	s_barrier
	s_cbranch_scc0 .Lmla_tail
	s_mov_b32 s21, s22
	s_branch .LBB0_590
.Lmla_tail:
	v_mfma_f32_32x32x16_bf16 v[50:65], v[200:203], v[242:245], v[50:65]
	v_mfma_f32_32x32x16_bf16 v[34:49], v[204:207], v[242:245], v[34:49]
	v_mfma_f32_32x32x16_bf16 v[18:33], v[208:211], v[242:245], v[18:33]
	v_mfma_f32_32x32x16_bf16 v[2:17], v[212:215], v[242:245], v[2:17]
	s_branch .LBB0_596

; DI u32 pack2(float a, float b) { f2_t v = {a, b}; bf2_t r = __builtin_convertvector(v, bf2_t); return __builtin_bit_cast(u32, r); }
; DI void store_o(const f32x16 (&o)[4], u16* rowp, int h) {
; #pragma unroll
;   for (int dt = 0; dt < 4; ++dt)
; #pragma unroll
;     for (int g = 0; g < 4; ++g) {
;       u32x2 v; v.x = pack2(o[dt][4 * g], o[dt][4 * g + 1]); v.y = pack2(o[dt][4 * g + 2], o[dt][4 * g + 3]);
;       *(u32x2*)(rowp + 32 * dt + 8 * g + 4 * h) = v;
;     }
; }
.LBB0_609:
	s_and_saveexec_b64 s[6:7], s[4:5]
	s_xor_b64 s[4:5], exec, s[6:7]
	s_cbranch_execz .LBB0_611
	v_mbcnt_lo_u32_b32 v218, -1, 0
	v_mbcnt_hi_u32_b32 v218, -1, v218
	v_and_b32_e32 v218, 32, v218
	v_lshrrev_b32_e32 v218, 2, v218
	v_mov_b32_e32 v219, 0
	v_lshl_add_u64 v[216:217], v[120:121], 0, v[218:219]
	v_cvt_pk_bf16_f32 v200, v112, v113
	s_waitcnt vmcnt(3)
	v_cvt_pk_bf16_f32 v201, v114, v115
	s_waitcnt vmcnt(2)
	s_nop 0
	v_cvt_pk_bf16_f32 v202, v108, v109
	v_cvt_pk_bf16_f32 v203, v110, v111
	s_nop 1
	v_permlane32_swap_b32_e32 v200, v202
	v_permlane32_swap_b32_e32 v201, v203
	global_store_dwordx4 v[216:217], v[200:203], off offset:16
	v_cvt_pk_bf16_f32 v204, v104, v105
	v_cvt_pk_bf16_f32 v205, v106, v107
	s_nop 0
	v_cvt_pk_bf16_f32 v206, v100, v101
	v_cvt_pk_bf16_f32 v207, v102, v103
	s_nop 1
	v_permlane32_swap_b32_e32 v204, v206
	v_permlane32_swap_b32_e32 v205, v207
	global_store_dwordx4 v[216:217], v[204:207], off offset:48
	v_cvt_pk_bf16_f32 v208, v96, v97
	v_cvt_pk_bf16_f32 v209, v98, v99
	s_nop 0
	v_cvt_pk_bf16_f32 v210, v92, v93
	v_cvt_pk_bf16_f32 v211, v94, v95
	s_nop 1
	v_permlane32_swap_b32_e32 v208, v210
	v_permlane32_swap_b32_e32 v209, v211
	global_store_dwordx4 v[216:217], v[208:211], off offset:80
	s_waitcnt vmcnt(4)
	v_cvt_pk_bf16_f32 v212, v88, v89
	v_cvt_pk_bf16_f32 v213, v90, v91
	s_nop 0
	s_waitcnt vmcnt(3)
	v_cvt_pk_bf16_f32 v214, v84, v85
	v_cvt_pk_bf16_f32 v215, v86, v87
	s_nop 1
	v_permlane32_swap_b32_e32 v212, v214
	v_permlane32_swap_b32_e32 v213, v215
	global_store_dwordx4 v[216:217], v[212:215], off offset:112
	v_cvt_pk_bf16_f32 v200, v80, v81
	v_cvt_pk_bf16_f32 v201, v82, v83
	s_nop 0
	v_cvt_pk_bf16_f32 v202, v76, v77
	v_cvt_pk_bf16_f32 v203, v78, v79
	s_nop 1
	v_permlane32_swap_b32_e32 v200, v202
	v_permlane32_swap_b32_e32 v201, v203
	global_store_dwordx4 v[216:217], v[200:203], off offset:144
	v_cvt_pk_bf16_f32 v204, v72, v73
	v_cvt_pk_bf16_f32 v205, v74, v75
	s_nop 0
	v_cvt_pk_bf16_f32 v206, v116, v117
	v_cvt_pk_bf16_f32 v207, v70, v71
	s_nop 1
	v_permlane32_swap_b32_e32 v204, v206
	v_permlane32_swap_b32_e32 v205, v207
	global_store_dwordx4 v[216:217], v[204:207], off offset:176
	v_cvt_pk_bf16_f32 v208, v118, v119
	v_cvt_pk_bf16_f32 v209, v134, v135
	s_nop 0
	v_cvt_pk_bf16_f32 v210, v130, v131
	s_waitcnt vmcnt(6)
	v_cvt_pk_bf16_f32 v211, v126, v127
	s_nop 1
	v_permlane32_swap_b32_e32 v208, v210
	v_permlane32_swap_b32_e32 v209, v211
	global_store_dwordx4 v[216:217], v[208:211], off offset:208
	v_cvt_pk_bf16_f32 v2, v124, v125
	v_cvt_pk_bf16_f32 v3, v122, v123
	global_store_dwordx2 v[120:121], v[2:3], off offset:240

; __global__ void __launch_bounds__(NTHR, 2) hybrid_encoder_mega(Params P) {
	.amdhsa_kernel _Z19hybrid_encoder_mega6Params
		.amdhsa_group_segment_fixed_size 64
		.amdhsa_private_segment_fixed_size 0
		.amdhsa_kernarg_size 552
		.amdhsa_user_sgpr_count 2
		.amdhsa_user_sgpr_dispatch_ptr 0
		.amdhsa_user_sgpr_queue_ptr 0
		.amdhsa_user_sgpr_kernarg_segment_ptr 1
		.amdhsa_user_sgpr_dispatch_id 0
		.amdhsa_user_sgpr_kernarg_preload_length 0
		.amdhsa_user_sgpr_kernarg_preload_offset 0
		.amdhsa_user_sgpr_private_segment_size 0
		.amdhsa_uses_dynamic_stack 0
		.amdhsa_enable_private_segment 0
		.amdhsa_system_sgpr_workgroup_id_x 1
		.amdhsa_system_sgpr_workgroup_id_y 0
		.amdhsa_system_sgpr_workgroup_id_z 0
		.amdhsa_system_sgpr_workgroup_info 0
		.amdhsa_system_vgpr_workitem_id 2
		.amdhsa_next_free_vgpr 256
		.amdhsa_next_free_sgpr 102
		.amdhsa_accum_offset 256
		.amdhsa_reserve_vcc 1
		.amdhsa_float_round_mode_32 0
		.amdhsa_float_round_mode_16_64 0
		.amdhsa_float_denorm_mode_32 3
		.amdhsa_float_denorm_mode_16_64 3
		.amdhsa_dx10_clamp 1
		.amdhsa_ieee_mode 1
		.amdhsa_fp16_overflow 0
		.amdhsa_tg_split 0
		.amdhsa_exception_fp_ieee_invalid_op 0
		.amdhsa_exception_fp_denorm_src 0
		.amdhsa_exception_fp_ieee_div_zero 0
		.amdhsa_exception_fp_ieee_overflow 0
		.amdhsa_exception_fp_ieee_underflow 0
		.amdhsa_exception_fp_ieee_inexact 0
		.amdhsa_exception_int_div_zero 0
	.end_amdhsa_kernel

; __global__ void __launch_bounds__(NTHR, 2) hybrid_encoder_mega(Params P) {
amdhsa.kernels:
  - .agpr_count:     0
    .args:
      - .offset:         0
        .size:           296
        .value_kind:     by_value
      - .offset:         296
        .size:           4
        .value_kind:     hidden_block_count_x
      - .offset:         300
        .size:           4
        .value_kind:     hidden_block_count_y
      - .offset:         304
        .size:           4
        .value_kind:     hidden_block_count_z
      - .offset:         308
        .size:           2
        .value_kind:     hidden_group_size_x
      - .offset:         310
        .size:           2
        .value_kind:     hidden_group_size_y
      - .offset:         312
        .size:           2
        .value_kind:     hidden_group_size_z
      - .offset:         314
        .size:           2
        .value_kind:     hidden_remainder_x
      - .offset:         316
        .size:           2
        .value_kind:     hidden_remainder_y
      - .offset:         318
        .size:           2
        .value_kind:     hidden_remainder_z
      - .offset:         336
        .size:           8
        .value_kind:     hidden_global_offset_x
      - .offset:         344
        .size:           8
        .value_kind:     hidden_global_offset_y
      - .offset:         352
        .size:           8
        .value_kind:     hidden_global_offset_z
      - .offset:         360
        .size:           2
        .value_kind:     hidden_grid_dims
      - .offset:         384
        .size:           8
        .value_kind:     hidden_multigrid_sync_arg
      - .offset:         416
        .size:           4
        .value_kind:     hidden_dynamic_lds_size
    .group_segment_fixed_size: 64
    .kernarg_segment_align: 8
    .kernarg_segment_size: 552
    .language:       OpenCL C
    .language_version:
      - 2
      - 0
    .max_flat_workgroup_size: 512
    .name:           _Z19hybrid_encoder_mega6Params
    .private_segment_fixed_size: 0
    .sgpr_count:     108
    .sgpr_spill_count: 196
    .symbol:         _Z19hybrid_encoder_mega6Params.kd
    .uniform_work_group_size: 1
    .uses_dynamic_stack: false
    .vgpr_count:     256
    .vgpr_spill_count: 0
    .wavefront_size: 64
